# attention fast loops: provably redundant lgkmcnt waits, inline-asm hazard pad and m0 save/restore removed
# baseline (speedup 1.0000x reference)
.Ldf_fast:
	s_add_i32 s0, s43, 2
	s_waitcnt vmcnt(4) lgkmcnt(0)
	s_barrier
	s_add_i32 s20, s58, s43
	s_cmp_lt_i32 s20, s89
	v_mfma_f32_32x32x16_bf16 v[2:17], v[158:161], v[182:185], v[2:17]
	v_subrev_u32_e32 v198, 64, v197
	s_cselect_b64 s[26:27], -1, 0
	v_cvt_f32_i32_e32 v98, v198
	v_cndmask_b32_e64 v188, -v193, v193, s[26:27]
	v_add_u32_e32 v199, s15, v240
	ds_read_b64_tr_b16 v[200:201], v199 offset:51200
	ds_read_b64_tr_b16 v[202:203], v199 offset:51712
	v_fma_f32 v186, v188, v98, -v233
	v_exp_f32_e32 v66, v66
	v_exp_f32_e32 v67, v67
	v_fma_f32 v114, 0, v188, v186
	v_fmamk_f32 v98, v188, 0x42000000, v186
	v_add_f32_e32 v115, v188, v186
	v_mfma_f32_32x32x16_bf16 v[2:17], v[154:157], v[178:181], v[2:17]
	ds_read_b64_tr_b16 v[182:183], v199 offset:52224
	ds_read_b64_tr_b16 v[184:185], v199 offset:52736
	v_fmamk_f32 v99, v188, 0x42040000, v186
	v_fma_f32 v116, 2.0, v188, v186
	v_exp_f32_e32 v68, v68
	v_exp_f32_e32 v69, v69
	s_waitcnt lgkmcnt(2)
	v_mfma_f32_32x32x16_bf16 v[2:17], v[150:153], v[200:203], v[2:17]
	ds_read_b64_tr_b16 v[178:179], v199 offset:53248
	ds_read_b64_tr_b16 v[180:181], v199 offset:53760
	v_add_f32_e32 v187, v187, v66
	v_fmamk_f32 v100, v188, 0x42080000, v186
	v_fmamk_f32 v117, v188, 0x40400000, v186
	v_cvt_pk_bf16_f32 v174, v66, v67
	v_add_f32_e32 v187, v67, v187
	v_exp_f32_e32 v70, v70
	s_waitcnt lgkmcnt(2)
	v_mfma_f32_32x32x16_bf16 v[2:17], v[146:149], v[182:185], v[2:17]
	ds_read_b64_tr_b16 v[200:201], v199 offset:54272
	ds_read_b64_tr_b16 v[202:203], v199 offset:54784
	v_fma_f32 v182, v188, s16, v186
	v_fma_f32 v183, v188, s17, v186
	v_fmamk_f32 v118, v188, 0x41000000, v186
	v_exp_f32_e32 v71, v71
	v_add_f32_e32 v187, v187, v68
	v_mov_b32_e32 v101, v182
	v_mov_b32_e32 v102, v183
	s_waitcnt lgkmcnt(2)
	v_mfma_f32_32x32x16_bf16 v[18:33], v[158:161], v[178:181], v[18:33]
	ds_read_b64_tr_b16 v[182:183], v199 offset:55296
	ds_read_b64_tr_b16 v[184:185], v199 offset:55808
	v_fmamk_f32 v119, v188, 0x41100000, v186
	v_fmamk_f32 v103, v188, 0x42240000, v186
	v_cvt_pk_bf16_f32 v175, v68, v69
	v_add_f32_e32 v187, v187, v69
	v_exp_f32_e32 v72, v72
	s_waitcnt lgkmcnt(2)
	v_mfma_f32_32x32x16_bf16 v[18:33], v[154:157], v[200:203], v[18:33]
	ds_read_b64_tr_b16 v[178:179], v199 offset:56320
	ds_read_b64_tr_b16 v[180:181], v199 offset:56832
	v_fmamk_f32 v120, v188, 0x41200000, v186
	v_fmamk_f32 v104, v188, 0x42280000, v186
	v_exp_f32_e32 v73, v73
	v_add_f32_e32 v187, v187, v70
	v_cvt_pk_bf16_f32 v176, v70, v71
	s_waitcnt lgkmcnt(2)
	v_mfma_f32_32x32x16_bf16 v[18:33], v[150:153], v[182:185], v[18:33]
	ds_read_b64_tr_b16 v[200:201], v199 offset:57344
	ds_read_b64_tr_b16 v[202:203], v199 offset:57856
	v_fmamk_f32 v121, v188, 0x41300000, v186
	v_fmamk_f32 v105, v188, 0x422c0000, v186
	v_add_f32_e32 v182, v187, v71
	v_exp_f32_e32 v74, v74
	v_exp_f32_e32 v75, v75
	s_waitcnt lgkmcnt(2)
	v_mfma_f32_32x32x16_bf16 v[18:33], v[146:149], v[178:181], v[18:33]
	ds_read_b64_tr_b16 v[204:205], v199 offset:58368
	ds_read_b64_tr_b16 v[206:207], v199 offset:58880
	v_add_f32_e32 v178, v182, v72
	v_fmamk_f32 v106, v188, 0x42400000, v186
	v_fma_f32 v122, v188, s48, v186
	v_fma_f32 v123, v188, s49, v186
	v_cvt_pk_bf16_f32 v177, v72, v73
	v_add_f32_e32 v187, v73, v178
	s_waitcnt lgkmcnt(2)
	v_mfma_f32_32x32x16_bf16 v[34:49], v[158:161], v[200:203], v[34:49]
	ds_read_b64_tr_b16 v[182:183], v199 offset:59392
	ds_read_b64_tr_b16 v[184:185], v199 offset:59904
	v_fmamk_f32 v107, v188, 0x42440000, v186
	v_fmamk_f32 v124, v188, 0x41900000, v186
	v_exp_f32_e32 v76, v76
	v_exp_f32_e32 v77, v77
	s_waitcnt lgkmcnt(2)
	v_mfma_f32_32x32x16_bf16 v[34:49], v[154:157], v[204:207], v[34:49]
	ds_read_b64_tr_b16 v[178:179], v199 offset:60416
	ds_read_b64_tr_b16 v[180:181], v199 offset:60928
	v_add_f32_e32 v187, v187, v74
	v_fmamk_f32 v108, v188, 0x42480000, v186
	v_fmamk_f32 v125, v188, 0x41980000, v186
	v_cvt_pk_bf16_f32 v170, v74, v75
	v_add_f32_e32 v200, v75, v187
	v_exp_f32_e32 v78, v78
	s_add_u32 s6, s76, s62
	s_addc_u32 s7, s77, s63
	s_add_u32 s26, s6, 0x30000
	s_addc_u32 s27, s7, 0
	s_add_u32 s6, s78, s62
	s_addc_u32 s7, s79, s63
	s_add_u32 s70, s6, 0x30000
	s_addc_u32 s71, s7, 0
	s_add_i32 s6, 0, s59
	s_add_i32 s7, s81, s90
	s_add_u32 s84, s26, 0x8000
	s_addc_u32 s85, s27, 0
	s_add_i32 s15, s6, 0x2000
	s_mov_b32 m0, s6
	s_nop 0
	global_load_lds_dwordx4 v191, s[26:27]
	s_mov_b32 m0, s15
	s_nop 0
	global_load_lds_dwordx4 v191, s[84:85]
	s_mov_b32 m0, s21
	s_add_u32 s26, s70, 0x80
	s_addc_u32 s27, s71, 0
	s_add_i32 s6, s7, 0x2000
	s_mov_b32 m0, s7
	s_nop 0
	global_load_lds_dwordx4 v192, s[70:71]
	s_mov_b32 m0, s6
	s_nop 0
	global_load_lds_dwordx4 v192, s[26:27]
	s_mov_b32 m0, s15
	s_waitcnt lgkmcnt(2)
	v_mfma_f32_32x32x16_bf16 v[34:49], v[150:153], v[182:185], v[34:49]
	ds_read_b64_tr_b16 v[202:203], v199 offset:61440
	ds_read_b64_tr_b16 v[204:205], v199 offset:61952
	v_mov_b32_e32 v189, v188
	v_mov_b32_e32 v187, v186
	v_fma_f32 v182, v188, s56, v186
	v_fma_f32 v183, v189, s57, v187
	v_fmamk_f32 v126, v188, 0x41c00000, v186
	v_exp_f32_e32 v79, v79
	v_add_f32_e32 v187, v200, v76
	v_mov_b32_e32 v109, v182
	v_mov_b32_e32 v110, v183
	s_waitcnt lgkmcnt(2)
	v_mfma_f32_32x32x16_bf16 v[34:49], v[146:149], v[178:181], v[34:49]
	ds_read_b64_tr_b16 v[182:183], v199 offset:62464
	ds_read_b64_tr_b16 v[184:185], v199 offset:62976
	v_fmamk_f32 v127, v188, 0x41c80000, v186
	v_fmamk_f32 v111, v188, 0x42640000, v186
	v_cvt_pk_bf16_f32 v171, v76, v77
	v_add_f32_e32 v187, v187, v77
	v_exp_f32_e32 v80, v80
	s_waitcnt lgkmcnt(2)
	v_mfma_f32_32x32x16_bf16 v[50:65], v[158:161], v[202:205], v[50:65]
	ds_read_b64_tr_b16 v[178:179], v199 offset:63488
	ds_read_b64_tr_b16 v[180:181], v199 offset:64000
	v_fmamk_f32 v128, v188, 0x41d00000, v186
	v_fmamk_f32 v112, v188, 0x42680000, v186
	v_exp_f32_e32 v81, v81
	v_add_f32_e32 v187, v187, v78
	v_cvt_pk_bf16_f32 v172, v78, v79
	s_waitcnt lgkmcnt(2)
	v_mfma_f32_32x32x16_bf16 v[50:65], v[154:157], v[182:185], v[50:65]
	ds_read_b64_tr_b16 v[200:201], v199 offset:64512
	ds_read_b64_tr_b16 v[202:203], v199 offset:65024
	v_fmamk_f32 v129, v188, 0x41d80000, v186
	v_fmac_f32_e32 v186, 0x426c0000, v188
	v_exp_f32_e32 v82, v82
	v_exp_f32_e32 v83, v83
	v_mov_b32_e32 v113, v186
	v_add_f32_e32 v186, v187, v79
	s_waitcnt lgkmcnt(2)
	v_mfma_f32_32x32x16_bf16 v[50:65], v[150:153], v[178:181], v[50:65]
	ds_read_b128 v[182:185], v190 offset:16384
	v_add_f32_e32 v178, v186, v80
	v_cvt_pk_bf16_f32 v173, v80, v81
	v_add_f32_e32 v186, v81, v178
	v_exp_f32_e32 v84, v84
	v_exp_f32_e32 v85, v85
	s_waitcnt lgkmcnt(1)
	v_mfma_f32_32x32x16_bf16 v[50:65], v[146:149], v[200:203], v[50:65]
	ds_read_b128 v[178:181], v190 offset:24576
	v_add_f32_e32 v186, v186, v82
	v_cvt_pk_bf16_f32 v166, v82, v83
	v_add_f32_e32 v199, v83, v186
	v_exp_f32_e32 v86, v86
	v_exp_f32_e32 v87, v87
	s_waitcnt lgkmcnt(1)
	v_mfma_f32_32x32x16_bf16 v[114:129], v[182:185], v[130:133], v[114:129]
	ds_read_b128 v[186:189], v194 offset:16384
	v_add_f32_e32 v182, v199, v84
	v_cvt_pk_bf16_f32 v167, v84, v85
	v_add_f32_e32 v199, v85, v182
	v_exp_f32_e32 v88, v88
	v_exp_f32_e32 v89, v89
	s_waitcnt lgkmcnt(1)
	v_mfma_f32_32x32x16_bf16 v[98:113], v[178:181], v[130:133], v[98:113]
	ds_read_b128 v[182:185], v194 offset:24576
	v_add_f32_e32 v178, v199, v86
	v_cvt_pk_bf16_f32 v168, v86, v87
	v_add_f32_e32 v199, v87, v178
	v_exp_f32_e32 v90, v90
	v_exp_f32_e32 v91, v91
	s_waitcnt lgkmcnt(1)
	v_mfma_f32_32x32x16_bf16 v[114:129], v[186:189], v[134:137], v[114:129]
	ds_read_b128 v[178:181], v195 offset:16384
	v_add_f32_e32 v186, v199, v88
	v_cvt_pk_bf16_f32 v169, v88, v89
	v_add_f32_e32 v199, v89, v186
	v_exp_f32_e32 v92, v92
	v_exp_f32_e32 v93, v93
	s_waitcnt lgkmcnt(1)
	v_mfma_f32_32x32x16_bf16 v[98:113], v[182:185], v[134:137], v[98:113]
	ds_read_b128 v[186:189], v195 offset:24576
	v_add_f32_e32 v182, v199, v90
	v_cvt_pk_bf16_f32 v162, v90, v91
	v_add_f32_e32 v182, v91, v182
	v_exp_f32_e32 v94, v94
	v_exp_f32_e32 v95, v95
	s_waitcnt lgkmcnt(1)
	v_mfma_f32_32x32x16_bf16 v[114:129], v[178:181], v[138:141], v[114:129]
	ds_read_b128 v[200:203], v196 offset:16384
	v_add_f32_e32 v178, v182, v92
	v_cvt_pk_bf16_f32 v163, v92, v93
	v_add_f32_e32 v178, v93, v178
	v_exp_f32_e32 v96, v96
	v_exp_f32_e32 v97, v97
	s_waitcnt lgkmcnt(1)
	v_mfma_f32_32x32x16_bf16 v[98:113], v[186:189], v[138:141], v[98:113]
	ds_read_b128 v[204:207], v196 offset:24576
	v_add_f32_e32 v165, v178, v94
	v_add_f32_e32 v165, v95, v165
	v_add_f32_e32 v178, v96, v165
	v_cvt_pk_bf16_f32 v164, v94, v95
	v_cvt_pk_bf16_f32 v165, v96, v97
	v_add_f32_e32 v187, v97, v178
	s_waitcnt lgkmcnt(1)
	v_mfma_f32_32x32x16_bf16 v[114:129], v[200:203], v[142:145], v[114:129]
	v_add_u32_e32 v199, s80, v240
	ds_read_b64_tr_b16 v[182:183], v199 offset:49152
	ds_read_b64_tr_b16 v[184:185], v199 offset:49664
	s_waitcnt lgkmcnt(2)
	v_mfma_f32_32x32x16_bf16 v[98:113], v[204:207], v[142:145], v[98:113]
	ds_read_b64_tr_b16 v[178:179], v199 offset:50176
	ds_read_b64_tr_b16 v[180:181], v199 offset:50688
	s_waitcnt vmcnt(4) lgkmcnt(0)
	s_barrier
	s_add_i32 s6, s81, 0x4000
	s_cmp_lg_u32 s81, 0x10000
	s_cselect_b32 s21, s6, 0
	s_add_i32 s20, s20, 1
	s_cmp_lt_i32 s20, s89
	v_mfma_f32_32x32x16_bf16 v[2:17], v[174:177], v[182:185], v[2:17]
	s_cselect_b64 s[6:7], -1, 0
	v_cvt_f32_i32_e32 v66, v197
	v_cndmask_b32_e64 v188, -v193, v193, s[6:7]
	ds_read_b64_tr_b16 v[200:201], v199 offset:51200
	ds_read_b64_tr_b16 v[202:203], v199 offset:51712
	v_fma_f32 v186, v188, v66, -v233
	v_exp_f32_e32 v114, v114
	v_exp_f32_e32 v115, v115
	v_fma_f32 v66, 0, v188, v186
	v_fmamk_f32 v82, v188, 0x42000000, v186
	v_add_f32_e32 v67, v188, v186
	v_mfma_f32_32x32x16_bf16 v[2:17], v[170:173], v[178:181], v[2:17]
	ds_read_b64_tr_b16 v[182:183], v199 offset:52224
	ds_read_b64_tr_b16 v[184:185], v199 offset:52736
	v_fmamk_f32 v83, v188, 0x42040000, v186
	v_fma_f32 v68, 2.0, v188, v186
	v_exp_f32_e32 v116, v116
	v_exp_f32_e32 v117, v117
	s_waitcnt lgkmcnt(2)
	v_mfma_f32_32x32x16_bf16 v[2:17], v[166:169], v[200:203], v[2:17]
	ds_read_b64_tr_b16 v[178:179], v199 offset:53248
	ds_read_b64_tr_b16 v[180:181], v199 offset:53760
	v_add_f32_e32 v187, v187, v114
	v_fmamk_f32 v84, v188, 0x42080000, v186
	v_fmamk_f32 v69, v188, 0x40400000, v186
	v_cvt_pk_bf16_f32 v158, v114, v115
	v_add_f32_e32 v187, v115, v187
	v_exp_f32_e32 v118, v118
	s_waitcnt lgkmcnt(2)
	v_mfma_f32_32x32x16_bf16 v[2:17], v[162:165], v[182:185], v[2:17]
	ds_read_b64_tr_b16 v[200:201], v199 offset:54272
	ds_read_b64_tr_b16 v[202:203], v199 offset:54784
	v_fma_f32 v182, v188, s16, v186
	v_fma_f32 v183, v188, s17, v186
	v_fmamk_f32 v70, v188, 0x41000000, v186
	v_exp_f32_e32 v119, v119
	v_add_f32_e32 v187, v187, v116
	v_mov_b32_e32 v85, v182
	v_mov_b32_e32 v86, v183
	s_waitcnt lgkmcnt(2)
	v_mfma_f32_32x32x16_bf16 v[18:33], v[174:177], v[178:181], v[18:33]
	ds_read_b64_tr_b16 v[182:183], v199 offset:55296
	ds_read_b64_tr_b16 v[184:185], v199 offset:55808
	v_fmamk_f32 v71, v188, 0x41100000, v186
	v_fmamk_f32 v87, v188, 0x42240000, v186
	v_cvt_pk_bf16_f32 v159, v116, v117
	v_add_f32_e32 v187, v187, v117
	v_exp_f32_e32 v120, v120
	s_waitcnt lgkmcnt(2)
	v_mfma_f32_32x32x16_bf16 v[18:33], v[170:173], v[200:203], v[18:33]
	ds_read_b64_tr_b16 v[178:179], v199 offset:56320
	ds_read_b64_tr_b16 v[180:181], v199 offset:56832
	v_fmamk_f32 v72, v188, 0x41200000, v186
	v_fmamk_f32 v88, v188, 0x42280000, v186
	v_exp_f32_e32 v121, v121
	v_add_f32_e32 v187, v187, v118
	v_cvt_pk_bf16_f32 v160, v118, v119
	s_waitcnt lgkmcnt(2)
	v_mfma_f32_32x32x16_bf16 v[18:33], v[166:169], v[182:185], v[18:33]
	ds_read_b64_tr_b16 v[200:201], v199 offset:57344
	ds_read_b64_tr_b16 v[202:203], v199 offset:57856
	v_fmamk_f32 v73, v188, 0x41300000, v186
	v_fmamk_f32 v89, v188, 0x422c0000, v186
	v_add_f32_e32 v182, v187, v119
	v_exp_f32_e32 v122, v122
	v_exp_f32_e32 v123, v123
	s_waitcnt lgkmcnt(2)
	v_mfma_f32_32x32x16_bf16 v[18:33], v[162:165], v[178:181], v[18:33]
	ds_read_b64_tr_b16 v[204:205], v199 offset:58368
	ds_read_b64_tr_b16 v[206:207], v199 offset:58880
	v_add_f32_e32 v178, v182, v120
	v_fmamk_f32 v90, v188, 0x42400000, v186
	v_fma_f32 v74, v188, s48, v186
	v_fma_f32 v75, v188, s49, v186
	v_cvt_pk_bf16_f32 v161, v120, v121
	v_add_f32_e32 v187, v121, v178
	s_waitcnt lgkmcnt(2)
	v_mfma_f32_32x32x16_bf16 v[34:49], v[174:177], v[200:203], v[34:49]
	ds_read_b64_tr_b16 v[182:183], v199 offset:59392
	ds_read_b64_tr_b16 v[184:185], v199 offset:59904
	v_fmamk_f32 v91, v188, 0x42440000, v186
	v_fmamk_f32 v76, v188, 0x41900000, v186
	v_exp_f32_e32 v124, v124
	v_exp_f32_e32 v125, v125
	s_waitcnt lgkmcnt(2)
	v_mfma_f32_32x32x16_bf16 v[34:49], v[170:173], v[204:207], v[34:49]
	ds_read_b64_tr_b16 v[178:179], v199 offset:60416
	ds_read_b64_tr_b16 v[180:181], v199 offset:60928
	v_add_f32_e32 v187, v187, v122
	v_fmamk_f32 v92, v188, 0x42480000, v186
	v_fmamk_f32 v77, v188, 0x41980000, v186
	v_cvt_pk_bf16_f32 v154, v122, v123
	v_add_f32_e32 v198, v123, v187
	v_exp_f32_e32 v126, v126
	s_add_u32 s6, s76, s62
	s_addc_u32 s7, s77, s63
	s_add_u32 s6, s6, 0x40000
	s_addc_u32 s7, s7, 0
	s_add_u32 s15, s78, s62
	s_addc_u32 s20, s79, s63
	s_add_u32 s24, s15, 0x40000
	s_addc_u32 s25, s20, 0
	s_add_i32 s15, 0x4000, s59
	s_add_i32 s20, s21, s90
	s_add_u32 s26, s6, 0x8000
	s_addc_u32 s27, s7, 0
	s_add_i32 s68, s15, 0x2000
	s_mov_b32 m0, s15
	s_nop 0
	global_load_lds_dwordx4 v191, s[6:7]
	s_mov_b32 m0, s68
	s_nop 0
	global_load_lds_dwordx4 v191, s[26:27]
	s_mov_b32 m0, s69
	s_add_u32 s6, s24, 0x80
	s_addc_u32 s7, s25, 0
	s_add_i32 s15, s20, 0x2000
	s_mov_b32 m0, s20
	s_nop 0
	global_load_lds_dwordx4 v192, s[24:25]
	s_mov_b32 m0, s15
	s_nop 0
	global_load_lds_dwordx4 v192, s[6:7]
	s_mov_b32 m0, s26
	s_waitcnt lgkmcnt(2)
	v_mfma_f32_32x32x16_bf16 v[34:49], v[166:169], v[182:185], v[34:49]
	ds_read_b64_tr_b16 v[200:201], v199 offset:61440
	ds_read_b64_tr_b16 v[202:203], v199 offset:61952
	v_mov_b32_e32 v189, v188
	v_mov_b32_e32 v187, v186
	s_add_i32 s6, s80, 0x4000
	s_cmp_lg_u32 s80, 0x10000
	v_pk_fma_f32 v[182:183], v[188:189], s[56:57], v[186:187]
	s_cselect_b32 s15, s6, 0
	v_fmamk_f32 v78, v188, 0x41c00000, v186
	v_exp_f32_e32 v127, v127
	v_add_f32_e32 v187, v198, v124
	v_mov_b32_e32 v93, v182
	v_mov_b32_e32 v94, v183
	s_waitcnt lgkmcnt(2)
	v_mfma_f32_32x32x16_bf16 v[34:49], v[162:165], v[178:181], v[34:49]
	ds_read_b64_tr_b16 v[182:183], v199 offset:62464
	ds_read_b64_tr_b16 v[184:185], v199 offset:62976
	v_fmamk_f32 v79, v188, 0x41c80000, v186
	v_fmamk_f32 v95, v188, 0x42640000, v186
	v_cvt_pk_bf16_f32 v155, v124, v125
	v_add_f32_e32 v187, v187, v125
	v_exp_f32_e32 v128, v128
	s_waitcnt lgkmcnt(2)
	v_mfma_f32_32x32x16_bf16 v[50:65], v[174:177], v[200:203], v[50:65]
	ds_read_b64_tr_b16 v[178:179], v199 offset:63488
	ds_read_b64_tr_b16 v[180:181], v199 offset:64000
	v_fmamk_f32 v80, v188, 0x41d00000, v186
	v_fmamk_f32 v96, v188, 0x42680000, v186
	v_exp_f32_e32 v129, v129
	v_add_f32_e32 v187, v187, v126
	v_cvt_pk_bf16_f32 v156, v126, v127
	s_waitcnt lgkmcnt(2)
	v_mfma_f32_32x32x16_bf16 v[50:65], v[170:173], v[182:185], v[50:65]
	ds_read_b64_tr_b16 v[200:201], v199 offset:64512
	ds_read_b64_tr_b16 v[202:203], v199 offset:65024
	v_fmamk_f32 v81, v188, 0x41d80000, v186
	v_fmac_f32_e32 v186, 0x426c0000, v188
	v_exp_f32_e32 v98, v98
	v_exp_f32_e32 v99, v99
	v_mov_b32_e32 v97, v186
	v_add_f32_e32 v186, v187, v127
	s_waitcnt lgkmcnt(2)
	v_mfma_f32_32x32x16_bf16 v[50:65], v[166:169], v[178:181], v[50:65]
	ds_read_b128 v[182:185], v190 offset:32768
	v_add_f32_e32 v178, v186, v128
	v_cvt_pk_bf16_f32 v157, v128, v129
	v_add_f32_e32 v186, v129, v178
	v_exp_f32_e32 v100, v100
	v_exp_f32_e32 v101, v101
	s_waitcnt lgkmcnt(1)
	v_mfma_f32_32x32x16_bf16 v[50:65], v[162:165], v[200:203], v[50:65]
	ds_read_b128 v[178:181], v190 offset:40960
	v_add_f32_e32 v186, v186, v98
	v_cvt_pk_bf16_f32 v150, v98, v99
	v_add_f32_e32 v198, v99, v186
	v_exp_f32_e32 v102, v102
	v_exp_f32_e32 v103, v103
	s_waitcnt lgkmcnt(1)
	v_mfma_f32_32x32x16_bf16 v[66:81], v[182:185], v[130:133], v[66:81]
	ds_read_b128 v[186:189], v194 offset:32768
	v_add_f32_e32 v182, v198, v100
	v_cvt_pk_bf16_f32 v151, v100, v101
	v_add_f32_e32 v198, v101, v182
	v_exp_f32_e32 v104, v104
	v_exp_f32_e32 v105, v105
	s_waitcnt lgkmcnt(1)
	v_mfma_f32_32x32x16_bf16 v[82:97], v[178:181], v[130:133], v[82:97]
	ds_read_b128 v[182:185], v194 offset:40960
	v_add_f32_e32 v178, v198, v102
	v_cvt_pk_bf16_f32 v152, v102, v103
	v_add_f32_e32 v198, v103, v178
	v_exp_f32_e32 v106, v106
	v_exp_f32_e32 v107, v107
	s_waitcnt lgkmcnt(1)
	v_mfma_f32_32x32x16_bf16 v[66:81], v[186:189], v[134:137], v[66:81]
	ds_read_b128 v[178:181], v195 offset:32768
	v_add_f32_e32 v186, v198, v104
	v_cvt_pk_bf16_f32 v153, v104, v105
	v_add_f32_e32 v198, v105, v186
	v_exp_f32_e32 v108, v108
	v_exp_f32_e32 v109, v109
	s_waitcnt lgkmcnt(1)
	v_mfma_f32_32x32x16_bf16 v[82:97], v[182:185], v[134:137], v[82:97]
	ds_read_b128 v[186:189], v195 offset:40960
	v_add_f32_e32 v182, v198, v106
	v_cvt_pk_bf16_f32 v146, v106, v107
	v_add_f32_e32 v182, v107, v182
	v_exp_f32_e32 v110, v110
	v_exp_f32_e32 v111, v111
	s_waitcnt lgkmcnt(1)
	v_mfma_f32_32x32x16_bf16 v[66:81], v[178:181], v[138:141], v[66:81]
	ds_read_b128 v[198:201], v196 offset:32768
	v_add_f32_e32 v178, v182, v108
	v_cvt_pk_bf16_f32 v147, v108, v109
	v_add_f32_e32 v178, v109, v178
	v_exp_f32_e32 v112, v112
	v_exp_f32_e32 v113, v113
	s_waitcnt lgkmcnt(1)
	v_mfma_f32_32x32x16_bf16 v[82:97], v[186:189], v[138:141], v[82:97]
	ds_read_b128 v[202:205], v196 offset:40960
	v_add_f32_e32 v149, v178, v110
	v_add_f32_e32 v149, v111, v149
	v_add_f32_e32 v178, v112, v149
	v_cvt_pk_bf16_f32 v148, v110, v111
	v_cvt_pk_bf16_f32 v149, v112, v113
	v_add_f32_e32 v187, v113, v178
	s_waitcnt lgkmcnt(1)
	v_mfma_f32_32x32x16_bf16 v[66:81], v[198:201], v[142:145], v[66:81]
	v_add_u32_e32 v180, s15, v240
	ds_read_b64_tr_b16 v[182:183], v180 offset:49152
	ds_read_b64_tr_b16 v[184:185], v180 offset:49664
	s_waitcnt lgkmcnt(2)
	v_mfma_f32_32x32x16_bf16 v[82:97], v[202:205], v[142:145], v[82:97]
	ds_read_b64_tr_b16 v[178:179], v180 offset:50176
	ds_read_b64_tr_b16 v[180:181], v180 offset:50688
	s_add_i32 s6, s15, 0x4000
	s_cmp_lg_u32 s15, 0x10000
	s_cselect_b32 s80, s6, 0
	s_add_i32 s6, s21, 0x4000
	s_cmp_lg_u32 s21, 0x10000
	s_cselect_b32 s81, s6, 0
	s_add_u32 s78, s78, 0x20000
	s_addc_u32 s79, s79, 0
	s_add_u32 s76, s76, 0x20000
	s_addc_u32 s77, s77, 0
	v_add_u32_e32 v197, 0x80, v197
	s_mov_b32 s43, s0
	s_add_i32 s0, s43, 2
	s_waitcnt vmcnt(4) lgkmcnt(0)
	s_barrier
	s_add_i32 s20, s58, s43
	s_cmp_lt_i32 s20, s89
	v_mfma_f32_32x32x16_bf16 v[2:17], v[158:161], v[182:185], v[2:17]
	v_subrev_u32_e32 v198, 64, v197
	s_cselect_b64 s[26:27], -1, 0
	v_cvt_f32_i32_e32 v98, v198
	v_cndmask_b32_e64 v188, -v193, v193, s[26:27]
	v_add_u32_e32 v199, s15, v240
	ds_read_b64_tr_b16 v[200:201], v199 offset:51200
	ds_read_b64_tr_b16 v[202:203], v199 offset:51712
	v_fma_f32 v186, v188, v98, -v233
	v_exp_f32_e32 v66, v66
	v_exp_f32_e32 v67, v67
	v_fma_f32 v114, 0, v188, v186
	v_fmamk_f32 v98, v188, 0x42000000, v186
	v_add_f32_e32 v115, v188, v186
	v_mfma_f32_32x32x16_bf16 v[2:17], v[154:157], v[178:181], v[2:17]
	ds_read_b64_tr_b16 v[182:183], v199 offset:52224
	ds_read_b64_tr_b16 v[184:185], v199 offset:52736
	v_fmamk_f32 v99, v188, 0x42040000, v186
	v_fma_f32 v116, 2.0, v188, v186
	v_exp_f32_e32 v68, v68
	v_exp_f32_e32 v69, v69
	s_waitcnt lgkmcnt(2)
	v_mfma_f32_32x32x16_bf16 v[2:17], v[150:153], v[200:203], v[2:17]
	ds_read_b64_tr_b16 v[178:179], v199 offset:53248
	ds_read_b64_tr_b16 v[180:181], v199 offset:53760
	v_add_f32_e32 v187, v187, v66
	v_fmamk_f32 v100, v188, 0x42080000, v186
	v_fmamk_f32 v117, v188, 0x40400000, v186
	v_cvt_pk_bf16_f32 v174, v66, v67
	v_add_f32_e32 v187, v67, v187
	v_exp_f32_e32 v70, v70
	s_waitcnt lgkmcnt(2)
	v_mfma_f32_32x32x16_bf16 v[2:17], v[146:149], v[182:185], v[2:17]
	ds_read_b64_tr_b16 v[200:201], v199 offset:54272
	ds_read_b64_tr_b16 v[202:203], v199 offset:54784
	v_fma_f32 v182, v188, s16, v186
	v_fma_f32 v183, v188, s17, v186
	v_fmamk_f32 v118, v188, 0x41000000, v186
	v_exp_f32_e32 v71, v71
	v_add_f32_e32 v187, v187, v68
	v_mov_b32_e32 v101, v182
	v_mov_b32_e32 v102, v183
	s_waitcnt lgkmcnt(2)
	v_mfma_f32_32x32x16_bf16 v[18:33], v[158:161], v[178:181], v[18:33]
	ds_read_b64_tr_b16 v[182:183], v199 offset:55296
	ds_read_b64_tr_b16 v[184:185], v199 offset:55808
	v_fmamk_f32 v119, v188, 0x41100000, v186
	v_fmamk_f32 v103, v188, 0x42240000, v186
	v_cvt_pk_bf16_f32 v175, v68, v69
	v_add_f32_e32 v187, v187, v69
	v_exp_f32_e32 v72, v72
	s_waitcnt lgkmcnt(2)
	v_mfma_f32_32x32x16_bf16 v[18:33], v[154:157], v[200:203], v[18:33]
	ds_read_b64_tr_b16 v[178:179], v199 offset:56320
	ds_read_b64_tr_b16 v[180:181], v199 offset:56832
	v_fmamk_f32 v120, v188, 0x41200000, v186
	v_fmamk_f32 v104, v188, 0x42280000, v186
	v_exp_f32_e32 v73, v73
	v_add_f32_e32 v187, v187, v70
	v_cvt_pk_bf16_f32 v176, v70, v71
	s_waitcnt lgkmcnt(2)
	v_mfma_f32_32x32x16_bf16 v[18:33], v[150:153], v[182:185], v[18:33]
	ds_read_b64_tr_b16 v[200:201], v199 offset:57344
	ds_read_b64_tr_b16 v[202:203], v199 offset:57856
	v_fmamk_f32 v121, v188, 0x41300000, v186
	v_fmamk_f32 v105, v188, 0x422c0000, v186
	v_add_f32_e32 v182, v187, v71
	v_exp_f32_e32 v74, v74
	v_exp_f32_e32 v75, v75
	s_waitcnt lgkmcnt(2)
	v_mfma_f32_32x32x16_bf16 v[18:33], v[146:149], v[178:181], v[18:33]
	ds_read_b64_tr_b16 v[204:205], v199 offset:58368
	ds_read_b64_tr_b16 v[206:207], v199 offset:58880
	v_add_f32_e32 v178, v182, v72
	v_fmamk_f32 v106, v188, 0x42400000, v186
	v_fma_f32 v122, v188, s48, v186
	v_fma_f32 v123, v188, s49, v186
	v_cvt_pk_bf16_f32 v177, v72, v73
	v_add_f32_e32 v187, v73, v178
	s_waitcnt lgkmcnt(2)
	v_mfma_f32_32x32x16_bf16 v[34:49], v[158:161], v[200:203], v[34:49]
	ds_read_b64_tr_b16 v[182:183], v199 offset:59392
	ds_read_b64_tr_b16 v[184:185], v199 offset:59904
	v_fmamk_f32 v107, v188, 0x42440000, v186
	v_fmamk_f32 v124, v188, 0x41900000, v186
	v_exp_f32_e32 v76, v76
	v_exp_f32_e32 v77, v77
	s_waitcnt lgkmcnt(2)
	v_mfma_f32_32x32x16_bf16 v[34:49], v[154:157], v[204:207], v[34:49]
	ds_read_b64_tr_b16 v[178:179], v199 offset:60416
	ds_read_b64_tr_b16 v[180:181], v199 offset:60928
	v_add_f32_e32 v187, v187, v74
	v_fmamk_f32 v108, v188, 0x42480000, v186
	v_fmamk_f32 v125, v188, 0x41980000, v186
	v_cvt_pk_bf16_f32 v170, v74, v75
	v_add_f32_e32 v200, v75, v187
	v_exp_f32_e32 v78, v78
	s_add_u32 s6, s76, s62
	s_addc_u32 s7, s77, s63
	s_add_u32 s26, s6, 0x30000
	s_addc_u32 s27, s7, 0
	s_add_u32 s6, s78, s62
	s_addc_u32 s7, s79, s63
	s_add_u32 s70, s6, 0x30000
	s_addc_u32 s71, s7, 0
	s_add_i32 s6, 0x8000, s59
	s_add_i32 s7, s81, s90
	s_add_u32 s84, s26, 0x8000
	s_addc_u32 s85, s27, 0
	s_add_i32 s15, s6, 0x2000
	s_mov_b32 m0, s6
	s_nop 0
	global_load_lds_dwordx4 v191, s[26:27]
	s_mov_b32 m0, s15
	s_nop 0
	global_load_lds_dwordx4 v191, s[84:85]
	s_mov_b32 m0, s21
	s_add_u32 s26, s70, 0x80
	s_addc_u32 s27, s71, 0
	s_add_i32 s6, s7, 0x2000
	s_mov_b32 m0, s7
	s_nop 0
	global_load_lds_dwordx4 v192, s[70:71]
	s_mov_b32 m0, s6
	s_nop 0
	global_load_lds_dwordx4 v192, s[26:27]
	s_mov_b32 m0, s15
	s_waitcnt lgkmcnt(2)
	v_mfma_f32_32x32x16_bf16 v[34:49], v[150:153], v[182:185], v[34:49]
	ds_read_b64_tr_b16 v[202:203], v199 offset:61440
	ds_read_b64_tr_b16 v[204:205], v199 offset:61952
	v_mov_b32_e32 v189, v188
	v_mov_b32_e32 v187, v186
	v_fma_f32 v182, v188, s56, v186
	v_fma_f32 v183, v189, s57, v187
	v_fmamk_f32 v126, v188, 0x41c00000, v186
	v_exp_f32_e32 v79, v79
	v_add_f32_e32 v187, v200, v76
	v_mov_b32_e32 v109, v182
	v_mov_b32_e32 v110, v183
	s_waitcnt lgkmcnt(2)
	v_mfma_f32_32x32x16_bf16 v[34:49], v[146:149], v[178:181], v[34:49]
	ds_read_b64_tr_b16 v[182:183], v199 offset:62464
	ds_read_b64_tr_b16 v[184:185], v199 offset:62976
	v_fmamk_f32 v127, v188, 0x41c80000, v186
	v_fmamk_f32 v111, v188, 0x42640000, v186
	v_cvt_pk_bf16_f32 v171, v76, v77
	v_add_f32_e32 v187, v187, v77
	v_exp_f32_e32 v80, v80
	s_waitcnt lgkmcnt(2)
	v_mfma_f32_32x32x16_bf16 v[50:65], v[158:161], v[202:205], v[50:65]
	ds_read_b64_tr_b16 v[178:179], v199 offset:63488
	ds_read_b64_tr_b16 v[180:181], v199 offset:64000
	v_fmamk_f32 v128, v188, 0x41d00000, v186
	v_fmamk_f32 v112, v188, 0x42680000, v186
	v_exp_f32_e32 v81, v81
	v_add_f32_e32 v187, v187, v78
	v_cvt_pk_bf16_f32 v172, v78, v79
	s_waitcnt lgkmcnt(2)
	v_mfma_f32_32x32x16_bf16 v[50:65], v[154:157], v[182:185], v[50:65]
	ds_read_b64_tr_b16 v[200:201], v199 offset:64512
	ds_read_b64_tr_b16 v[202:203], v199 offset:65024
	v_fmamk_f32 v129, v188, 0x41d80000, v186
	v_fmac_f32_e32 v186, 0x426c0000, v188
	v_exp_f32_e32 v82, v82
	v_exp_f32_e32 v83, v83
	v_mov_b32_e32 v113, v186
	v_add_f32_e32 v186, v187, v79
	s_waitcnt lgkmcnt(2)
	v_mfma_f32_32x32x16_bf16 v[50:65], v[150:153], v[178:181], v[50:65]
	ds_read_b128 v[182:185], v190
	v_add_f32_e32 v178, v186, v80
	v_cvt_pk_bf16_f32 v173, v80, v81
	v_add_f32_e32 v186, v81, v178
	v_exp_f32_e32 v84, v84
	v_exp_f32_e32 v85, v85
	s_waitcnt lgkmcnt(1)
	v_mfma_f32_32x32x16_bf16 v[50:65], v[146:149], v[200:203], v[50:65]
	ds_read_b128 v[178:181], v190 offset:8192
	v_add_f32_e32 v186, v186, v82
	v_cvt_pk_bf16_f32 v166, v82, v83
	v_add_f32_e32 v199, v83, v186
	v_exp_f32_e32 v86, v86
	v_exp_f32_e32 v87, v87
	s_waitcnt lgkmcnt(1)
	v_mfma_f32_32x32x16_bf16 v[114:129], v[182:185], v[130:133], v[114:129]
	ds_read_b128 v[186:189], v194
	v_add_f32_e32 v182, v199, v84
	v_cvt_pk_bf16_f32 v167, v84, v85
	v_add_f32_e32 v199, v85, v182
	v_exp_f32_e32 v88, v88
	v_exp_f32_e32 v89, v89
	s_waitcnt lgkmcnt(1)
	v_mfma_f32_32x32x16_bf16 v[98:113], v[178:181], v[130:133], v[98:113]
	ds_read_b128 v[182:185], v194 offset:8192
	v_add_f32_e32 v178, v199, v86
	v_cvt_pk_bf16_f32 v168, v86, v87
	v_add_f32_e32 v199, v87, v178
	v_exp_f32_e32 v90, v90
	v_exp_f32_e32 v91, v91
	s_waitcnt lgkmcnt(1)
	v_mfma_f32_32x32x16_bf16 v[114:129], v[186:189], v[134:137], v[114:129]
	ds_read_b128 v[178:181], v195
	v_add_f32_e32 v186, v199, v88
	v_cvt_pk_bf16_f32 v169, v88, v89
	v_add_f32_e32 v199, v89, v186
	v_exp_f32_e32 v92, v92
	v_exp_f32_e32 v93, v93
	s_waitcnt lgkmcnt(1)
	v_mfma_f32_32x32x16_bf16 v[98:113], v[182:185], v[134:137], v[98:113]
	ds_read_b128 v[186:189], v195 offset:8192
	v_add_f32_e32 v182, v199, v90
	v_cvt_pk_bf16_f32 v162, v90, v91
	v_add_f32_e32 v182, v91, v182
	v_exp_f32_e32 v94, v94
	v_exp_f32_e32 v95, v95
	s_waitcnt lgkmcnt(1)
	v_mfma_f32_32x32x16_bf16 v[114:129], v[178:181], v[138:141], v[114:129]
	ds_read_b128 v[200:203], v196
	v_add_f32_e32 v178, v182, v92
	v_cvt_pk_bf16_f32 v163, v92, v93
	v_add_f32_e32 v178, v93, v178
	v_exp_f32_e32 v96, v96
	v_exp_f32_e32 v97, v97
	s_waitcnt lgkmcnt(1)
	v_mfma_f32_32x32x16_bf16 v[98:113], v[186:189], v[138:141], v[98:113]
	ds_read_b128 v[204:207], v196 offset:8192
	v_add_f32_e32 v165, v178, v94
	v_add_f32_e32 v165, v95, v165
	v_add_f32_e32 v178, v96, v165
	v_cvt_pk_bf16_f32 v164, v94, v95
	v_cvt_pk_bf16_f32 v165, v96, v97
	v_add_f32_e32 v187, v97, v178
	s_waitcnt lgkmcnt(1)
	v_mfma_f32_32x32x16_bf16 v[114:129], v[200:203], v[142:145], v[114:129]
	v_add_u32_e32 v199, s80, v240
	ds_read_b64_tr_b16 v[182:183], v199 offset:49152
	ds_read_b64_tr_b16 v[184:185], v199 offset:49664
	s_waitcnt lgkmcnt(2)
	v_mfma_f32_32x32x16_bf16 v[98:113], v[204:207], v[142:145], v[98:113]
	ds_read_b64_tr_b16 v[178:179], v199 offset:50176
	ds_read_b64_tr_b16 v[180:181], v199 offset:50688
	s_waitcnt vmcnt(4) lgkmcnt(0)
	s_barrier
	s_add_i32 s6, s81, 0x4000
	s_cmp_lg_u32 s81, 0x10000
	s_cselect_b32 s21, s6, 0
	s_add_i32 s20, s20, 1
	s_cmp_lt_i32 s20, s89
	v_mfma_f32_32x32x16_bf16 v[2:17], v[174:177], v[182:185], v[2:17]
	s_cselect_b64 s[6:7], -1, 0
	v_cvt_f32_i32_e32 v66, v197
	v_cndmask_b32_e64 v188, -v193, v193, s[6:7]
	ds_read_b64_tr_b16 v[200:201], v199 offset:51200
	ds_read_b64_tr_b16 v[202:203], v199 offset:51712
	v_fma_f32 v186, v188, v66, -v233
	v_exp_f32_e32 v114, v114
	v_exp_f32_e32 v115, v115
	v_fma_f32 v66, 0, v188, v186
	v_fmamk_f32 v82, v188, 0x42000000, v186
	v_add_f32_e32 v67, v188, v186
	v_mfma_f32_32x32x16_bf16 v[2:17], v[170:173], v[178:181], v[2:17]
	ds_read_b64_tr_b16 v[182:183], v199 offset:52224
	ds_read_b64_tr_b16 v[184:185], v199 offset:52736
	v_fmamk_f32 v83, v188, 0x42040000, v186
	v_fma_f32 v68, 2.0, v188, v186
	v_exp_f32_e32 v116, v116
	v_exp_f32_e32 v117, v117
	s_waitcnt lgkmcnt(2)
	v_mfma_f32_32x32x16_bf16 v[2:17], v[166:169], v[200:203], v[2:17]
	ds_read_b64_tr_b16 v[178:179], v199 offset:53248
	ds_read_b64_tr_b16 v[180:181], v199 offset:53760
	v_add_f32_e32 v187, v187, v114
	v_fmamk_f32 v84, v188, 0x42080000, v186
	v_fmamk_f32 v69, v188, 0x40400000, v186
	v_cvt_pk_bf16_f32 v158, v114, v115
	v_add_f32_e32 v187, v115, v187
	v_exp_f32_e32 v118, v118
	s_waitcnt lgkmcnt(2)
	v_mfma_f32_32x32x16_bf16 v[2:17], v[162:165], v[182:185], v[2:17]
	ds_read_b64_tr_b16 v[200:201], v199 offset:54272
	ds_read_b64_tr_b16 v[202:203], v199 offset:54784
	v_fma_f32 v182, v188, s16, v186
	v_fma_f32 v183, v188, s17, v186
	v_fmamk_f32 v70, v188, 0x41000000, v186
	v_exp_f32_e32 v119, v119
	v_add_f32_e32 v187, v187, v116
	v_mov_b32_e32 v85, v182
	v_mov_b32_e32 v86, v183
	s_waitcnt lgkmcnt(2)
	v_mfma_f32_32x32x16_bf16 v[18:33], v[174:177], v[178:181], v[18:33]
	ds_read_b64_tr_b16 v[182:183], v199 offset:55296
	ds_read_b64_tr_b16 v[184:185], v199 offset:55808
	v_fmamk_f32 v71, v188, 0x41100000, v186
	v_fmamk_f32 v87, v188, 0x42240000, v186
	v_cvt_pk_bf16_f32 v159, v116, v117
	v_add_f32_e32 v187, v187, v117
	v_exp_f32_e32 v120, v120
	s_waitcnt lgkmcnt(2)
	v_mfma_f32_32x32x16_bf16 v[18:33], v[170:173], v[200:203], v[18:33]
	ds_read_b64_tr_b16 v[178:179], v199 offset:56320
	ds_read_b64_tr_b16 v[180:181], v199 offset:56832
	v_fmamk_f32 v72, v188, 0x41200000, v186
	v_fmamk_f32 v88, v188, 0x42280000, v186
	v_exp_f32_e32 v121, v121
	v_add_f32_e32 v187, v187, v118
	v_cvt_pk_bf16_f32 v160, v118, v119
	s_waitcnt lgkmcnt(2)
	v_mfma_f32_32x32x16_bf16 v[18:33], v[166:169], v[182:185], v[18:33]
	ds_read_b64_tr_b16 v[200:201], v199 offset:57344
	ds_read_b64_tr_b16 v[202:203], v199 offset:57856
	v_fmamk_f32 v73, v188, 0x41300000, v186
	v_fmamk_f32 v89, v188, 0x422c0000, v186
	v_add_f32_e32 v182, v187, v119
	v_exp_f32_e32 v122, v122
	v_exp_f32_e32 v123, v123
	s_waitcnt lgkmcnt(2)
	v_mfma_f32_32x32x16_bf16 v[18:33], v[162:165], v[178:181], v[18:33]
	ds_read_b64_tr_b16 v[204:205], v199 offset:58368
	ds_read_b64_tr_b16 v[206:207], v199 offset:58880
	v_add_f32_e32 v178, v182, v120
	v_fmamk_f32 v90, v188, 0x42400000, v186
	v_fma_f32 v74, v188, s48, v186
	v_fma_f32 v75, v188, s49, v186
	v_cvt_pk_bf16_f32 v161, v120, v121
	v_add_f32_e32 v187, v121, v178
	s_waitcnt lgkmcnt(2)
	v_mfma_f32_32x32x16_bf16 v[34:49], v[174:177], v[200:203], v[34:49]
	ds_read_b64_tr_b16 v[182:183], v199 offset:59392
	ds_read_b64_tr_b16 v[184:185], v199 offset:59904
	v_fmamk_f32 v91, v188, 0x42440000, v186
	v_fmamk_f32 v76, v188, 0x41900000, v186
	v_exp_f32_e32 v124, v124
	v_exp_f32_e32 v125, v125
	s_waitcnt lgkmcnt(2)
	v_mfma_f32_32x32x16_bf16 v[34:49], v[170:173], v[204:207], v[34:49]
	ds_read_b64_tr_b16 v[178:179], v199 offset:60416
	ds_read_b64_tr_b16 v[180:181], v199 offset:60928
	v_add_f32_e32 v187, v187, v122
	v_fmamk_f32 v92, v188, 0x42480000, v186
	v_fmamk_f32 v77, v188, 0x41980000, v186
	v_cvt_pk_bf16_f32 v154, v122, v123
	v_add_f32_e32 v198, v123, v187
	v_exp_f32_e32 v126, v126
	s_add_u32 s6, s76, s62
	s_addc_u32 s7, s77, s63
	s_add_u32 s6, s6, 0x40000
	s_addc_u32 s7, s7, 0
	s_add_u32 s15, s78, s62
	s_addc_u32 s20, s79, s63
	s_add_u32 s24, s15, 0x40000
	s_addc_u32 s25, s20, 0
	s_add_i32 s15, 0, s59
	s_add_i32 s20, s21, s90
	s_add_u32 s26, s6, 0x8000
	s_addc_u32 s27, s7, 0
	s_add_i32 s68, s15, 0x2000
	s_mov_b32 m0, s15
	s_nop 0
	global_load_lds_dwordx4 v191, s[6:7]
	s_mov_b32 m0, s68
	s_nop 0
	global_load_lds_dwordx4 v191, s[26:27]
	s_mov_b32 m0, s69
	s_add_u32 s6, s24, 0x80
	s_addc_u32 s7, s25, 0
	s_add_i32 s15, s20, 0x2000
	s_mov_b32 m0, s20
	s_nop 0
	global_load_lds_dwordx4 v192, s[24:25]
	s_mov_b32 m0, s15
	s_nop 0
	global_load_lds_dwordx4 v192, s[6:7]
	s_mov_b32 m0, s26
	s_waitcnt lgkmcnt(2)
	v_mfma_f32_32x32x16_bf16 v[34:49], v[166:169], v[182:185], v[34:49]
	ds_read_b64_tr_b16 v[200:201], v199 offset:61440
	ds_read_b64_tr_b16 v[202:203], v199 offset:61952
	v_mov_b32_e32 v189, v188
	v_mov_b32_e32 v187, v186
	s_add_i32 s6, s80, 0x4000
	s_cmp_lg_u32 s80, 0x10000
	v_pk_fma_f32 v[182:183], v[188:189], s[56:57], v[186:187]
	s_cselect_b32 s15, s6, 0
	v_fmamk_f32 v78, v188, 0x41c00000, v186
	v_exp_f32_e32 v127, v127
	v_add_f32_e32 v187, v198, v124
	v_mov_b32_e32 v93, v182
	v_mov_b32_e32 v94, v183
	s_waitcnt lgkmcnt(2)
	v_mfma_f32_32x32x16_bf16 v[34:49], v[162:165], v[178:181], v[34:49]
	ds_read_b64_tr_b16 v[182:183], v199 offset:62464
	ds_read_b64_tr_b16 v[184:185], v199 offset:62976
	v_fmamk_f32 v79, v188, 0x41c80000, v186
	v_fmamk_f32 v95, v188, 0x42640000, v186
	v_cvt_pk_bf16_f32 v155, v124, v125
	v_add_f32_e32 v187, v187, v125
	v_exp_f32_e32 v128, v128
	s_waitcnt lgkmcnt(2)
	v_mfma_f32_32x32x16_bf16 v[50:65], v[174:177], v[200:203], v[50:65]
	ds_read_b64_tr_b16 v[178:179], v199 offset:63488
	ds_read_b64_tr_b16 v[180:181], v199 offset:64000
	v_fmamk_f32 v80, v188, 0x41d00000, v186
	v_fmamk_f32 v96, v188, 0x42680000, v186
	v_exp_f32_e32 v129, v129
	v_add_f32_e32 v187, v187, v126
	v_cvt_pk_bf16_f32 v156, v126, v127
	s_waitcnt lgkmcnt(2)
	v_mfma_f32_32x32x16_bf16 v[50:65], v[170:173], v[182:185], v[50:65]
	ds_read_b64_tr_b16 v[200:201], v199 offset:64512
	ds_read_b64_tr_b16 v[202:203], v199 offset:65024
	v_fmamk_f32 v81, v188, 0x41d80000, v186
	v_fmac_f32_e32 v186, 0x426c0000, v188
	v_exp_f32_e32 v98, v98
	v_exp_f32_e32 v99, v99
	v_mov_b32_e32 v97, v186
	v_add_f32_e32 v186, v187, v127
	s_waitcnt lgkmcnt(2)
	v_mfma_f32_32x32x16_bf16 v[50:65], v[166:169], v[178:181], v[50:65]
	ds_read_b128 v[182:185], v190 offset:16384
	v_add_f32_e32 v178, v186, v128
	v_cvt_pk_bf16_f32 v157, v128, v129
	v_add_f32_e32 v186, v129, v178
	v_exp_f32_e32 v100, v100
	v_exp_f32_e32 v101, v101
	s_waitcnt lgkmcnt(1)
	v_mfma_f32_32x32x16_bf16 v[50:65], v[162:165], v[200:203], v[50:65]
	ds_read_b128 v[178:181], v190 offset:24576
	v_add_f32_e32 v186, v186, v98
	v_cvt_pk_bf16_f32 v150, v98, v99
	v_add_f32_e32 v198, v99, v186
	v_exp_f32_e32 v102, v102
	v_exp_f32_e32 v103, v103
	s_waitcnt lgkmcnt(1)
	v_mfma_f32_32x32x16_bf16 v[66:81], v[182:185], v[130:133], v[66:81]
	ds_read_b128 v[186:189], v194 offset:16384
	v_add_f32_e32 v182, v198, v100
	v_cvt_pk_bf16_f32 v151, v100, v101
	v_add_f32_e32 v198, v101, v182
	v_exp_f32_e32 v104, v104
	v_exp_f32_e32 v105, v105
	s_waitcnt lgkmcnt(1)
	v_mfma_f32_32x32x16_bf16 v[82:97], v[178:181], v[130:133], v[82:97]
	ds_read_b128 v[182:185], v194 offset:24576
	v_add_f32_e32 v178, v198, v102
	v_cvt_pk_bf16_f32 v152, v102, v103
	v_add_f32_e32 v198, v103, v178
	v_exp_f32_e32 v106, v106
	v_exp_f32_e32 v107, v107
	s_waitcnt lgkmcnt(1)
	v_mfma_f32_32x32x16_bf16 v[66:81], v[186:189], v[134:137], v[66:81]
	ds_read_b128 v[178:181], v195 offset:16384
	v_add_f32_e32 v186, v198, v104
	v_cvt_pk_bf16_f32 v153, v104, v105
	v_add_f32_e32 v198, v105, v186
	v_exp_f32_e32 v108, v108
	v_exp_f32_e32 v109, v109
	s_waitcnt lgkmcnt(1)
	v_mfma_f32_32x32x16_bf16 v[82:97], v[182:185], v[134:137], v[82:97]
	ds_read_b128 v[186:189], v195 offset:24576
	v_add_f32_e32 v182, v198, v106
	v_cvt_pk_bf16_f32 v146, v106, v107
	v_add_f32_e32 v182, v107, v182
	v_exp_f32_e32 v110, v110
	v_exp_f32_e32 v111, v111
	s_waitcnt lgkmcnt(1)
	v_mfma_f32_32x32x16_bf16 v[66:81], v[178:181], v[138:141], v[66:81]
	ds_read_b128 v[198:201], v196 offset:16384
	v_add_f32_e32 v178, v182, v108
	v_cvt_pk_bf16_f32 v147, v108, v109
	v_add_f32_e32 v178, v109, v178
	v_exp_f32_e32 v112, v112
	v_exp_f32_e32 v113, v113
	s_waitcnt lgkmcnt(1)
	v_mfma_f32_32x32x16_bf16 v[82:97], v[186:189], v[138:141], v[82:97]
	ds_read_b128 v[202:205], v196 offset:24576
	v_add_f32_e32 v149, v178, v110
	v_add_f32_e32 v149, v111, v149
	v_add_f32_e32 v178, v112, v149
	v_cvt_pk_bf16_f32 v148, v110, v111
	v_cvt_pk_bf16_f32 v149, v112, v113
	v_add_f32_e32 v187, v113, v178
	s_waitcnt lgkmcnt(1)
	v_mfma_f32_32x32x16_bf16 v[66:81], v[198:201], v[142:145], v[66:81]
	v_add_u32_e32 v180, s15, v240
	ds_read_b64_tr_b16 v[182:183], v180 offset:49152
	ds_read_b64_tr_b16 v[184:185], v180 offset:49664
	s_waitcnt lgkmcnt(2)
	v_mfma_f32_32x32x16_bf16 v[82:97], v[202:205], v[142:145], v[82:97]
	ds_read_b64_tr_b16 v[178:179], v180 offset:50176
	ds_read_b64_tr_b16 v[180:181], v180 offset:50688
	s_add_i32 s6, s15, 0x4000
	s_cmp_lg_u32 s15, 0x10000
	s_cselect_b32 s80, s6, 0
	s_add_i32 s6, s21, 0x4000
	s_cmp_lg_u32 s21, 0x10000
	s_cselect_b32 s81, s6, 0
	s_add_u32 s78, s78, 0x20000
	s_addc_u32 s79, s79, 0
	s_add_u32 s76, s76, 0x20000
	s_addc_u32 s77, s77, 0
	v_add_u32_e32 v197, 0x80, v197
	s_mov_b32 s43, s0
	s_add_i32 s0, s43, 2
	s_waitcnt vmcnt(4) lgkmcnt(0)
	s_barrier
	s_add_i32 s20, s58, s43
	s_cmp_lt_i32 s20, s89
	v_mfma_f32_32x32x16_bf16 v[2:17], v[158:161], v[182:185], v[2:17]
	v_subrev_u32_e32 v198, 64, v197
	s_cselect_b64 s[26:27], -1, 0
	v_cvt_f32_i32_e32 v98, v198
	v_cndmask_b32_e64 v188, -v193, v193, s[26:27]
	v_add_u32_e32 v199, s15, v240
	ds_read_b64_tr_b16 v[200:201], v199 offset:51200
	ds_read_b64_tr_b16 v[202:203], v199 offset:51712
	v_fma_f32 v186, v188, v98, -v233
	v_exp_f32_e32 v66, v66
	v_exp_f32_e32 v67, v67
	v_fma_f32 v114, 0, v188, v186
	v_fmamk_f32 v98, v188, 0x42000000, v186
	v_add_f32_e32 v115, v188, v186
	v_mfma_f32_32x32x16_bf16 v[2:17], v[154:157], v[178:181], v[2:17]
	ds_read_b64_tr_b16 v[182:183], v199 offset:52224
	ds_read_b64_tr_b16 v[184:185], v199 offset:52736
	v_fmamk_f32 v99, v188, 0x42040000, v186
	v_fma_f32 v116, 2.0, v188, v186
	v_exp_f32_e32 v68, v68
	v_exp_f32_e32 v69, v69
	s_waitcnt lgkmcnt(2)
	v_mfma_f32_32x32x16_bf16 v[2:17], v[150:153], v[200:203], v[2:17]
	ds_read_b64_tr_b16 v[178:179], v199 offset:53248
	ds_read_b64_tr_b16 v[180:181], v199 offset:53760
	v_add_f32_e32 v187, v187, v66
	v_fmamk_f32 v100, v188, 0x42080000, v186
	v_fmamk_f32 v117, v188, 0x40400000, v186
	v_cvt_pk_bf16_f32 v174, v66, v67
	v_add_f32_e32 v187, v67, v187
	v_exp_f32_e32 v70, v70
	s_waitcnt lgkmcnt(2)
	v_mfma_f32_32x32x16_bf16 v[2:17], v[146:149], v[182:185], v[2:17]
	ds_read_b64_tr_b16 v[200:201], v199 offset:54272
	ds_read_b64_tr_b16 v[202:203], v199 offset:54784
	v_fma_f32 v182, v188, s16, v186
	v_fma_f32 v183, v188, s17, v186
	v_fmamk_f32 v118, v188, 0x41000000, v186
	v_exp_f32_e32 v71, v71
	v_add_f32_e32 v187, v187, v68
	v_mov_b32_e32 v101, v182
	v_mov_b32_e32 v102, v183
	s_waitcnt lgkmcnt(2)
	v_mfma_f32_32x32x16_bf16 v[18:33], v[158:161], v[178:181], v[18:33]
	ds_read_b64_tr_b16 v[182:183], v199 offset:55296
	ds_read_b64_tr_b16 v[184:185], v199 offset:55808
	v_fmamk_f32 v119, v188, 0x41100000, v186
	v_fmamk_f32 v103, v188, 0x42240000, v186
	v_cvt_pk_bf16_f32 v175, v68, v69
	v_add_f32_e32 v187, v187, v69
	v_exp_f32_e32 v72, v72
	s_waitcnt lgkmcnt(2)
	v_mfma_f32_32x32x16_bf16 v[18:33], v[154:157], v[200:203], v[18:33]
	ds_read_b64_tr_b16 v[178:179], v199 offset:56320
	ds_read_b64_tr_b16 v[180:181], v199 offset:56832
	v_fmamk_f32 v120, v188, 0x41200000, v186
	v_fmamk_f32 v104, v188, 0x42280000, v186
	v_exp_f32_e32 v73, v73
	v_add_f32_e32 v187, v187, v70
	v_cvt_pk_bf16_f32 v176, v70, v71
	s_waitcnt lgkmcnt(2)
	v_mfma_f32_32x32x16_bf16 v[18:33], v[150:153], v[182:185], v[18:33]
	ds_read_b64_tr_b16 v[200:201], v199 offset:57344
	ds_read_b64_tr_b16 v[202:203], v199 offset:57856
	v_fmamk_f32 v121, v188, 0x41300000, v186
	v_fmamk_f32 v105, v188, 0x422c0000, v186
	v_add_f32_e32 v182, v187, v71
	v_exp_f32_e32 v74, v74
	v_exp_f32_e32 v75, v75
	s_waitcnt lgkmcnt(2)
	v_mfma_f32_32x32x16_bf16 v[18:33], v[146:149], v[178:181], v[18:33]
	ds_read_b64_tr_b16 v[204:205], v199 offset:58368
	ds_read_b64_tr_b16 v[206:207], v199 offset:58880
	v_add_f32_e32 v178, v182, v72
	v_fmamk_f32 v106, v188, 0x42400000, v186
	v_fma_f32 v122, v188, s48, v186
	v_fma_f32 v123, v188, s49, v186
	v_cvt_pk_bf16_f32 v177, v72, v73
	v_add_f32_e32 v187, v73, v178
	s_waitcnt lgkmcnt(2)
	v_mfma_f32_32x32x16_bf16 v[34:49], v[158:161], v[200:203], v[34:49]
	ds_read_b64_tr_b16 v[182:183], v199 offset:59392
	ds_read_b64_tr_b16 v[184:185], v199 offset:59904
	v_fmamk_f32 v107, v188, 0x42440000, v186
	v_fmamk_f32 v124, v188, 0x41900000, v186
	v_exp_f32_e32 v76, v76
	v_exp_f32_e32 v77, v77
	s_waitcnt lgkmcnt(2)
	v_mfma_f32_32x32x16_bf16 v[34:49], v[154:157], v[204:207], v[34:49]
	ds_read_b64_tr_b16 v[178:179], v199 offset:60416
	ds_read_b64_tr_b16 v[180:181], v199 offset:60928
	v_add_f32_e32 v187, v187, v74
	v_fmamk_f32 v108, v188, 0x42480000, v186
	v_fmamk_f32 v125, v188, 0x41980000, v186
	v_cvt_pk_bf16_f32 v170, v74, v75
	v_add_f32_e32 v200, v75, v187
	v_exp_f32_e32 v78, v78
	s_add_u32 s6, s76, s62
	s_addc_u32 s7, s77, s63
	s_add_u32 s26, s6, 0x30000
	s_addc_u32 s27, s7, 0
	s_add_u32 s6, s78, s62
	s_addc_u32 s7, s79, s63
	s_add_u32 s70, s6, 0x30000
	s_addc_u32 s71, s7, 0
	s_add_i32 s6, 0x4000, s59
	s_add_i32 s7, s81, s90
	s_add_u32 s84, s26, 0x8000
	s_addc_u32 s85, s27, 0
	s_add_i32 s15, s6, 0x2000
	s_mov_b32 m0, s6
	s_nop 0
	global_load_lds_dwordx4 v191, s[26:27]
	s_mov_b32 m0, s15
	s_nop 0
	global_load_lds_dwordx4 v191, s[84:85]
	s_mov_b32 m0, s21
	s_add_u32 s26, s70, 0x80
	s_addc_u32 s27, s71, 0
	s_add_i32 s6, s7, 0x2000
	s_mov_b32 m0, s7
	s_nop 0
	global_load_lds_dwordx4 v192, s[70:71]
	s_mov_b32 m0, s6
	s_nop 0
	global_load_lds_dwordx4 v192, s[26:27]
	s_mov_b32 m0, s15
	s_waitcnt lgkmcnt(2)
	v_mfma_f32_32x32x16_bf16 v[34:49], v[150:153], v[182:185], v[34:49]
	ds_read_b64_tr_b16 v[202:203], v199 offset:61440
	ds_read_b64_tr_b16 v[204:205], v199 offset:61952
	v_mov_b32_e32 v189, v188
	v_mov_b32_e32 v187, v186
	v_fma_f32 v182, v188, s56, v186
	v_fma_f32 v183, v189, s57, v187
	v_fmamk_f32 v126, v188, 0x41c00000, v186
	v_exp_f32_e32 v79, v79
	v_add_f32_e32 v187, v200, v76
	v_mov_b32_e32 v109, v182
	v_mov_b32_e32 v110, v183
	s_waitcnt lgkmcnt(2)
	v_mfma_f32_32x32x16_bf16 v[34:49], v[146:149], v[178:181], v[34:49]
	ds_read_b64_tr_b16 v[182:183], v199 offset:62464
	ds_read_b64_tr_b16 v[184:185], v199 offset:62976
	v_fmamk_f32 v127, v188, 0x41c80000, v186
	v_fmamk_f32 v111, v188, 0x42640000, v186
	v_cvt_pk_bf16_f32 v171, v76, v77
	v_add_f32_e32 v187, v187, v77
	v_exp_f32_e32 v80, v80
	s_waitcnt lgkmcnt(2)
	v_mfma_f32_32x32x16_bf16 v[50:65], v[158:161], v[202:205], v[50:65]
	ds_read_b64_tr_b16 v[178:179], v199 offset:63488
	ds_read_b64_tr_b16 v[180:181], v199 offset:64000
	v_fmamk_f32 v128, v188, 0x41d00000, v186
	v_fmamk_f32 v112, v188, 0x42680000, v186
	v_exp_f32_e32 v81, v81
	v_add_f32_e32 v187, v187, v78
	v_cvt_pk_bf16_f32 v172, v78, v79
	s_waitcnt lgkmcnt(2)
	v_mfma_f32_32x32x16_bf16 v[50:65], v[154:157], v[182:185], v[50:65]
	ds_read_b64_tr_b16 v[200:201], v199 offset:64512
	ds_read_b64_tr_b16 v[202:203], v199 offset:65024
	v_fmamk_f32 v129, v188, 0x41d80000, v186
	v_fmac_f32_e32 v186, 0x426c0000, v188
	v_exp_f32_e32 v82, v82
	v_exp_f32_e32 v83, v83
	v_mov_b32_e32 v113, v186
	v_add_f32_e32 v186, v187, v79
	s_waitcnt lgkmcnt(2)
	v_mfma_f32_32x32x16_bf16 v[50:65], v[150:153], v[178:181], v[50:65]
	ds_read_b128 v[182:185], v190 offset:32768
	v_add_f32_e32 v178, v186, v80
	v_cvt_pk_bf16_f32 v173, v80, v81
	v_add_f32_e32 v186, v81, v178
	v_exp_f32_e32 v84, v84
	v_exp_f32_e32 v85, v85
	s_waitcnt lgkmcnt(1)
	v_mfma_f32_32x32x16_bf16 v[50:65], v[146:149], v[200:203], v[50:65]
	ds_read_b128 v[178:181], v190 offset:40960
	v_add_f32_e32 v186, v186, v82
	v_cvt_pk_bf16_f32 v166, v82, v83
	v_add_f32_e32 v199, v83, v186
	v_exp_f32_e32 v86, v86
	v_exp_f32_e32 v87, v87
	s_waitcnt lgkmcnt(1)
	v_mfma_f32_32x32x16_bf16 v[114:129], v[182:185], v[130:133], v[114:129]
	ds_read_b128 v[186:189], v194 offset:32768
	v_add_f32_e32 v182, v199, v84
	v_cvt_pk_bf16_f32 v167, v84, v85
	v_add_f32_e32 v199, v85, v182
	v_exp_f32_e32 v88, v88
	v_exp_f32_e32 v89, v89
	s_waitcnt lgkmcnt(1)
	v_mfma_f32_32x32x16_bf16 v[98:113], v[178:181], v[130:133], v[98:113]
	ds_read_b128 v[182:185], v194 offset:40960
	v_add_f32_e32 v178, v199, v86
	v_cvt_pk_bf16_f32 v168, v86, v87
	v_add_f32_e32 v199, v87, v178
	v_exp_f32_e32 v90, v90
	v_exp_f32_e32 v91, v91
	s_waitcnt lgkmcnt(1)
	v_mfma_f32_32x32x16_bf16 v[114:129], v[186:189], v[134:137], v[114:129]
	ds_read_b128 v[178:181], v195 offset:32768
	v_add_f32_e32 v186, v199, v88
	v_cvt_pk_bf16_f32 v169, v88, v89
	v_add_f32_e32 v199, v89, v186
	v_exp_f32_e32 v92, v92
	v_exp_f32_e32 v93, v93
	s_waitcnt lgkmcnt(1)
	v_mfma_f32_32x32x16_bf16 v[98:113], v[182:185], v[134:137], v[98:113]
	ds_read_b128 v[186:189], v195 offset:40960
	v_add_f32_e32 v182, v199, v90
	v_cvt_pk_bf16_f32 v162, v90, v91
	v_add_f32_e32 v182, v91, v182
	v_exp_f32_e32 v94, v94
	v_exp_f32_e32 v95, v95
	s_waitcnt lgkmcnt(1)
	v_mfma_f32_32x32x16_bf16 v[114:129], v[178:181], v[138:141], v[114:129]
	ds_read_b128 v[200:203], v196 offset:32768
	v_add_f32_e32 v178, v182, v92
	v_cvt_pk_bf16_f32 v163, v92, v93
	v_add_f32_e32 v178, v93, v178
	v_exp_f32_e32 v96, v96
	v_exp_f32_e32 v97, v97
	s_waitcnt lgkmcnt(1)
	v_mfma_f32_32x32x16_bf16 v[98:113], v[186:189], v[138:141], v[98:113]
	ds_read_b128 v[204:207], v196 offset:40960
	v_add_f32_e32 v165, v178, v94
	v_add_f32_e32 v165, v95, v165
	v_add_f32_e32 v178, v96, v165
	v_cvt_pk_bf16_f32 v164, v94, v95
	v_cvt_pk_bf16_f32 v165, v96, v97
	v_add_f32_e32 v187, v97, v178
	s_waitcnt lgkmcnt(1)
	v_mfma_f32_32x32x16_bf16 v[114:129], v[200:203], v[142:145], v[114:129]
	v_add_u32_e32 v199, s80, v240
	ds_read_b64_tr_b16 v[182:183], v199 offset:49152
	ds_read_b64_tr_b16 v[184:185], v199 offset:49664
	s_waitcnt lgkmcnt(2)
	v_mfma_f32_32x32x16_bf16 v[98:113], v[204:207], v[142:145], v[98:113]
	ds_read_b64_tr_b16 v[178:179], v199 offset:50176
	ds_read_b64_tr_b16 v[180:181], v199 offset:50688
	s_waitcnt vmcnt(4) lgkmcnt(0)
	s_barrier
	s_add_i32 s6, s81, 0x4000
	s_cmp_lg_u32 s81, 0x10000
	s_cselect_b32 s21, s6, 0
	s_add_i32 s20, s20, 1
	s_cmp_lt_i32 s20, s89
	v_mfma_f32_32x32x16_bf16 v[2:17], v[174:177], v[182:185], v[2:17]
	s_cselect_b64 s[6:7], -1, 0
	v_cvt_f32_i32_e32 v66, v197
	v_cndmask_b32_e64 v188, -v193, v193, s[6:7]
	ds_read_b64_tr_b16 v[200:201], v199 offset:51200
	ds_read_b64_tr_b16 v[202:203], v199 offset:51712
	v_fma_f32 v186, v188, v66, -v233
	v_exp_f32_e32 v114, v114
	v_exp_f32_e32 v115, v115
	v_fma_f32 v66, 0, v188, v186
	v_fmamk_f32 v82, v188, 0x42000000, v186
	v_add_f32_e32 v67, v188, v186
	v_mfma_f32_32x32x16_bf16 v[2:17], v[170:173], v[178:181], v[2:17]
	ds_read_b64_tr_b16 v[182:183], v199 offset:52224
	ds_read_b64_tr_b16 v[184:185], v199 offset:52736
	v_fmamk_f32 v83, v188, 0x42040000, v186
	v_fma_f32 v68, 2.0, v188, v186
	v_exp_f32_e32 v116, v116
	v_exp_f32_e32 v117, v117
	s_waitcnt lgkmcnt(2)
	v_mfma_f32_32x32x16_bf16 v[2:17], v[166:169], v[200:203], v[2:17]
	ds_read_b64_tr_b16 v[178:179], v199 offset:53248
	ds_read_b64_tr_b16 v[180:181], v199 offset:53760
	v_add_f32_e32 v187, v187, v114
	v_fmamk_f32 v84, v188, 0x42080000, v186
	v_fmamk_f32 v69, v188, 0x40400000, v186
	v_cvt_pk_bf16_f32 v158, v114, v115
	v_add_f32_e32 v187, v115, v187
	v_exp_f32_e32 v118, v118
	s_waitcnt lgkmcnt(2)
	v_mfma_f32_32x32x16_bf16 v[2:17], v[162:165], v[182:185], v[2:17]
	ds_read_b64_tr_b16 v[200:201], v199 offset:54272
	ds_read_b64_tr_b16 v[202:203], v199 offset:54784
	v_fma_f32 v182, v188, s16, v186
	v_fma_f32 v183, v188, s17, v186
	v_fmamk_f32 v70, v188, 0x41000000, v186
	v_exp_f32_e32 v119, v119
	v_add_f32_e32 v187, v187, v116
	v_mov_b32_e32 v85, v182
	v_mov_b32_e32 v86, v183
	s_waitcnt lgkmcnt(2)
	v_mfma_f32_32x32x16_bf16 v[18:33], v[174:177], v[178:181], v[18:33]
	ds_read_b64_tr_b16 v[182:183], v199 offset:55296
	ds_read_b64_tr_b16 v[184:185], v199 offset:55808
	v_fmamk_f32 v71, v188, 0x41100000, v186
	v_fmamk_f32 v87, v188, 0x42240000, v186
	v_cvt_pk_bf16_f32 v159, v116, v117
	v_add_f32_e32 v187, v187, v117
	v_exp_f32_e32 v120, v120
	s_waitcnt lgkmcnt(2)
	v_mfma_f32_32x32x16_bf16 v[18:33], v[170:173], v[200:203], v[18:33]
	ds_read_b64_tr_b16 v[178:179], v199 offset:56320
	ds_read_b64_tr_b16 v[180:181], v199 offset:56832
	v_fmamk_f32 v72, v188, 0x41200000, v186
	v_fmamk_f32 v88, v188, 0x42280000, v186
	v_exp_f32_e32 v121, v121
	v_add_f32_e32 v187, v187, v118
	v_cvt_pk_bf16_f32 v160, v118, v119
	s_waitcnt lgkmcnt(2)
	v_mfma_f32_32x32x16_bf16 v[18:33], v[166:169], v[182:185], v[18:33]
	ds_read_b64_tr_b16 v[200:201], v199 offset:57344
	ds_read_b64_tr_b16 v[202:203], v199 offset:57856
	v_fmamk_f32 v73, v188, 0x41300000, v186
	v_fmamk_f32 v89, v188, 0x422c0000, v186
	v_add_f32_e32 v182, v187, v119
	v_exp_f32_e32 v122, v122
	v_exp_f32_e32 v123, v123
	s_waitcnt lgkmcnt(2)
	v_mfma_f32_32x32x16_bf16 v[18:33], v[162:165], v[178:181], v[18:33]
	ds_read_b64_tr_b16 v[204:205], v199 offset:58368
	ds_read_b64_tr_b16 v[206:207], v199 offset:58880
	v_add_f32_e32 v178, v182, v120
	v_fmamk_f32 v90, v188, 0x42400000, v186
	v_fma_f32 v74, v188, s48, v186
	v_fma_f32 v75, v188, s49, v186
	v_cvt_pk_bf16_f32 v161, v120, v121
	v_add_f32_e32 v187, v121, v178
	s_waitcnt lgkmcnt(2)
	v_mfma_f32_32x32x16_bf16 v[34:49], v[174:177], v[200:203], v[34:49]
	ds_read_b64_tr_b16 v[182:183], v199 offset:59392
	ds_read_b64_tr_b16 v[184:185], v199 offset:59904
	v_fmamk_f32 v91, v188, 0x42440000, v186
	v_fmamk_f32 v76, v188, 0x41900000, v186
	v_exp_f32_e32 v124, v124
	v_exp_f32_e32 v125, v125
	s_waitcnt lgkmcnt(2)
	v_mfma_f32_32x32x16_bf16 v[34:49], v[170:173], v[204:207], v[34:49]
	ds_read_b64_tr_b16 v[178:179], v199 offset:60416
	ds_read_b64_tr_b16 v[180:181], v199 offset:60928
	v_add_f32_e32 v187, v187, v122
	v_fmamk_f32 v92, v188, 0x42480000, v186
	v_fmamk_f32 v77, v188, 0x41980000, v186
	v_cvt_pk_bf16_f32 v154, v122, v123
	v_add_f32_e32 v198, v123, v187
	v_exp_f32_e32 v126, v126
	s_add_u32 s6, s76, s62
	s_addc_u32 s7, s77, s63
	s_add_u32 s6, s6, 0x40000
	s_addc_u32 s7, s7, 0
	s_add_u32 s15, s78, s62
	s_addc_u32 s20, s79, s63
	s_add_u32 s24, s15, 0x40000
	s_addc_u32 s25, s20, 0
	s_add_i32 s15, 0x8000, s59
	s_add_i32 s20, s21, s90
	s_add_u32 s26, s6, 0x8000
	s_addc_u32 s27, s7, 0
	s_add_i32 s68, s15, 0x2000
	s_mov_b32 m0, s15
	s_nop 0
	global_load_lds_dwordx4 v191, s[6:7]
	s_mov_b32 m0, s68
	s_nop 0
	global_load_lds_dwordx4 v191, s[26:27]
	s_mov_b32 m0, s69
	s_add_u32 s6, s24, 0x80
	s_addc_u32 s7, s25, 0
	s_add_i32 s15, s20, 0x2000
	s_mov_b32 m0, s20
	s_nop 0
	global_load_lds_dwordx4 v192, s[24:25]
	s_mov_b32 m0, s15
	s_nop 0
	global_load_lds_dwordx4 v192, s[6:7]
	s_mov_b32 m0, s26
	s_waitcnt lgkmcnt(2)
	v_mfma_f32_32x32x16_bf16 v[34:49], v[166:169], v[182:185], v[34:49]
	ds_read_b64_tr_b16 v[200:201], v199 offset:61440
	ds_read_b64_tr_b16 v[202:203], v199 offset:61952
	v_mov_b32_e32 v189, v188
	v_mov_b32_e32 v187, v186
	s_add_i32 s6, s80, 0x4000
	s_cmp_lg_u32 s80, 0x10000
	v_pk_fma_f32 v[182:183], v[188:189], s[56:57], v[186:187]
	s_cselect_b32 s15, s6, 0
	v_fmamk_f32 v78, v188, 0x41c00000, v186
	v_exp_f32_e32 v127, v127
	v_add_f32_e32 v187, v198, v124
	v_mov_b32_e32 v93, v182
	v_mov_b32_e32 v94, v183
	s_waitcnt lgkmcnt(2)
	v_mfma_f32_32x32x16_bf16 v[34:49], v[162:165], v[178:181], v[34:49]
	ds_read_b64_tr_b16 v[182:183], v199 offset:62464
	ds_read_b64_tr_b16 v[184:185], v199 offset:62976
	v_fmamk_f32 v79, v188, 0x41c80000, v186
	v_fmamk_f32 v95, v188, 0x42640000, v186
	v_cvt_pk_bf16_f32 v155, v124, v125
	v_add_f32_e32 v187, v187, v125
	v_exp_f32_e32 v128, v128
	s_waitcnt lgkmcnt(2)
	v_mfma_f32_32x32x16_bf16 v[50:65], v[174:177], v[200:203], v[50:65]
	ds_read_b64_tr_b16 v[178:179], v199 offset:63488
	ds_read_b64_tr_b16 v[180:181], v199 offset:64000
	v_fmamk_f32 v80, v188, 0x41d00000, v186
	v_fmamk_f32 v96, v188, 0x42680000, v186
	v_exp_f32_e32 v129, v129
	v_add_f32_e32 v187, v187, v126
	v_cvt_pk_bf16_f32 v156, v126, v127
	s_waitcnt lgkmcnt(2)
	v_mfma_f32_32x32x16_bf16 v[50:65], v[170:173], v[182:185], v[50:65]
	ds_read_b64_tr_b16 v[200:201], v199 offset:64512
	ds_read_b64_tr_b16 v[202:203], v199 offset:65024
	v_fmamk_f32 v81, v188, 0x41d80000, v186
	v_fmac_f32_e32 v186, 0x426c0000, v188
	v_exp_f32_e32 v98, v98
	v_exp_f32_e32 v99, v99
	v_mov_b32_e32 v97, v186
	v_add_f32_e32 v186, v187, v127
	s_waitcnt lgkmcnt(2)
	v_mfma_f32_32x32x16_bf16 v[50:65], v[166:169], v[178:181], v[50:65]
	ds_read_b128 v[182:185], v190
	v_add_f32_e32 v178, v186, v128
	v_cvt_pk_bf16_f32 v157, v128, v129
	v_add_f32_e32 v186, v129, v178
	v_exp_f32_e32 v100, v100
	v_exp_f32_e32 v101, v101
	s_waitcnt lgkmcnt(1)
	v_mfma_f32_32x32x16_bf16 v[50:65], v[162:165], v[200:203], v[50:65]
	ds_read_b128 v[178:181], v190 offset:8192
	v_add_f32_e32 v186, v186, v98
	v_cvt_pk_bf16_f32 v150, v98, v99
	v_add_f32_e32 v198, v99, v186
	v_exp_f32_e32 v102, v102
	v_exp_f32_e32 v103, v103
	s_waitcnt lgkmcnt(1)
	v_mfma_f32_32x32x16_bf16 v[66:81], v[182:185], v[130:133], v[66:81]
	ds_read_b128 v[186:189], v194
	v_add_f32_e32 v182, v198, v100
	v_cvt_pk_bf16_f32 v151, v100, v101
	v_add_f32_e32 v198, v101, v182
	v_exp_f32_e32 v104, v104
	v_exp_f32_e32 v105, v105
	s_waitcnt lgkmcnt(1)
	v_mfma_f32_32x32x16_bf16 v[82:97], v[178:181], v[130:133], v[82:97]
	ds_read_b128 v[182:185], v194 offset:8192
	v_add_f32_e32 v178, v198, v102
	v_cvt_pk_bf16_f32 v152, v102, v103
	v_add_f32_e32 v198, v103, v178
	v_exp_f32_e32 v106, v106
	v_exp_f32_e32 v107, v107
	s_waitcnt lgkmcnt(1)
	v_mfma_f32_32x32x16_bf16 v[66:81], v[186:189], v[134:137], v[66:81]
	ds_read_b128 v[178:181], v195
	v_add_f32_e32 v186, v198, v104
	v_cvt_pk_bf16_f32 v153, v104, v105
	v_add_f32_e32 v198, v105, v186
	v_exp_f32_e32 v108, v108
	v_exp_f32_e32 v109, v109
	s_waitcnt lgkmcnt(1)
	v_mfma_f32_32x32x16_bf16 v[82:97], v[182:185], v[134:137], v[82:97]
	ds_read_b128 v[186:189], v195 offset:8192
	v_add_f32_e32 v182, v198, v106
	v_cvt_pk_bf16_f32 v146, v106, v107
	v_add_f32_e32 v182, v107, v182
	v_exp_f32_e32 v110, v110
	v_exp_f32_e32 v111, v111
	s_waitcnt lgkmcnt(1)
	v_mfma_f32_32x32x16_bf16 v[66:81], v[178:181], v[138:141], v[66:81]
	ds_read_b128 v[198:201], v196
	v_add_f32_e32 v178, v182, v108
	v_cvt_pk_bf16_f32 v147, v108, v109
	v_add_f32_e32 v178, v109, v178
	v_exp_f32_e32 v112, v112
	v_exp_f32_e32 v113, v113
	s_waitcnt lgkmcnt(1)
	v_mfma_f32_32x32x16_bf16 v[82:97], v[186:189], v[138:141], v[82:97]
	ds_read_b128 v[202:205], v196 offset:8192
	v_add_f32_e32 v149, v178, v110
	v_add_f32_e32 v149, v111, v149
	v_add_f32_e32 v178, v112, v149
	v_cvt_pk_bf16_f32 v148, v110, v111
	v_cvt_pk_bf16_f32 v149, v112, v113
	v_add_f32_e32 v187, v113, v178
	s_waitcnt lgkmcnt(1)
	v_mfma_f32_32x32x16_bf16 v[66:81], v[198:201], v[142:145], v[66:81]
	v_add_u32_e32 v180, s15, v240
	ds_read_b64_tr_b16 v[182:183], v180 offset:49152
	ds_read_b64_tr_b16 v[184:185], v180 offset:49664
	s_waitcnt lgkmcnt(2)
	v_mfma_f32_32x32x16_bf16 v[82:97], v[202:205], v[142:145], v[82:97]
	ds_read_b64_tr_b16 v[178:179], v180 offset:50176
	ds_read_b64_tr_b16 v[180:181], v180 offset:50688
	s_add_i32 s6, s15, 0x4000
	s_cmp_lg_u32 s15, 0x10000
	s_cselect_b32 s80, s6, 0
	s_add_i32 s6, s21, 0x4000
	s_cmp_lg_u32 s21, 0x10000
	s_cselect_b32 s81, s6, 0
	s_add_u32 s78, s78, 0x20000
	s_addc_u32 s79, s79, 0
	s_add_u32 s76, s76, 0x20000
	s_addc_u32 s77, s77, 0
	v_add_u32_e32 v197, 0x80, v197
	s_mov_b32 s43, s0
	s_branch .LBB0_1377
.Lmla_fast_w03:
	s_waitcnt vmcnt(6) lgkmcnt(0)
	s_barrier
	v_mfma_f32_32x32x16_bf16 v[2:17], v[134:137], v[166:169], v[2:17]
	ds_read_b64_tr_b16 v[66:67], v189 offset:28672
	ds_read_b64_tr_b16 v[68:69], v189 offset:29184
	v_exp_f32_e32 v34, v34
	v_exp_f32_e32 v35, v35
	v_exp_f32_e32 v36, v36
	v_mfma_f32_32x32x16_bf16 v[2:17], v[130:133], v[162:165], v[2:17]
	ds_read_b64_tr_b16 v[70:71], v189 offset:29696
	ds_read_b64_tr_b16 v[72:73], v189 offset:30208
	v_add_f32_e32 v74, v193, v34
	v_exp_f32_e32 v37, v37
	v_cvt_pk_bf16_f32 v150, v34, v35
	v_add_f32_e32 v78, v35, v74
	v_mfma_f32_32x32x16_bf16 v[2:17], v[126:129], v[158:161], v[2:17]
	ds_read_b64_tr_b16 v[74:75], v189 offset:30720
	ds_read_b64_tr_b16 v[76:77], v189 offset:31232
	v_exp_f32_e32 v38, v38
	v_exp_f32_e32 v39, v39
	v_add_f32_e32 v82, v78, v36
	v_cvt_pk_bf16_f32 v151, v36, v37
	v_mfma_f32_32x32x16_bf16 v[2:17], v[122:125], v[154:157], v[2:17]
	ds_read_b64_tr_b16 v[78:79], v189 offset:31744
	ds_read_b64_tr_b16 v[80:81], v189 offset:32256
	v_add_f32_e32 v82, v82, v37
	v_exp_f32_e32 v40, v40
	v_exp_f32_e32 v41, v41
	v_add_f32_e32 v86, v38, v82
	s_waitcnt lgkmcnt(6)
	v_mfma_f32_32x32x16_bf16 v[18:33], v[134:137], v[66:69], v[18:33]
	ds_read_b128 v[82:85], v182 offset:36864
	v_cvt_pk_bf16_f32 v152, v38, v39
	v_add_f32_e32 v90, v86, v39
	v_exp_f32_e32 v42, v42
	v_exp_f32_e32 v43, v43
	s_waitcnt lgkmcnt(5)
	v_mfma_f32_32x32x16_bf16 v[18:33], v[130:133], v[70:73], v[18:33]
	ds_read_b128 v[86:89], v182 offset:40960
	v_add_f32_e32 v66, v90, v40
	v_exp_f32_e32 v44, v44
	v_cvt_pk_bf16_f32 v153, v40, v41
	v_add_f32_e32 v66, v41, v66
	s_waitcnt lgkmcnt(4)
	v_mfma_f32_32x32x16_bf16 v[18:33], v[126:129], v[74:77], v[18:33]
	ds_read_b128 v[154:157], v183 offset:36864
	v_add_f32_e32 v66, v66, v42
	v_exp_f32_e32 v45, v45
	v_cvt_pk_bf16_f32 v146, v42, v43
	v_add_f32_e32 v66, v43, v66
	s_waitcnt lgkmcnt(3)
	v_mfma_f32_32x32x16_bf16 v[18:33], v[122:125], v[78:81], v[18:33]
	ds_read_b128 v[162:165], v183 offset:40960
	v_exp_f32_e32 v46, v46
	v_exp_f32_e32 v47, v47
	v_add_f32_e32 v66, v66, v44
	v_cvt_pk_bf16_f32 v147, v44, v45
	s_nop 0
	v_add_f32_e32 v66, v66, v45
	v_add_f32_e32 v91, v46, v66
	s_waitcnt lgkmcnt(3)
	v_mfma_f32_32x32x16_bf16 v[66:81], v[82:85], v[98:101], 0
	ds_read_b128 v[166:169], v184 offset:36864
	v_exp_f32_e32 v48, v48
	v_exp_f32_e32 v49, v49
	ds_read_b128 v[158:161], v184 offset:40960
	v_add_f32_e32 v193, v91, v47
	s_waitcnt lgkmcnt(4)
	v_mfma_f32_32x32x16_bf16 v[82:97], v[86:89], v[98:101], 0
	v_exp_f32_e32 v50, v50
	v_exp_f32_e32 v51, v51
	v_cvt_pk_bf16_f32 v148, v46, v47
	s_add_u32 s26, s20, 0xfffe0000
	s_addc_u32 s27, s21, -1
	s_add_i32 s31, 0x6000, s8
	s_add_i32 s33, 0, s12
	s_add_u32 s28, s22, 0xfffff000
	s_addc_u32 s29, s23, -1
	s_add_i32 s40, s31, 0x2000
	s_mov_b32 m0, s31
	s_nop 0
	global_load_lds_dwordx4 v174, s[26:27]
	s_mov_b32 m0, s40
	s_nop 0
	global_load_lds_dwordx4 v192, s[28:29]
	s_mov_b32 m0, s33
	s_nop 0
	global_load_lds_dwordx4 v191, s[26:27]
	s_mov_b32 m0, s41
	s_waitcnt lgkmcnt(3)
	v_mfma_f32_32x32x16_bf16 v[66:81], v[154:157], v[102:105], v[66:81]
	ds_read_b128 v[194:197], v185 offset:36864
	v_add_f32_e32 v193, v193, v48
	v_cvt_pk_bf16_f32 v149, v48, v49
	v_add_f32_e32 v193, v49, v193
	v_exp_f32_e32 v52, v52
	s_waitcnt lgkmcnt(3)
	v_mfma_f32_32x32x16_bf16 v[82:97], v[162:165], v[102:105], v[82:97]
	ds_read_b128 v[154:157], v185 offset:40960
	v_add_f32_e32 v193, v193, v50
	v_exp_f32_e32 v53, v53
	v_cvt_pk_bf16_f32 v142, v50, v51
	v_add_f32_e32 v193, v51, v193
	s_waitcnt lgkmcnt(3)
	v_mfma_f32_32x32x16_bf16 v[66:81], v[166:169], v[106:109], v[66:81]
	ds_read_b128 v[162:165], v187 offset:45056
	v_exp_f32_e32 v54, v54
	v_exp_f32_e32 v55, v55
	v_add_f32_e32 v193, v193, v52
	v_cvt_pk_bf16_f32 v143, v52, v53
	s_waitcnt lgkmcnt(3)
	v_mfma_f32_32x32x16_bf16 v[82:97], v[158:161], v[106:109], v[82:97]
	ds_read_b128 v[198:201], v187 offset:47104
	v_add_f32_e32 v166, v193, v53
	v_exp_f32_e32 v56, v56
	v_exp_f32_e32 v57, v57
	v_add_f32_e32 v166, v54, v166
	s_waitcnt lgkmcnt(3)
	v_mfma_f32_32x32x16_bf16 v[66:81], v[194:197], v[110:113], v[66:81]
	ds_read_b128 v[202:205], v188 offset:45056
	v_cvt_pk_bf16_f32 v144, v54, v55
	v_add_f32_e32 v159, v166, v55
	v_exp_f32_e32 v58, v58
	v_exp_f32_e32 v59, v59
	s_waitcnt lgkmcnt(3)
	v_mfma_f32_32x32x16_bf16 v[82:97], v[154:157], v[110:113], v[82:97]
	ds_read_b128 v[194:197], v188 offset:47104
	v_add_f32_e32 v158, v159, v56
	v_exp_f32_e32 v60, v60
	v_cvt_pk_bf16_f32 v145, v56, v57
	v_add_f32_e32 v158, v57, v158
	s_waitcnt lgkmcnt(3)
	v_mfma_f32_32x32x16_bf16 v[66:81], v[162:165], v[114:117], v[66:81]
	ds_read_b64_tr_b16 v[166:167], v189 offset:32768
	ds_read_b64_tr_b16 v[168:169], v189 offset:33280
	v_add_f32_e32 v154, v158, v58
	v_exp_f32_e32 v61, v61
	v_cvt_pk_bf16_f32 v138, v58, v59
	v_add_f32_e32 v154, v59, v154
	s_waitcnt lgkmcnt(4)
	v_mfma_f32_32x32x16_bf16 v[82:97], v[198:201], v[114:117], v[82:97]
	ds_read_b64_tr_b16 v[162:163], v189 offset:33792
	ds_read_b64_tr_b16 v[164:165], v189 offset:34304
	v_exp_f32_e32 v62, v62
	v_exp_f32_e32 v63, v63
	v_add_f32_e32 v154, v154, v60
	v_cvt_pk_bf16_f32 v139, v60, v61
	s_waitcnt lgkmcnt(5)
	v_mfma_f32_32x32x16_bf16 v[66:81], v[202:205], v[118:121], v[66:81]
	ds_read_b64_tr_b16 v[158:159], v189 offset:34816
	ds_read_b64_tr_b16 v[160:161], v189 offset:35328
	v_add_f32_e32 v154, v154, v61
	v_exp_f32_e32 v64, v64
	v_exp_f32_e32 v65, v65
	v_add_f32_e32 v198, v62, v154
	s_waitcnt lgkmcnt(6)
	v_mfma_f32_32x32x16_bf16 v[82:97], v[194:197], v[118:121], v[82:97]
	ds_read_b64_tr_b16 v[154:155], v189 offset:35840
	ds_read_b64_tr_b16 v[156:157], v189 offset:36352
	v_add_f32_e32 v141, v198, v63
	v_add_f32_e32 v198, v64, v141
	v_cvt_pk_bf16_f32 v140, v62, v63
	v_cvt_pk_bf16_f32 v141, v64, v65
	v_add_f32_e32 v194, v65, v198
	s_waitcnt vmcnt(6) lgkmcnt(0)
	s_barrier
	v_mfma_f32_32x32x16_bf16 v[2:17], v[150:153], v[166:169], v[2:17]
	ds_read_b64_tr_b16 v[34:35], v189 offset:36864
	ds_read_b64_tr_b16 v[36:37], v189 offset:37376
	v_exp_f32_e32 v66, v66
	v_exp_f32_e32 v67, v67
	v_exp_f32_e32 v68, v68
	v_mfma_f32_32x32x16_bf16 v[2:17], v[146:149], v[162:165], v[2:17]
	ds_read_b64_tr_b16 v[38:39], v189 offset:37888
	ds_read_b64_tr_b16 v[40:41], v189 offset:38400
	v_add_f32_e32 v42, v194, v66
	v_exp_f32_e32 v69, v69
	v_cvt_pk_bf16_f32 v134, v66, v67
	v_add_f32_e32 v46, v67, v42
	v_mfma_f32_32x32x16_bf16 v[2:17], v[142:145], v[158:161], v[2:17]
	ds_read_b64_tr_b16 v[42:43], v189 offset:38912
	ds_read_b64_tr_b16 v[44:45], v189 offset:39424
	v_exp_f32_e32 v70, v70
	v_exp_f32_e32 v71, v71
	v_add_f32_e32 v50, v46, v68
	v_cvt_pk_bf16_f32 v135, v68, v69
	v_mfma_f32_32x32x16_bf16 v[2:17], v[138:141], v[154:157], v[2:17]
	ds_read_b64_tr_b16 v[46:47], v189 offset:39936
	ds_read_b64_tr_b16 v[48:49], v189 offset:40448
	v_add_f32_e32 v50, v50, v69
	v_exp_f32_e32 v72, v72
	v_exp_f32_e32 v73, v73
	v_add_f32_e32 v54, v70, v50
	s_waitcnt lgkmcnt(6)
	v_mfma_f32_32x32x16_bf16 v[18:33], v[150:153], v[34:37], v[18:33]
	ds_read_b128 v[50:53], v182
	v_cvt_pk_bf16_f32 v136, v70, v71
	v_add_f32_e32 v58, v54, v71
	v_exp_f32_e32 v74, v74
	v_exp_f32_e32 v75, v75
	s_waitcnt lgkmcnt(5)
	v_mfma_f32_32x32x16_bf16 v[18:33], v[146:149], v[38:41], v[18:33]
	ds_read_b128 v[54:57], v182 offset:4096
	v_add_f32_e32 v34, v58, v72
	v_exp_f32_e32 v76, v76
	v_cvt_pk_bf16_f32 v137, v72, v73
	v_add_f32_e32 v34, v73, v34
	s_waitcnt lgkmcnt(4)
	v_mfma_f32_32x32x16_bf16 v[18:33], v[142:145], v[42:45], v[18:33]
	ds_read_b128 v[154:157], v183
	v_add_f32_e32 v34, v34, v74
	v_exp_f32_e32 v77, v77
	v_cvt_pk_bf16_f32 v130, v74, v75
	v_add_f32_e32 v34, v75, v34
	s_waitcnt lgkmcnt(3)
	v_mfma_f32_32x32x16_bf16 v[18:33], v[138:141], v[46:49], v[18:33]
	ds_read_b128 v[162:165], v183 offset:4096
	v_exp_f32_e32 v78, v78
	v_exp_f32_e32 v79, v79
	v_add_f32_e32 v34, v34, v76
	v_cvt_pk_bf16_f32 v131, v76, v77
	s_nop 0
	v_add_f32_e32 v34, v34, v77
	v_add_f32_e32 v59, v78, v34
	s_waitcnt lgkmcnt(3)
	v_mfma_f32_32x32x16_bf16 v[34:49], v[50:53], v[98:101], 0
	ds_read_b128 v[166:169], v184
	v_exp_f32_e32 v80, v80
	v_exp_f32_e32 v81, v81
	ds_read_b128 v[158:161], v184 offset:4096
	v_add_f32_e32 v193, v59, v79
	s_waitcnt lgkmcnt(4)
	v_mfma_f32_32x32x16_bf16 v[50:65], v[54:57], v[98:101], 0
	v_exp_f32_e32 v82, v82
	v_exp_f32_e32 v83, v83
	v_cvt_pk_bf16_f32 v132, v78, v79
	s_add_i32 s26, 0x9000, s8
	s_add_i32 s28, 0x2000, s12
	s_add_i32 s24, s26, 0x2000
	s_mov_b32 m0, s26
	s_nop 0
	global_load_lds_dwordx4 v174, s[20:21]
	s_mov_b32 m0, s24
	s_nop 0
	global_load_lds_dwordx4 v192, s[22:23]
	s_mov_b32 m0, s28
	s_nop 0
	global_load_lds_dwordx4 v191, s[20:21]
	s_mov_b32 m0, s25
	s_waitcnt lgkmcnt(3)
	v_mfma_f32_32x32x16_bf16 v[34:49], v[154:157], v[102:105], v[34:49]
	ds_read_b128 v[194:197], v185
	v_add_f32_e32 v154, v193, v80
	v_exp_f32_e32 v84, v84
	v_cvt_pk_bf16_f32 v133, v80, v81
	v_add_f32_e32 v193, v81, v154
	s_waitcnt lgkmcnt(3)
	v_mfma_f32_32x32x16_bf16 v[50:65], v[162:165], v[102:105], v[50:65]
	ds_read_b128 v[154:157], v185 offset:4096
	v_add_f32_e32 v193, v193, v82
	v_exp_f32_e32 v85, v85
	v_cvt_pk_bf16_f32 v126, v82, v83
	v_add_f32_e32 v193, v83, v193
	s_waitcnt lgkmcnt(3)
	v_mfma_f32_32x32x16_bf16 v[34:49], v[166:169], v[106:109], v[34:49]
	ds_read_b128 v[162:165], v187 offset:8192
	v_exp_f32_e32 v86, v86
	v_exp_f32_e32 v87, v87
	v_add_f32_e32 v193, v193, v84
	v_cvt_pk_bf16_f32 v127, v84, v85
	s_waitcnt lgkmcnt(3)
	v_mfma_f32_32x32x16_bf16 v[50:65], v[158:161], v[106:109], v[50:65]
	ds_read_b128 v[198:201], v187 offset:10240
	v_add_f32_e32 v166, v193, v85
	v_exp_f32_e32 v88, v88
	v_exp_f32_e32 v89, v89
	v_add_f32_e32 v166, v86, v166
	s_waitcnt lgkmcnt(3)
	v_mfma_f32_32x32x16_bf16 v[34:49], v[194:197], v[110:113], v[34:49]
	ds_read_b128 v[202:205], v188 offset:8192
	v_cvt_pk_bf16_f32 v128, v86, v87
	v_add_f32_e32 v159, v166, v87
	v_exp_f32_e32 v90, v90
	v_exp_f32_e32 v91, v91
	s_waitcnt lgkmcnt(3)
	v_mfma_f32_32x32x16_bf16 v[50:65], v[154:157], v[110:113], v[50:65]
	ds_read_b128 v[194:197], v188 offset:10240
	v_add_f32_e32 v158, v159, v88
	v_exp_f32_e32 v92, v92
	v_cvt_pk_bf16_f32 v129, v88, v89
	v_add_f32_e32 v158, v89, v158
	s_waitcnt lgkmcnt(3)
	v_mfma_f32_32x32x16_bf16 v[34:49], v[162:165], v[114:117], v[34:49]
	ds_read_b64_tr_b16 v[166:167], v189 offset:40960
	ds_read_b64_tr_b16 v[168:169], v189 offset:41472
	v_add_f32_e32 v154, v158, v90
	v_exp_f32_e32 v93, v93
	v_cvt_pk_bf16_f32 v122, v90, v91
	v_add_f32_e32 v154, v91, v154
	s_waitcnt lgkmcnt(4)
	v_mfma_f32_32x32x16_bf16 v[50:65], v[198:201], v[114:117], v[50:65]
	ds_read_b64_tr_b16 v[162:163], v189 offset:41984
	ds_read_b64_tr_b16 v[164:165], v189 offset:42496
	v_exp_f32_e32 v94, v94
	v_exp_f32_e32 v95, v95
	v_add_f32_e32 v154, v154, v92
	v_cvt_pk_bf16_f32 v123, v92, v93
	s_waitcnt lgkmcnt(5)
	v_mfma_f32_32x32x16_bf16 v[34:49], v[202:205], v[118:121], v[34:49]
	ds_read_b64_tr_b16 v[158:159], v189 offset:43008
	ds_read_b64_tr_b16 v[160:161], v189 offset:43520
	v_add_f32_e32 v154, v154, v93
	v_exp_f32_e32 v96, v96
	v_exp_f32_e32 v97, v97
	v_add_f32_e32 v193, v94, v154
	s_waitcnt lgkmcnt(6)
	v_mfma_f32_32x32x16_bf16 v[50:65], v[194:197], v[118:121], v[50:65]
	ds_read_b64_tr_b16 v[154:155], v189 offset:44032
	ds_read_b64_tr_b16 v[156:157], v189 offset:44544
	v_add_f32_e32 v125, v193, v95
	v_add_f32_e32 v193, v96, v125
	v_cvt_pk_bf16_f32 v124, v94, v95
	v_cvt_pk_bf16_f32 v125, v96, v97
	v_add_f32_e32 v193, v97, v193
	s_add_u32 s22, s22, 0x2000
	s_addc_u32 s23, s23, 0
	s_add_u32 s20, s20, 0x40000
	s_addc_u32 s21, s21, 0
	s_waitcnt vmcnt(6) lgkmcnt(0)
	s_barrier
	v_mfma_f32_32x32x16_bf16 v[2:17], v[134:137], v[166:169], v[2:17]
	ds_read_b64_tr_b16 v[66:67], v189 offset:45056
	ds_read_b64_tr_b16 v[68:69], v189 offset:45568
	v_exp_f32_e32 v34, v34
	v_exp_f32_e32 v35, v35
	v_exp_f32_e32 v36, v36
	v_mfma_f32_32x32x16_bf16 v[2:17], v[130:133], v[162:165], v[2:17]
	ds_read_b64_tr_b16 v[70:71], v189 offset:46080
	ds_read_b64_tr_b16 v[72:73], v189 offset:46592
	v_add_f32_e32 v74, v193, v34
	v_exp_f32_e32 v37, v37
	v_cvt_pk_bf16_f32 v150, v34, v35
	v_add_f32_e32 v78, v35, v74
	v_mfma_f32_32x32x16_bf16 v[2:17], v[126:129], v[158:161], v[2:17]
	ds_read_b64_tr_b16 v[74:75], v189 offset:47104
	ds_read_b64_tr_b16 v[76:77], v189 offset:47616
	v_exp_f32_e32 v38, v38
	v_exp_f32_e32 v39, v39
	v_add_f32_e32 v82, v78, v36
	v_cvt_pk_bf16_f32 v151, v36, v37
	v_mfma_f32_32x32x16_bf16 v[2:17], v[122:125], v[154:157], v[2:17]
	ds_read_b64_tr_b16 v[78:79], v189 offset:48128
	ds_read_b64_tr_b16 v[80:81], v189 offset:48640
	v_add_f32_e32 v82, v82, v37
	v_exp_f32_e32 v40, v40
	v_exp_f32_e32 v41, v41
	v_add_f32_e32 v86, v38, v82
	s_waitcnt lgkmcnt(6)
	v_mfma_f32_32x32x16_bf16 v[18:33], v[134:137], v[66:69], v[18:33]
	ds_read_b128 v[82:85], v182 offset:12288
	v_cvt_pk_bf16_f32 v152, v38, v39
	v_add_f32_e32 v90, v86, v39
	v_exp_f32_e32 v42, v42
	v_exp_f32_e32 v43, v43
	s_waitcnt lgkmcnt(5)
	v_mfma_f32_32x32x16_bf16 v[18:33], v[130:133], v[70:73], v[18:33]
	ds_read_b128 v[86:89], v182 offset:16384
	v_add_f32_e32 v66, v90, v40
	v_exp_f32_e32 v44, v44
	v_cvt_pk_bf16_f32 v153, v40, v41
	v_add_f32_e32 v66, v41, v66
	s_waitcnt lgkmcnt(4)
	v_mfma_f32_32x32x16_bf16 v[18:33], v[126:129], v[74:77], v[18:33]
	ds_read_b128 v[154:157], v183 offset:12288
	v_add_f32_e32 v66, v66, v42
	v_exp_f32_e32 v45, v45
	v_cvt_pk_bf16_f32 v146, v42, v43
	v_add_f32_e32 v66, v43, v66
	s_waitcnt lgkmcnt(3)
	v_mfma_f32_32x32x16_bf16 v[18:33], v[122:125], v[78:81], v[18:33]
	ds_read_b128 v[162:165], v183 offset:16384
	v_exp_f32_e32 v46, v46
	v_exp_f32_e32 v47, v47
	v_add_f32_e32 v66, v66, v44
	v_cvt_pk_bf16_f32 v147, v44, v45
	s_nop 0
	v_add_f32_e32 v66, v66, v45
	v_add_f32_e32 v91, v46, v66
	s_waitcnt lgkmcnt(3)
	v_mfma_f32_32x32x16_bf16 v[66:81], v[82:85], v[98:101], 0
	ds_read_b128 v[166:169], v184 offset:12288
	v_exp_f32_e32 v48, v48
	v_exp_f32_e32 v49, v49
	ds_read_b128 v[158:161], v184 offset:16384
	v_add_f32_e32 v193, v91, v47
	s_waitcnt lgkmcnt(4)
	v_mfma_f32_32x32x16_bf16 v[82:97], v[86:89], v[98:101], 0
	v_exp_f32_e32 v50, v50
	v_exp_f32_e32 v51, v51
	v_cvt_pk_bf16_f32 v148, v46, v47
	s_add_u32 s26, s20, 0xfffe0000
	s_addc_u32 s27, s21, -1
	s_add_i32 s31, 0, s8
	s_add_i32 s33, 0x4000, s12
	s_add_u32 s28, s22, 0xfffff000
	s_addc_u32 s29, s23, -1
	s_add_i32 s40, s31, 0x2000
	s_mov_b32 m0, s31
	s_nop 0
	global_load_lds_dwordx4 v174, s[26:27]
	s_mov_b32 m0, s40
	s_nop 0
	global_load_lds_dwordx4 v192, s[28:29]
	s_mov_b32 m0, s33
	s_nop 0
	global_load_lds_dwordx4 v191, s[26:27]
	s_mov_b32 m0, s41
	s_waitcnt lgkmcnt(3)
	v_mfma_f32_32x32x16_bf16 v[66:81], v[154:157], v[102:105], v[66:81]
	ds_read_b128 v[194:197], v185 offset:12288
	v_add_f32_e32 v193, v193, v48
	v_cvt_pk_bf16_f32 v149, v48, v49
	v_add_f32_e32 v193, v49, v193
	v_exp_f32_e32 v52, v52
	s_waitcnt lgkmcnt(3)
	v_mfma_f32_32x32x16_bf16 v[82:97], v[162:165], v[102:105], v[82:97]
	ds_read_b128 v[154:157], v185 offset:16384
	v_add_f32_e32 v193, v193, v50
	v_exp_f32_e32 v53, v53
	v_cvt_pk_bf16_f32 v142, v50, v51
	v_add_f32_e32 v193, v51, v193
	s_waitcnt lgkmcnt(3)
	v_mfma_f32_32x32x16_bf16 v[66:81], v[166:169], v[106:109], v[66:81]
	ds_read_b128 v[162:165], v187 offset:20480
	v_exp_f32_e32 v54, v54
	v_exp_f32_e32 v55, v55
	v_add_f32_e32 v193, v193, v52
	v_cvt_pk_bf16_f32 v143, v52, v53
	s_waitcnt lgkmcnt(3)
	v_mfma_f32_32x32x16_bf16 v[82:97], v[158:161], v[106:109], v[82:97]
	ds_read_b128 v[198:201], v187 offset:22528
	v_add_f32_e32 v166, v193, v53
	v_exp_f32_e32 v56, v56
	v_exp_f32_e32 v57, v57
	v_add_f32_e32 v166, v54, v166
	s_waitcnt lgkmcnt(3)
	v_mfma_f32_32x32x16_bf16 v[66:81], v[194:197], v[110:113], v[66:81]
	ds_read_b128 v[202:205], v188 offset:20480
	v_cvt_pk_bf16_f32 v144, v54, v55
	v_add_f32_e32 v159, v166, v55
	v_exp_f32_e32 v58, v58
	v_exp_f32_e32 v59, v59
	s_waitcnt lgkmcnt(3)
	v_mfma_f32_32x32x16_bf16 v[82:97], v[154:157], v[110:113], v[82:97]
	ds_read_b128 v[194:197], v188 offset:22528
	v_add_f32_e32 v158, v159, v56
	v_exp_f32_e32 v60, v60
	v_cvt_pk_bf16_f32 v145, v56, v57
	v_add_f32_e32 v158, v57, v158
	s_waitcnt lgkmcnt(3)
	v_mfma_f32_32x32x16_bf16 v[66:81], v[162:165], v[114:117], v[66:81]
	ds_read_b64_tr_b16 v[166:167], v189 offset:49152
	ds_read_b64_tr_b16 v[168:169], v189 offset:49664
	v_add_f32_e32 v154, v158, v58
	v_exp_f32_e32 v61, v61
	v_cvt_pk_bf16_f32 v138, v58, v59
	v_add_f32_e32 v154, v59, v154
	s_waitcnt lgkmcnt(4)
	v_mfma_f32_32x32x16_bf16 v[82:97], v[198:201], v[114:117], v[82:97]
	ds_read_b64_tr_b16 v[162:163], v189 offset:50176
	ds_read_b64_tr_b16 v[164:165], v189 offset:50688
	v_exp_f32_e32 v62, v62
	v_exp_f32_e32 v63, v63
	v_add_f32_e32 v154, v154, v60
	v_cvt_pk_bf16_f32 v139, v60, v61
	s_waitcnt lgkmcnt(5)
	v_mfma_f32_32x32x16_bf16 v[66:81], v[202:205], v[118:121], v[66:81]
	ds_read_b64_tr_b16 v[158:159], v189 offset:51200
	ds_read_b64_tr_b16 v[160:161], v189 offset:51712
	v_add_f32_e32 v154, v154, v61
	v_exp_f32_e32 v64, v64
	v_exp_f32_e32 v65, v65
	v_add_f32_e32 v198, v62, v154
	s_waitcnt lgkmcnt(6)
	v_mfma_f32_32x32x16_bf16 v[82:97], v[194:197], v[118:121], v[82:97]
	ds_read_b64_tr_b16 v[154:155], v189 offset:52224
	ds_read_b64_tr_b16 v[156:157], v189 offset:52736
	v_add_f32_e32 v141, v198, v63
	v_add_f32_e32 v198, v64, v141
	v_cvt_pk_bf16_f32 v140, v62, v63
	v_cvt_pk_bf16_f32 v141, v64, v65
	v_add_f32_e32 v194, v65, v198
	s_waitcnt vmcnt(6) lgkmcnt(0)
	s_barrier
	v_mfma_f32_32x32x16_bf16 v[2:17], v[150:153], v[166:169], v[2:17]
	ds_read_b64_tr_b16 v[34:35], v189 offset:53248
	ds_read_b64_tr_b16 v[36:37], v189 offset:53760
	v_exp_f32_e32 v66, v66
	v_exp_f32_e32 v67, v67
	v_exp_f32_e32 v68, v68
	v_mfma_f32_32x32x16_bf16 v[2:17], v[146:149], v[162:165], v[2:17]
	ds_read_b64_tr_b16 v[38:39], v189 offset:54272
	ds_read_b64_tr_b16 v[40:41], v189 offset:54784
	v_add_f32_e32 v42, v194, v66
	v_exp_f32_e32 v69, v69
	v_cvt_pk_bf16_f32 v134, v66, v67
	v_add_f32_e32 v46, v67, v42
	v_mfma_f32_32x32x16_bf16 v[2:17], v[142:145], v[158:161], v[2:17]
	ds_read_b64_tr_b16 v[42:43], v189 offset:55296
	ds_read_b64_tr_b16 v[44:45], v189 offset:55808
	v_exp_f32_e32 v70, v70
	v_exp_f32_e32 v71, v71
	v_add_f32_e32 v50, v46, v68
	v_cvt_pk_bf16_f32 v135, v68, v69
	v_mfma_f32_32x32x16_bf16 v[2:17], v[138:141], v[154:157], v[2:17]
	ds_read_b64_tr_b16 v[46:47], v189 offset:56320
	ds_read_b64_tr_b16 v[48:49], v189 offset:56832
	v_add_f32_e32 v50, v50, v69
	v_exp_f32_e32 v72, v72
	v_exp_f32_e32 v73, v73
	v_add_f32_e32 v54, v70, v50
	s_waitcnt lgkmcnt(6)
	v_mfma_f32_32x32x16_bf16 v[18:33], v[150:153], v[34:37], v[18:33]
	ds_read_b128 v[50:53], v182 offset:24576
	v_cvt_pk_bf16_f32 v136, v70, v71
	v_add_f32_e32 v58, v54, v71
	v_exp_f32_e32 v74, v74
	v_exp_f32_e32 v75, v75
	s_waitcnt lgkmcnt(5)
	v_mfma_f32_32x32x16_bf16 v[18:33], v[146:149], v[38:41], v[18:33]
	ds_read_b128 v[54:57], v182 offset:28672
	v_add_f32_e32 v34, v58, v72
	v_exp_f32_e32 v76, v76
	v_cvt_pk_bf16_f32 v137, v72, v73
	v_add_f32_e32 v34, v73, v34
	s_waitcnt lgkmcnt(4)
	v_mfma_f32_32x32x16_bf16 v[18:33], v[142:145], v[42:45], v[18:33]
	ds_read_b128 v[154:157], v183 offset:24576
	v_add_f32_e32 v34, v34, v74
	v_exp_f32_e32 v77, v77
	v_cvt_pk_bf16_f32 v130, v74, v75
	v_add_f32_e32 v34, v75, v34
	s_waitcnt lgkmcnt(3)
	v_mfma_f32_32x32x16_bf16 v[18:33], v[138:141], v[46:49], v[18:33]
	ds_read_b128 v[162:165], v183 offset:28672
	v_exp_f32_e32 v78, v78
	v_exp_f32_e32 v79, v79
	v_add_f32_e32 v34, v34, v76
	v_cvt_pk_bf16_f32 v131, v76, v77
	s_nop 0
	v_add_f32_e32 v34, v34, v77
	v_add_f32_e32 v59, v78, v34
	s_waitcnt lgkmcnt(3)
	v_mfma_f32_32x32x16_bf16 v[34:49], v[50:53], v[98:101], 0
	ds_read_b128 v[166:169], v184 offset:24576
	v_exp_f32_e32 v80, v80
	v_exp_f32_e32 v81, v81
	ds_read_b128 v[158:161], v184 offset:28672
	v_add_f32_e32 v193, v59, v79
	s_waitcnt lgkmcnt(4)
	v_mfma_f32_32x32x16_bf16 v[50:65], v[54:57], v[98:101], 0
	v_exp_f32_e32 v82, v82
	v_exp_f32_e32 v83, v83
	v_cvt_pk_bf16_f32 v132, v78, v79
	s_add_i32 s26, 0x3000, s8
	s_add_i32 s28, 0x6000, s12
	s_add_i32 s24, s26, 0x2000
	s_mov_b32 m0, s26
	s_nop 0
	global_load_lds_dwordx4 v174, s[20:21]
	s_mov_b32 m0, s24
	s_nop 0
	global_load_lds_dwordx4 v192, s[22:23]
	s_mov_b32 m0, s28
	s_nop 0
	global_load_lds_dwordx4 v191, s[20:21]
	s_mov_b32 m0, s25
	s_waitcnt lgkmcnt(3)
	v_mfma_f32_32x32x16_bf16 v[34:49], v[154:157], v[102:105], v[34:49]
	ds_read_b128 v[194:197], v185 offset:24576
	v_add_f32_e32 v154, v193, v80
	v_exp_f32_e32 v84, v84
	v_cvt_pk_bf16_f32 v133, v80, v81
	v_add_f32_e32 v193, v81, v154
	s_waitcnt lgkmcnt(3)
	v_mfma_f32_32x32x16_bf16 v[50:65], v[162:165], v[102:105], v[50:65]
	ds_read_b128 v[154:157], v185 offset:28672
	v_add_f32_e32 v193, v193, v82
	v_exp_f32_e32 v85, v85
	v_cvt_pk_bf16_f32 v126, v82, v83
	v_add_f32_e32 v193, v83, v193
	s_waitcnt lgkmcnt(3)
	v_mfma_f32_32x32x16_bf16 v[34:49], v[166:169], v[106:109], v[34:49]
	ds_read_b128 v[162:165], v187 offset:32768
	v_exp_f32_e32 v86, v86
	v_exp_f32_e32 v87, v87
	v_add_f32_e32 v193, v193, v84
	v_cvt_pk_bf16_f32 v127, v84, v85
	s_waitcnt lgkmcnt(3)
	v_mfma_f32_32x32x16_bf16 v[50:65], v[158:161], v[106:109], v[50:65]
	ds_read_b128 v[198:201], v187 offset:34816
	v_add_f32_e32 v166, v193, v85
	v_exp_f32_e32 v88, v88
	v_exp_f32_e32 v89, v89
	v_add_f32_e32 v166, v86, v166
	s_waitcnt lgkmcnt(3)
	v_mfma_f32_32x32x16_bf16 v[34:49], v[194:197], v[110:113], v[34:49]
	ds_read_b128 v[202:205], v188 offset:32768
	v_cvt_pk_bf16_f32 v128, v86, v87
	v_add_f32_e32 v159, v166, v87
	v_exp_f32_e32 v90, v90
	v_exp_f32_e32 v91, v91
	s_waitcnt lgkmcnt(3)
	v_mfma_f32_32x32x16_bf16 v[50:65], v[154:157], v[110:113], v[50:65]
	ds_read_b128 v[194:197], v188 offset:34816
	v_add_f32_e32 v158, v159, v88
	v_exp_f32_e32 v92, v92
	v_cvt_pk_bf16_f32 v129, v88, v89
	v_add_f32_e32 v158, v89, v158
	s_waitcnt lgkmcnt(3)
	v_mfma_f32_32x32x16_bf16 v[34:49], v[162:165], v[114:117], v[34:49]
	ds_read_b64_tr_b16 v[166:167], v189 offset:57344
	ds_read_b64_tr_b16 v[168:169], v189 offset:57856
	v_add_f32_e32 v154, v158, v90
	v_exp_f32_e32 v93, v93
	v_cvt_pk_bf16_f32 v122, v90, v91
	v_add_f32_e32 v154, v91, v154
	s_waitcnt lgkmcnt(4)
	v_mfma_f32_32x32x16_bf16 v[50:65], v[198:201], v[114:117], v[50:65]
	ds_read_b64_tr_b16 v[162:163], v189 offset:58368
	ds_read_b64_tr_b16 v[164:165], v189 offset:58880
	v_exp_f32_e32 v94, v94
	v_exp_f32_e32 v95, v95
	v_add_f32_e32 v154, v154, v92
	v_cvt_pk_bf16_f32 v123, v92, v93
	s_waitcnt lgkmcnt(5)
	v_mfma_f32_32x32x16_bf16 v[34:49], v[202:205], v[118:121], v[34:49]
	ds_read_b64_tr_b16 v[158:159], v189 offset:59392
	ds_read_b64_tr_b16 v[160:161], v189 offset:59904
	v_add_f32_e32 v154, v154, v93
	v_exp_f32_e32 v96, v96
	v_exp_f32_e32 v97, v97
	v_add_f32_e32 v193, v94, v154
	s_waitcnt lgkmcnt(6)
	v_mfma_f32_32x32x16_bf16 v[50:65], v[194:197], v[118:121], v[50:65]
	ds_read_b64_tr_b16 v[154:155], v189 offset:60416
	ds_read_b64_tr_b16 v[156:157], v189 offset:60928
	v_add_f32_e32 v125, v193, v95
	v_add_f32_e32 v193, v96, v125
	v_cvt_pk_bf16_f32 v124, v94, v95
	v_cvt_pk_bf16_f32 v125, v96, v97
	v_add_f32_e32 v193, v97, v193
	s_add_u32 s22, s22, 0x2000
	s_addc_u32 s23, s23, 0
	s_add_u32 s20, s20, 0x40000
	s_addc_u32 s21, s21, 0
	s_waitcnt vmcnt(6) lgkmcnt(0)
	s_barrier
	v_mfma_f32_32x32x16_bf16 v[2:17], v[134:137], v[166:169], v[2:17]
	ds_read_b64_tr_b16 v[66:67], v189 offset:61440
	ds_read_b64_tr_b16 v[68:69], v189 offset:61952
	v_exp_f32_e32 v34, v34
	v_exp_f32_e32 v35, v35
	v_exp_f32_e32 v36, v36
	v_mfma_f32_32x32x16_bf16 v[2:17], v[130:133], v[162:165], v[2:17]
	ds_read_b64_tr_b16 v[70:71], v189 offset:62464
	ds_read_b64_tr_b16 v[72:73], v189 offset:62976
	v_add_f32_e32 v74, v193, v34
	v_exp_f32_e32 v37, v37
	v_cvt_pk_bf16_f32 v150, v34, v35
	v_add_f32_e32 v78, v35, v74
	v_mfma_f32_32x32x16_bf16 v[2:17], v[126:129], v[158:161], v[2:17]
	ds_read_b64_tr_b16 v[74:75], v189 offset:63488
	ds_read_b64_tr_b16 v[76:77], v189 offset:64000
	v_exp_f32_e32 v38, v38
	v_exp_f32_e32 v39, v39
	v_add_f32_e32 v82, v78, v36
	v_cvt_pk_bf16_f32 v151, v36, v37
	v_mfma_f32_32x32x16_bf16 v[2:17], v[122:125], v[154:157], v[2:17]
	ds_read_b64_tr_b16 v[78:79], v189 offset:64512
	ds_read_b64_tr_b16 v[80:81], v189 offset:65024
	v_add_f32_e32 v82, v82, v37
	v_exp_f32_e32 v40, v40
	v_exp_f32_e32 v41, v41
	v_add_f32_e32 v86, v38, v82
	s_waitcnt lgkmcnt(6)
	v_mfma_f32_32x32x16_bf16 v[18:33], v[134:137], v[66:69], v[18:33]
	ds_read_b128 v[82:85], v182 offset:36864
	v_cvt_pk_bf16_f32 v152, v38, v39
	v_add_f32_e32 v90, v86, v39
	v_exp_f32_e32 v42, v42
	v_exp_f32_e32 v43, v43
	s_waitcnt lgkmcnt(5)
	v_mfma_f32_32x32x16_bf16 v[18:33], v[130:133], v[70:73], v[18:33]
	ds_read_b128 v[86:89], v182 offset:40960
	v_add_f32_e32 v66, v90, v40
	v_exp_f32_e32 v44, v44
	v_cvt_pk_bf16_f32 v153, v40, v41
	v_add_f32_e32 v66, v41, v66
	s_waitcnt lgkmcnt(4)
	v_mfma_f32_32x32x16_bf16 v[18:33], v[126:129], v[74:77], v[18:33]
	ds_read_b128 v[154:157], v183 offset:36864
	v_add_f32_e32 v66, v66, v42
	v_exp_f32_e32 v45, v45
	v_cvt_pk_bf16_f32 v146, v42, v43
	v_add_f32_e32 v66, v43, v66
	s_waitcnt lgkmcnt(3)
	v_mfma_f32_32x32x16_bf16 v[18:33], v[122:125], v[78:81], v[18:33]
	ds_read_b128 v[162:165], v183 offset:40960
	v_exp_f32_e32 v46, v46
	v_exp_f32_e32 v47, v47
	v_add_f32_e32 v66, v66, v44
	v_cvt_pk_bf16_f32 v147, v44, v45
	s_nop 0
	v_add_f32_e32 v66, v66, v45
	v_add_f32_e32 v91, v46, v66
	s_waitcnt lgkmcnt(3)
	v_mfma_f32_32x32x16_bf16 v[66:81], v[82:85], v[98:101], 0
	ds_read_b128 v[166:169], v184 offset:36864
	v_exp_f32_e32 v48, v48
	v_exp_f32_e32 v49, v49
	ds_read_b128 v[158:161], v184 offset:40960
	v_add_f32_e32 v193, v91, v47
	s_waitcnt lgkmcnt(4)
	v_mfma_f32_32x32x16_bf16 v[82:97], v[86:89], v[98:101], 0
	v_exp_f32_e32 v50, v50
	v_exp_f32_e32 v51, v51
	v_cvt_pk_bf16_f32 v148, v46, v47
	s_add_u32 s26, s20, 0xfffe0000
	s_addc_u32 s27, s21, -1
	s_add_i32 s31, 0x6000, s8
	s_add_i32 s33, 0x8000, s12
	s_add_u32 s28, s22, 0xfffff000
	s_addc_u32 s29, s23, -1
	s_add_i32 s40, s31, 0x2000
	s_mov_b32 m0, s31
	s_nop 0
	global_load_lds_dwordx4 v174, s[26:27]
	s_mov_b32 m0, s40
	s_nop 0
	global_load_lds_dwordx4 v192, s[28:29]
	s_mov_b32 m0, s33
	s_nop 0
	global_load_lds_dwordx4 v191, s[26:27]
	s_mov_b32 m0, s41
	s_waitcnt lgkmcnt(3)
	v_mfma_f32_32x32x16_bf16 v[66:81], v[154:157], v[102:105], v[66:81]
	ds_read_b128 v[194:197], v185 offset:36864
	v_add_f32_e32 v193, v193, v48
	v_cvt_pk_bf16_f32 v149, v48, v49
	v_add_f32_e32 v193, v49, v193
	v_exp_f32_e32 v52, v52
	s_waitcnt lgkmcnt(3)
	v_mfma_f32_32x32x16_bf16 v[82:97], v[162:165], v[102:105], v[82:97]
	ds_read_b128 v[154:157], v185 offset:40960
	v_add_f32_e32 v193, v193, v50
	v_exp_f32_e32 v53, v53
	v_cvt_pk_bf16_f32 v142, v50, v51
	v_add_f32_e32 v193, v51, v193
	s_waitcnt lgkmcnt(3)
	v_mfma_f32_32x32x16_bf16 v[66:81], v[166:169], v[106:109], v[66:81]
	ds_read_b128 v[162:165], v187 offset:45056
	v_exp_f32_e32 v54, v54
	v_exp_f32_e32 v55, v55
	v_add_f32_e32 v193, v193, v52
	v_cvt_pk_bf16_f32 v143, v52, v53
	s_waitcnt lgkmcnt(3)
	v_mfma_f32_32x32x16_bf16 v[82:97], v[158:161], v[106:109], v[82:97]
	ds_read_b128 v[198:201], v187 offset:47104
	v_add_f32_e32 v166, v193, v53
	v_exp_f32_e32 v56, v56
	v_exp_f32_e32 v57, v57
	v_add_f32_e32 v166, v54, v166
	s_waitcnt lgkmcnt(3)
	v_mfma_f32_32x32x16_bf16 v[66:81], v[194:197], v[110:113], v[66:81]
	ds_read_b128 v[202:205], v188 offset:45056
	v_cvt_pk_bf16_f32 v144, v54, v55
	v_add_f32_e32 v159, v166, v55
	v_exp_f32_e32 v58, v58
	v_exp_f32_e32 v59, v59
	s_waitcnt lgkmcnt(3)
	v_mfma_f32_32x32x16_bf16 v[82:97], v[154:157], v[110:113], v[82:97]
	ds_read_b128 v[194:197], v188 offset:47104
	v_add_f32_e32 v158, v159, v56
	v_exp_f32_e32 v60, v60
	v_cvt_pk_bf16_f32 v145, v56, v57
	v_add_f32_e32 v158, v57, v158
	s_waitcnt lgkmcnt(3)
	v_mfma_f32_32x32x16_bf16 v[66:81], v[162:165], v[114:117], v[66:81]
	ds_read_b64_tr_b16 v[166:167], v189 offset:16384
	ds_read_b64_tr_b16 v[168:169], v189 offset:16896
	v_add_f32_e32 v154, v158, v58
	v_exp_f32_e32 v61, v61
	v_cvt_pk_bf16_f32 v138, v58, v59
	v_add_f32_e32 v154, v59, v154
	s_waitcnt lgkmcnt(4)
	v_mfma_f32_32x32x16_bf16 v[82:97], v[198:201], v[114:117], v[82:97]
	ds_read_b64_tr_b16 v[162:163], v189 offset:17408
	ds_read_b64_tr_b16 v[164:165], v189 offset:17920
	v_exp_f32_e32 v62, v62
	v_exp_f32_e32 v63, v63
	v_add_f32_e32 v154, v154, v60
	v_cvt_pk_bf16_f32 v139, v60, v61
	s_waitcnt lgkmcnt(5)
	v_mfma_f32_32x32x16_bf16 v[66:81], v[202:205], v[118:121], v[66:81]
	ds_read_b64_tr_b16 v[158:159], v189 offset:18432
	ds_read_b64_tr_b16 v[160:161], v189 offset:18944
	v_add_f32_e32 v154, v154, v61
	v_exp_f32_e32 v64, v64
	v_exp_f32_e32 v65, v65
	v_add_f32_e32 v198, v62, v154
	s_waitcnt lgkmcnt(6)
	v_mfma_f32_32x32x16_bf16 v[82:97], v[194:197], v[118:121], v[82:97]
	ds_read_b64_tr_b16 v[154:155], v189 offset:19456
	ds_read_b64_tr_b16 v[156:157], v189 offset:19968
	v_add_f32_e32 v141, v198, v63
	v_add_f32_e32 v198, v64, v141
	v_cvt_pk_bf16_f32 v140, v62, v63
	v_cvt_pk_bf16_f32 v141, v64, v65
	v_add_f32_e32 v194, v65, v198
	s_waitcnt vmcnt(6) lgkmcnt(0)
	s_barrier
	v_mfma_f32_32x32x16_bf16 v[2:17], v[150:153], v[166:169], v[2:17]
	ds_read_b64_tr_b16 v[34:35], v189 offset:20480
	ds_read_b64_tr_b16 v[36:37], v189 offset:20992
	v_exp_f32_e32 v66, v66
	v_exp_f32_e32 v67, v67
	v_exp_f32_e32 v68, v68
	v_mfma_f32_32x32x16_bf16 v[2:17], v[146:149], v[162:165], v[2:17]
	ds_read_b64_tr_b16 v[38:39], v189 offset:21504
	ds_read_b64_tr_b16 v[40:41], v189 offset:22016
	v_add_f32_e32 v42, v194, v66
	v_exp_f32_e32 v69, v69
	v_cvt_pk_bf16_f32 v134, v66, v67
	v_add_f32_e32 v46, v67, v42
	v_mfma_f32_32x32x16_bf16 v[2:17], v[142:145], v[158:161], v[2:17]
	ds_read_b64_tr_b16 v[42:43], v189 offset:22528
	ds_read_b64_tr_b16 v[44:45], v189 offset:23040
	v_exp_f32_e32 v70, v70
	v_exp_f32_e32 v71, v71
	v_add_f32_e32 v50, v46, v68
	v_cvt_pk_bf16_f32 v135, v68, v69
	v_mfma_f32_32x32x16_bf16 v[2:17], v[138:141], v[154:157], v[2:17]
	ds_read_b64_tr_b16 v[46:47], v189 offset:23552
	ds_read_b64_tr_b16 v[48:49], v189 offset:24064
	v_add_f32_e32 v50, v50, v69
	v_exp_f32_e32 v72, v72
	v_exp_f32_e32 v73, v73
	v_add_f32_e32 v54, v70, v50
	s_waitcnt lgkmcnt(6)
	v_mfma_f32_32x32x16_bf16 v[18:33], v[150:153], v[34:37], v[18:33]
	ds_read_b128 v[50:53], v182
	v_cvt_pk_bf16_f32 v136, v70, v71
	v_add_f32_e32 v58, v54, v71
	v_exp_f32_e32 v74, v74
	v_exp_f32_e32 v75, v75
	s_waitcnt lgkmcnt(5)
	v_mfma_f32_32x32x16_bf16 v[18:33], v[146:149], v[38:41], v[18:33]
	ds_read_b128 v[54:57], v182 offset:4096
	v_add_f32_e32 v34, v58, v72
	v_exp_f32_e32 v76, v76
	v_cvt_pk_bf16_f32 v137, v72, v73
	v_add_f32_e32 v34, v73, v34
	s_waitcnt lgkmcnt(4)
	v_mfma_f32_32x32x16_bf16 v[18:33], v[142:145], v[42:45], v[18:33]
	ds_read_b128 v[154:157], v183
	v_add_f32_e32 v34, v34, v74
	v_exp_f32_e32 v77, v77
	v_cvt_pk_bf16_f32 v130, v74, v75
	v_add_f32_e32 v34, v75, v34
	s_waitcnt lgkmcnt(3)
	v_mfma_f32_32x32x16_bf16 v[18:33], v[138:141], v[46:49], v[18:33]
	ds_read_b128 v[162:165], v183 offset:4096
	v_exp_f32_e32 v78, v78
	v_exp_f32_e32 v79, v79
	v_add_f32_e32 v34, v34, v76
	v_cvt_pk_bf16_f32 v131, v76, v77
	s_nop 0
	v_add_f32_e32 v34, v34, v77
	v_add_f32_e32 v59, v78, v34
	s_waitcnt lgkmcnt(3)
	v_mfma_f32_32x32x16_bf16 v[34:49], v[50:53], v[98:101], 0
	ds_read_b128 v[166:169], v184
	v_exp_f32_e32 v80, v80
	v_exp_f32_e32 v81, v81
	ds_read_b128 v[158:161], v184 offset:4096
	v_add_f32_e32 v193, v59, v79
	s_waitcnt lgkmcnt(4)
	v_mfma_f32_32x32x16_bf16 v[50:65], v[54:57], v[98:101], 0
	v_exp_f32_e32 v82, v82
	v_exp_f32_e32 v83, v83
	v_cvt_pk_bf16_f32 v132, v78, v79
	s_add_i32 s26, 0x9000, s8
	s_add_i32 s28, 0xa000, s12
	s_add_i32 s24, s26, 0x2000
	s_mov_b32 m0, s26
	s_nop 0
	global_load_lds_dwordx4 v174, s[20:21]
	s_mov_b32 m0, s24
	s_nop 0
	global_load_lds_dwordx4 v192, s[22:23]
	s_mov_b32 m0, s28
	s_nop 0
	global_load_lds_dwordx4 v191, s[20:21]
	s_mov_b32 m0, s25
	s_waitcnt lgkmcnt(3)
	v_mfma_f32_32x32x16_bf16 v[34:49], v[154:157], v[102:105], v[34:49]
	ds_read_b128 v[194:197], v185
	v_add_f32_e32 v154, v193, v80
	v_exp_f32_e32 v84, v84
	v_cvt_pk_bf16_f32 v133, v80, v81
	v_add_f32_e32 v193, v81, v154
	s_waitcnt lgkmcnt(3)
	v_mfma_f32_32x32x16_bf16 v[50:65], v[162:165], v[102:105], v[50:65]
	ds_read_b128 v[154:157], v185 offset:4096
	v_add_f32_e32 v193, v193, v82
	v_exp_f32_e32 v85, v85
	v_cvt_pk_bf16_f32 v126, v82, v83
	v_add_f32_e32 v193, v83, v193
	s_waitcnt lgkmcnt(3)
	v_mfma_f32_32x32x16_bf16 v[34:49], v[166:169], v[106:109], v[34:49]
	ds_read_b128 v[162:165], v187 offset:8192
	v_exp_f32_e32 v86, v86
	v_exp_f32_e32 v87, v87
	v_add_f32_e32 v193, v193, v84
	v_cvt_pk_bf16_f32 v127, v84, v85
	s_waitcnt lgkmcnt(3)
	v_mfma_f32_32x32x16_bf16 v[50:65], v[158:161], v[106:109], v[50:65]
	ds_read_b128 v[198:201], v187 offset:10240
	v_add_f32_e32 v166, v193, v85
	v_exp_f32_e32 v88, v88
	v_exp_f32_e32 v89, v89
	v_add_f32_e32 v166, v86, v166
	s_waitcnt lgkmcnt(3)
	v_mfma_f32_32x32x16_bf16 v[34:49], v[194:197], v[110:113], v[34:49]
	ds_read_b128 v[202:205], v188 offset:8192
	v_cvt_pk_bf16_f32 v128, v86, v87
	v_add_f32_e32 v159, v166, v87
	v_exp_f32_e32 v90, v90
	v_exp_f32_e32 v91, v91
	s_waitcnt lgkmcnt(3)
	v_mfma_f32_32x32x16_bf16 v[50:65], v[154:157], v[110:113], v[50:65]
	ds_read_b128 v[194:197], v188 offset:10240
	v_add_f32_e32 v158, v159, v88
	v_exp_f32_e32 v92, v92
	v_cvt_pk_bf16_f32 v129, v88, v89
	v_add_f32_e32 v158, v89, v158
	s_waitcnt lgkmcnt(3)
	v_mfma_f32_32x32x16_bf16 v[34:49], v[162:165], v[114:117], v[34:49]
	ds_read_b64_tr_b16 v[166:167], v189 offset:24576
	ds_read_b64_tr_b16 v[168:169], v189 offset:25088
	v_add_f32_e32 v154, v158, v90
	v_exp_f32_e32 v93, v93
	v_cvt_pk_bf16_f32 v122, v90, v91
	v_add_f32_e32 v154, v91, v154
	s_waitcnt lgkmcnt(4)
	v_mfma_f32_32x32x16_bf16 v[50:65], v[198:201], v[114:117], v[50:65]
	ds_read_b64_tr_b16 v[162:163], v189 offset:25600
	ds_read_b64_tr_b16 v[164:165], v189 offset:26112
	v_exp_f32_e32 v94, v94
	v_exp_f32_e32 v95, v95
	v_add_f32_e32 v154, v154, v92
	v_cvt_pk_bf16_f32 v123, v92, v93
	s_waitcnt lgkmcnt(5)
	v_mfma_f32_32x32x16_bf16 v[34:49], v[202:205], v[118:121], v[34:49]
	ds_read_b64_tr_b16 v[158:159], v189 offset:26624
	ds_read_b64_tr_b16 v[160:161], v189 offset:27136
	v_add_f32_e32 v154, v154, v93
	v_exp_f32_e32 v96, v96
	v_exp_f32_e32 v97, v97
	v_add_f32_e32 v193, v94, v154
	s_waitcnt lgkmcnt(6)
	v_mfma_f32_32x32x16_bf16 v[50:65], v[194:197], v[118:121], v[50:65]
	ds_read_b64_tr_b16 v[154:155], v189 offset:27648
	ds_read_b64_tr_b16 v[156:157], v189 offset:28160
	v_add_f32_e32 v125, v193, v95
	v_add_f32_e32 v193, v96, v125
	v_cvt_pk_bf16_f32 v124, v94, v95
	v_cvt_pk_bf16_f32 v125, v96, v97
	v_add_f32_e32 v193, v97, v193
	s_add_u32 s22, s22, 0x2000
	s_addc_u32 s23, s23, 0
	s_add_u32 s20, s20, 0x40000
	s_addc_u32 s21, s21, 0
	s_waitcnt vmcnt(6) lgkmcnt(0)
	s_barrier
	v_mfma_f32_32x32x16_bf16 v[2:17], v[134:137], v[166:169], v[2:17]
	ds_read_b64_tr_b16 v[66:67], v189 offset:28672
	ds_read_b64_tr_b16 v[68:69], v189 offset:29184
	v_exp_f32_e32 v34, v34
	v_exp_f32_e32 v35, v35
	v_exp_f32_e32 v36, v36
	v_mfma_f32_32x32x16_bf16 v[2:17], v[130:133], v[162:165], v[2:17]
	ds_read_b64_tr_b16 v[70:71], v189 offset:29696
	ds_read_b64_tr_b16 v[72:73], v189 offset:30208
	v_add_f32_e32 v74, v193, v34
	v_exp_f32_e32 v37, v37
	v_cvt_pk_bf16_f32 v150, v34, v35
	v_add_f32_e32 v78, v35, v74
	v_mfma_f32_32x32x16_bf16 v[2:17], v[126:129], v[158:161], v[2:17]
	ds_read_b64_tr_b16 v[74:75], v189 offset:30720
	ds_read_b64_tr_b16 v[76:77], v189 offset:31232
	v_exp_f32_e32 v38, v38
	v_exp_f32_e32 v39, v39
	v_add_f32_e32 v82, v78, v36
	v_cvt_pk_bf16_f32 v151, v36, v37
	v_mfma_f32_32x32x16_bf16 v[2:17], v[122:125], v[154:157], v[2:17]
	ds_read_b64_tr_b16 v[78:79], v189 offset:31744
	ds_read_b64_tr_b16 v[80:81], v189 offset:32256
	v_add_f32_e32 v82, v82, v37
	v_exp_f32_e32 v40, v40
	v_exp_f32_e32 v41, v41
	v_add_f32_e32 v86, v38, v82
	s_waitcnt lgkmcnt(6)
	v_mfma_f32_32x32x16_bf16 v[18:33], v[134:137], v[66:69], v[18:33]
	ds_read_b128 v[82:85], v182 offset:12288
	v_cvt_pk_bf16_f32 v152, v38, v39
	v_add_f32_e32 v90, v86, v39
	v_exp_f32_e32 v42, v42
	v_exp_f32_e32 v43, v43
	s_waitcnt lgkmcnt(5)
	v_mfma_f32_32x32x16_bf16 v[18:33], v[130:133], v[70:73], v[18:33]
	ds_read_b128 v[86:89], v182 offset:16384
	v_add_f32_e32 v66, v90, v40
	v_exp_f32_e32 v44, v44
	v_cvt_pk_bf16_f32 v153, v40, v41
	v_add_f32_e32 v66, v41, v66
	s_waitcnt lgkmcnt(4)
	v_mfma_f32_32x32x16_bf16 v[18:33], v[126:129], v[74:77], v[18:33]
	ds_read_b128 v[154:157], v183 offset:12288
	v_add_f32_e32 v66, v66, v42
	v_exp_f32_e32 v45, v45
	v_cvt_pk_bf16_f32 v146, v42, v43
	v_add_f32_e32 v66, v43, v66
	s_waitcnt lgkmcnt(3)
	v_mfma_f32_32x32x16_bf16 v[18:33], v[122:125], v[78:81], v[18:33]
	ds_read_b128 v[162:165], v183 offset:16384
	v_exp_f32_e32 v46, v46
	v_exp_f32_e32 v47, v47
	v_add_f32_e32 v66, v66, v44
	v_cvt_pk_bf16_f32 v147, v44, v45
	s_nop 0
	v_add_f32_e32 v66, v66, v45
	v_add_f32_e32 v91, v46, v66
	s_waitcnt lgkmcnt(3)
	v_mfma_f32_32x32x16_bf16 v[66:81], v[82:85], v[98:101], 0
	ds_read_b128 v[166:169], v184 offset:12288
	v_exp_f32_e32 v48, v48
	v_exp_f32_e32 v49, v49
	ds_read_b128 v[158:161], v184 offset:16384
	v_add_f32_e32 v193, v91, v47
	s_waitcnt lgkmcnt(4)
	v_mfma_f32_32x32x16_bf16 v[82:97], v[86:89], v[98:101], 0
	v_exp_f32_e32 v50, v50
	v_exp_f32_e32 v51, v51
	v_cvt_pk_bf16_f32 v148, v46, v47
	s_add_u32 s26, s20, 0xfffe0000
	s_addc_u32 s27, s21, -1
	s_add_i32 s31, 0, s8
	s_add_i32 s33, 0, s12
	s_add_u32 s28, s22, 0xfffff000
	s_addc_u32 s29, s23, -1
	s_add_i32 s40, s31, 0x2000
	s_mov_b32 m0, s31
	s_nop 0
	global_load_lds_dwordx4 v174, s[26:27]
	s_mov_b32 m0, s40
	s_nop 0
	global_load_lds_dwordx4 v192, s[28:29]
	s_mov_b32 m0, s33
	s_nop 0
	global_load_lds_dwordx4 v191, s[26:27]
	s_mov_b32 m0, s41
	s_waitcnt lgkmcnt(3)
	v_mfma_f32_32x32x16_bf16 v[66:81], v[154:157], v[102:105], v[66:81]
	ds_read_b128 v[194:197], v185 offset:12288
	v_add_f32_e32 v193, v193, v48
	v_cvt_pk_bf16_f32 v149, v48, v49
	v_add_f32_e32 v193, v49, v193
	v_exp_f32_e32 v52, v52
	s_waitcnt lgkmcnt(3)
	v_mfma_f32_32x32x16_bf16 v[82:97], v[162:165], v[102:105], v[82:97]
	ds_read_b128 v[154:157], v185 offset:16384
	v_add_f32_e32 v193, v193, v50
	v_exp_f32_e32 v53, v53
	v_cvt_pk_bf16_f32 v142, v50, v51
	v_add_f32_e32 v193, v51, v193
	s_waitcnt lgkmcnt(3)
	v_mfma_f32_32x32x16_bf16 v[66:81], v[166:169], v[106:109], v[66:81]
	ds_read_b128 v[162:165], v187 offset:20480
	v_exp_f32_e32 v54, v54
	v_exp_f32_e32 v55, v55
	v_add_f32_e32 v193, v193, v52
	v_cvt_pk_bf16_f32 v143, v52, v53
	s_waitcnt lgkmcnt(3)
	v_mfma_f32_32x32x16_bf16 v[82:97], v[158:161], v[106:109], v[82:97]
	ds_read_b128 v[198:201], v187 offset:22528
	v_add_f32_e32 v166, v193, v53
	v_exp_f32_e32 v56, v56
	v_exp_f32_e32 v57, v57
	v_add_f32_e32 v166, v54, v166
	s_waitcnt lgkmcnt(3)
	v_mfma_f32_32x32x16_bf16 v[66:81], v[194:197], v[110:113], v[66:81]
	ds_read_b128 v[202:205], v188 offset:20480
	v_cvt_pk_bf16_f32 v144, v54, v55
	v_add_f32_e32 v159, v166, v55
	v_exp_f32_e32 v58, v58
	v_exp_f32_e32 v59, v59
	s_waitcnt lgkmcnt(3)
	v_mfma_f32_32x32x16_bf16 v[82:97], v[154:157], v[110:113], v[82:97]
	ds_read_b128 v[194:197], v188 offset:22528
	v_add_f32_e32 v158, v159, v56
	v_exp_f32_e32 v60, v60
	v_cvt_pk_bf16_f32 v145, v56, v57
	v_add_f32_e32 v158, v57, v158
	s_waitcnt lgkmcnt(3)
	v_mfma_f32_32x32x16_bf16 v[66:81], v[162:165], v[114:117], v[66:81]
	ds_read_b64_tr_b16 v[166:167], v189 offset:32768
	ds_read_b64_tr_b16 v[168:169], v189 offset:33280
	v_add_f32_e32 v154, v158, v58
	v_exp_f32_e32 v61, v61
	v_cvt_pk_bf16_f32 v138, v58, v59
	v_add_f32_e32 v154, v59, v154
	s_waitcnt lgkmcnt(4)
	v_mfma_f32_32x32x16_bf16 v[82:97], v[198:201], v[114:117], v[82:97]
	ds_read_b64_tr_b16 v[162:163], v189 offset:33792
	ds_read_b64_tr_b16 v[164:165], v189 offset:34304
	v_exp_f32_e32 v62, v62
	v_exp_f32_e32 v63, v63
	v_add_f32_e32 v154, v154, v60
	v_cvt_pk_bf16_f32 v139, v60, v61
	s_waitcnt lgkmcnt(5)
	v_mfma_f32_32x32x16_bf16 v[66:81], v[202:205], v[118:121], v[66:81]
	ds_read_b64_tr_b16 v[158:159], v189 offset:34816
	ds_read_b64_tr_b16 v[160:161], v189 offset:35328
	v_add_f32_e32 v154, v154, v61
	v_exp_f32_e32 v64, v64
	v_exp_f32_e32 v65, v65
	v_add_f32_e32 v198, v62, v154
	s_waitcnt lgkmcnt(6)
	v_mfma_f32_32x32x16_bf16 v[82:97], v[194:197], v[118:121], v[82:97]
	ds_read_b64_tr_b16 v[154:155], v189 offset:35840
	ds_read_b64_tr_b16 v[156:157], v189 offset:36352
	v_add_f32_e32 v141, v198, v63
	v_add_f32_e32 v198, v64, v141
	v_cvt_pk_bf16_f32 v140, v62, v63
	v_cvt_pk_bf16_f32 v141, v64, v65
	v_add_f32_e32 v194, v65, v198
	s_waitcnt vmcnt(6) lgkmcnt(0)
	s_barrier
	v_mfma_f32_32x32x16_bf16 v[2:17], v[150:153], v[166:169], v[2:17]
	ds_read_b64_tr_b16 v[34:35], v189 offset:36864
	ds_read_b64_tr_b16 v[36:37], v189 offset:37376
	v_exp_f32_e32 v66, v66
	v_exp_f32_e32 v67, v67
	v_exp_f32_e32 v68, v68
	v_mfma_f32_32x32x16_bf16 v[2:17], v[146:149], v[162:165], v[2:17]
	ds_read_b64_tr_b16 v[38:39], v189 offset:37888
	ds_read_b64_tr_b16 v[40:41], v189 offset:38400
	v_add_f32_e32 v42, v194, v66
	v_exp_f32_e32 v69, v69
	v_cvt_pk_bf16_f32 v134, v66, v67
	v_add_f32_e32 v46, v67, v42
	v_mfma_f32_32x32x16_bf16 v[2:17], v[142:145], v[158:161], v[2:17]
	ds_read_b64_tr_b16 v[42:43], v189 offset:38912
	ds_read_b64_tr_b16 v[44:45], v189 offset:39424
	v_exp_f32_e32 v70, v70
	v_exp_f32_e32 v71, v71
	v_add_f32_e32 v50, v46, v68
	v_cvt_pk_bf16_f32 v135, v68, v69
	v_mfma_f32_32x32x16_bf16 v[2:17], v[138:141], v[154:157], v[2:17]
	ds_read_b64_tr_b16 v[46:47], v189 offset:39936
	ds_read_b64_tr_b16 v[48:49], v189 offset:40448
	v_add_f32_e32 v50, v50, v69
	v_exp_f32_e32 v72, v72
	v_exp_f32_e32 v73, v73
	v_add_f32_e32 v54, v70, v50
	s_waitcnt lgkmcnt(6)
	v_mfma_f32_32x32x16_bf16 v[18:33], v[150:153], v[34:37], v[18:33]
	ds_read_b128 v[50:53], v182 offset:24576
	v_cvt_pk_bf16_f32 v136, v70, v71
	v_add_f32_e32 v58, v54, v71
	v_exp_f32_e32 v74, v74
	v_exp_f32_e32 v75, v75
	s_waitcnt lgkmcnt(5)
	v_mfma_f32_32x32x16_bf16 v[18:33], v[146:149], v[38:41], v[18:33]
	ds_read_b128 v[54:57], v182 offset:28672
	v_add_f32_e32 v34, v58, v72
	v_exp_f32_e32 v76, v76
	v_cvt_pk_bf16_f32 v137, v72, v73
	v_add_f32_e32 v34, v73, v34
	s_waitcnt lgkmcnt(4)
	v_mfma_f32_32x32x16_bf16 v[18:33], v[142:145], v[42:45], v[18:33]
	ds_read_b128 v[154:157], v183 offset:24576
	v_add_f32_e32 v34, v34, v74
	v_exp_f32_e32 v77, v77
	v_cvt_pk_bf16_f32 v130, v74, v75
	v_add_f32_e32 v34, v75, v34
	s_waitcnt lgkmcnt(3)
	v_mfma_f32_32x32x16_bf16 v[18:33], v[138:141], v[46:49], v[18:33]
	ds_read_b128 v[162:165], v183 offset:28672
	v_exp_f32_e32 v78, v78
	v_exp_f32_e32 v79, v79
	v_add_f32_e32 v34, v34, v76
	v_cvt_pk_bf16_f32 v131, v76, v77
	s_nop 0
	v_add_f32_e32 v34, v34, v77
	v_add_f32_e32 v59, v78, v34
	s_waitcnt lgkmcnt(3)
	v_mfma_f32_32x32x16_bf16 v[34:49], v[50:53], v[98:101], 0
	ds_read_b128 v[166:169], v184 offset:24576
	v_exp_f32_e32 v80, v80
	v_exp_f32_e32 v81, v81
	ds_read_b128 v[158:161], v184 offset:28672
	v_add_f32_e32 v193, v59, v79
	s_waitcnt lgkmcnt(4)
	v_mfma_f32_32x32x16_bf16 v[50:65], v[54:57], v[98:101], 0
	v_exp_f32_e32 v82, v82
	v_exp_f32_e32 v83, v83
	v_cvt_pk_bf16_f32 v132, v78, v79
	s_add_i32 s26, 0x3000, s8
	s_add_i32 s28, 0x2000, s12
	s_add_i32 s24, s26, 0x2000
	s_mov_b32 m0, s26
	s_nop 0
	global_load_lds_dwordx4 v174, s[20:21]
	s_mov_b32 m0, s24
	s_nop 0
	global_load_lds_dwordx4 v192, s[22:23]
	s_mov_b32 m0, s28
	s_nop 0
	global_load_lds_dwordx4 v191, s[20:21]
	s_mov_b32 m0, s25
	s_waitcnt lgkmcnt(3)
	v_mfma_f32_32x32x16_bf16 v[34:49], v[154:157], v[102:105], v[34:49]
	ds_read_b128 v[194:197], v185 offset:24576
	v_add_f32_e32 v154, v193, v80
	v_exp_f32_e32 v84, v84
	v_cvt_pk_bf16_f32 v133, v80, v81
	v_add_f32_e32 v193, v81, v154
	s_waitcnt lgkmcnt(3)
	v_mfma_f32_32x32x16_bf16 v[50:65], v[162:165], v[102:105], v[50:65]
	ds_read_b128 v[154:157], v185 offset:28672
	v_add_f32_e32 v193, v193, v82
	v_exp_f32_e32 v85, v85
	v_cvt_pk_bf16_f32 v126, v82, v83
	v_add_f32_e32 v193, v83, v193
	s_waitcnt lgkmcnt(3)
	v_mfma_f32_32x32x16_bf16 v[34:49], v[166:169], v[106:109], v[34:49]
	ds_read_b128 v[162:165], v187 offset:32768
	v_exp_f32_e32 v86, v86
	v_exp_f32_e32 v87, v87
	v_add_f32_e32 v193, v193, v84
	v_cvt_pk_bf16_f32 v127, v84, v85
	s_waitcnt lgkmcnt(3)
	v_mfma_f32_32x32x16_bf16 v[50:65], v[158:161], v[106:109], v[50:65]
	ds_read_b128 v[198:201], v187 offset:34816
	v_add_f32_e32 v166, v193, v85
	v_exp_f32_e32 v88, v88
	v_exp_f32_e32 v89, v89
	v_add_f32_e32 v166, v86, v166
	s_waitcnt lgkmcnt(3)
	v_mfma_f32_32x32x16_bf16 v[34:49], v[194:197], v[110:113], v[34:49]
	ds_read_b128 v[202:205], v188 offset:32768
	v_cvt_pk_bf16_f32 v128, v86, v87
	v_add_f32_e32 v159, v166, v87
	v_exp_f32_e32 v90, v90
	v_exp_f32_e32 v91, v91
	s_waitcnt lgkmcnt(3)
	v_mfma_f32_32x32x16_bf16 v[50:65], v[154:157], v[110:113], v[50:65]
	ds_read_b128 v[194:197], v188 offset:34816
	v_add_f32_e32 v158, v159, v88
	v_exp_f32_e32 v92, v92
	v_cvt_pk_bf16_f32 v129, v88, v89
	v_add_f32_e32 v158, v89, v158
	s_waitcnt lgkmcnt(3)
	v_mfma_f32_32x32x16_bf16 v[34:49], v[162:165], v[114:117], v[34:49]
	ds_read_b64_tr_b16 v[166:167], v189 offset:40960
	ds_read_b64_tr_b16 v[168:169], v189 offset:41472
	v_add_f32_e32 v154, v158, v90
	v_exp_f32_e32 v93, v93
	v_cvt_pk_bf16_f32 v122, v90, v91
	v_add_f32_e32 v154, v91, v154
	s_waitcnt lgkmcnt(4)
	v_mfma_f32_32x32x16_bf16 v[50:65], v[198:201], v[114:117], v[50:65]
	ds_read_b64_tr_b16 v[162:163], v189 offset:41984
	ds_read_b64_tr_b16 v[164:165], v189 offset:42496
	v_exp_f32_e32 v94, v94
	v_exp_f32_e32 v95, v95
	v_add_f32_e32 v154, v154, v92
	v_cvt_pk_bf16_f32 v123, v92, v93
	s_waitcnt lgkmcnt(5)
	v_mfma_f32_32x32x16_bf16 v[34:49], v[202:205], v[118:121], v[34:49]
	ds_read_b64_tr_b16 v[158:159], v189 offset:43008
	ds_read_b64_tr_b16 v[160:161], v189 offset:43520
	v_add_f32_e32 v154, v154, v93
	v_exp_f32_e32 v96, v96
	v_exp_f32_e32 v97, v97
	v_add_f32_e32 v193, v94, v154
	s_waitcnt lgkmcnt(6)
	v_mfma_f32_32x32x16_bf16 v[50:65], v[194:197], v[118:121], v[50:65]
	ds_read_b64_tr_b16 v[154:155], v189 offset:44032
	ds_read_b64_tr_b16 v[156:157], v189 offset:44544
	v_add_f32_e32 v125, v193, v95
	v_add_f32_e32 v193, v96, v125
	v_cvt_pk_bf16_f32 v124, v94, v95
	v_cvt_pk_bf16_f32 v125, v96, v97
	v_add_f32_e32 v193, v97, v193
	s_add_u32 s22, s22, 0x2000
	s_addc_u32 s23, s23, 0
	s_add_u32 s20, s20, 0x40000
	s_addc_u32 s21, s21, 0
	s_waitcnt vmcnt(6) lgkmcnt(0)
	s_barrier
	v_mfma_f32_32x32x16_bf16 v[2:17], v[134:137], v[166:169], v[2:17]
	ds_read_b64_tr_b16 v[66:67], v189 offset:45056
	ds_read_b64_tr_b16 v[68:69], v189 offset:45568
	v_exp_f32_e32 v34, v34
	v_exp_f32_e32 v35, v35
	v_exp_f32_e32 v36, v36
	v_mfma_f32_32x32x16_bf16 v[2:17], v[130:133], v[162:165], v[2:17]
	ds_read_b64_tr_b16 v[70:71], v189 offset:46080
	ds_read_b64_tr_b16 v[72:73], v189 offset:46592
	v_add_f32_e32 v74, v193, v34
	v_exp_f32_e32 v37, v37
	v_cvt_pk_bf16_f32 v150, v34, v35
	v_add_f32_e32 v78, v35, v74
	v_mfma_f32_32x32x16_bf16 v[2:17], v[126:129], v[158:161], v[2:17]
	ds_read_b64_tr_b16 v[74:75], v189 offset:47104
	ds_read_b64_tr_b16 v[76:77], v189 offset:47616
	v_exp_f32_e32 v38, v38
	v_exp_f32_e32 v39, v39
	v_add_f32_e32 v82, v78, v36
	v_cvt_pk_bf16_f32 v151, v36, v37
	v_mfma_f32_32x32x16_bf16 v[2:17], v[122:125], v[154:157], v[2:17]
	ds_read_b64_tr_b16 v[78:79], v189 offset:48128
	ds_read_b64_tr_b16 v[80:81], v189 offset:48640
	v_add_f32_e32 v82, v82, v37
	v_exp_f32_e32 v40, v40
	v_exp_f32_e32 v41, v41
	v_add_f32_e32 v86, v38, v82
	s_waitcnt lgkmcnt(6)
	v_mfma_f32_32x32x16_bf16 v[18:33], v[134:137], v[66:69], v[18:33]
	ds_read_b128 v[82:85], v182 offset:36864
	v_cvt_pk_bf16_f32 v152, v38, v39
	v_add_f32_e32 v90, v86, v39
	v_exp_f32_e32 v42, v42
	v_exp_f32_e32 v43, v43
	s_waitcnt lgkmcnt(5)
	v_mfma_f32_32x32x16_bf16 v[18:33], v[130:133], v[70:73], v[18:33]
	ds_read_b128 v[86:89], v182 offset:40960
	v_add_f32_e32 v66, v90, v40
	v_exp_f32_e32 v44, v44
	v_cvt_pk_bf16_f32 v153, v40, v41
	v_add_f32_e32 v66, v41, v66
	s_waitcnt lgkmcnt(4)
	v_mfma_f32_32x32x16_bf16 v[18:33], v[126:129], v[74:77], v[18:33]
	ds_read_b128 v[154:157], v183 offset:36864
	v_add_f32_e32 v66, v66, v42
	v_exp_f32_e32 v45, v45
	v_cvt_pk_bf16_f32 v146, v42, v43
	v_add_f32_e32 v66, v43, v66
	s_waitcnt lgkmcnt(3)
	v_mfma_f32_32x32x16_bf16 v[18:33], v[122:125], v[78:81], v[18:33]
	ds_read_b128 v[162:165], v183 offset:40960
	v_exp_f32_e32 v46, v46
	v_exp_f32_e32 v47, v47
	v_add_f32_e32 v66, v66, v44
	v_cvt_pk_bf16_f32 v147, v44, v45
	s_nop 0
	v_add_f32_e32 v66, v66, v45
	v_add_f32_e32 v91, v46, v66
	s_waitcnt lgkmcnt(3)
	v_mfma_f32_32x32x16_bf16 v[66:81], v[82:85], v[98:101], 0
	ds_read_b128 v[166:169], v184 offset:36864
	v_exp_f32_e32 v48, v48
	v_exp_f32_e32 v49, v49
	ds_read_b128 v[158:161], v184 offset:40960
	v_add_f32_e32 v193, v91, v47
	s_waitcnt lgkmcnt(4)
	v_mfma_f32_32x32x16_bf16 v[82:97], v[86:89], v[98:101], 0
	v_exp_f32_e32 v50, v50
	v_exp_f32_e32 v51, v51
	v_cvt_pk_bf16_f32 v148, v46, v47
	s_add_u32 s26, s20, 0xfffe0000
	s_addc_u32 s27, s21, -1
	s_add_i32 s31, 0x6000, s8
	s_add_i32 s33, 0x4000, s12
	s_add_u32 s28, s22, 0xfffff000
	s_addc_u32 s29, s23, -1
	s_add_i32 s40, s31, 0x2000
	s_mov_b32 m0, s31
	s_nop 0
	global_load_lds_dwordx4 v174, s[26:27]
	s_mov_b32 m0, s40
	s_nop 0
	global_load_lds_dwordx4 v192, s[28:29]
	s_mov_b32 m0, s33
	s_nop 0
	global_load_lds_dwordx4 v191, s[26:27]
	s_mov_b32 m0, s41
	s_waitcnt lgkmcnt(3)
	v_mfma_f32_32x32x16_bf16 v[66:81], v[154:157], v[102:105], v[66:81]
	ds_read_b128 v[194:197], v185 offset:36864
	v_add_f32_e32 v193, v193, v48
	v_cvt_pk_bf16_f32 v149, v48, v49
	v_add_f32_e32 v193, v49, v193
	v_exp_f32_e32 v52, v52
	s_waitcnt lgkmcnt(3)
	v_mfma_f32_32x32x16_bf16 v[82:97], v[162:165], v[102:105], v[82:97]
	ds_read_b128 v[154:157], v185 offset:40960
	v_add_f32_e32 v193, v193, v50
	v_exp_f32_e32 v53, v53
	v_cvt_pk_bf16_f32 v142, v50, v51
	v_add_f32_e32 v193, v51, v193
	s_waitcnt lgkmcnt(3)
	v_mfma_f32_32x32x16_bf16 v[66:81], v[166:169], v[106:109], v[66:81]
	ds_read_b128 v[162:165], v187 offset:45056
	v_exp_f32_e32 v54, v54
	v_exp_f32_e32 v55, v55
	v_add_f32_e32 v193, v193, v52
	v_cvt_pk_bf16_f32 v143, v52, v53
	s_waitcnt lgkmcnt(3)
	v_mfma_f32_32x32x16_bf16 v[82:97], v[158:161], v[106:109], v[82:97]
	ds_read_b128 v[198:201], v187 offset:47104
	v_add_f32_e32 v166, v193, v53
	v_exp_f32_e32 v56, v56
	v_exp_f32_e32 v57, v57
	v_add_f32_e32 v166, v54, v166
	s_waitcnt lgkmcnt(3)
	v_mfma_f32_32x32x16_bf16 v[66:81], v[194:197], v[110:113], v[66:81]
	ds_read_b128 v[202:205], v188 offset:45056
	v_cvt_pk_bf16_f32 v144, v54, v55
	v_add_f32_e32 v159, v166, v55
	v_exp_f32_e32 v58, v58
	v_exp_f32_e32 v59, v59
	s_waitcnt lgkmcnt(3)
	v_mfma_f32_32x32x16_bf16 v[82:97], v[154:157], v[110:113], v[82:97]
	ds_read_b128 v[194:197], v188 offset:47104
	v_add_f32_e32 v158, v159, v56
	v_exp_f32_e32 v60, v60
	v_cvt_pk_bf16_f32 v145, v56, v57
	v_add_f32_e32 v158, v57, v158
	s_waitcnt lgkmcnt(3)
	v_mfma_f32_32x32x16_bf16 v[66:81], v[162:165], v[114:117], v[66:81]
	ds_read_b64_tr_b16 v[166:167], v189 offset:49152
	ds_read_b64_tr_b16 v[168:169], v189 offset:49664
	v_add_f32_e32 v154, v158, v58
	v_exp_f32_e32 v61, v61
	v_cvt_pk_bf16_f32 v138, v58, v59
	v_add_f32_e32 v154, v59, v154
	s_waitcnt lgkmcnt(4)
	v_mfma_f32_32x32x16_bf16 v[82:97], v[198:201], v[114:117], v[82:97]
	ds_read_b64_tr_b16 v[162:163], v189 offset:50176
	ds_read_b64_tr_b16 v[164:165], v189 offset:50688
	v_exp_f32_e32 v62, v62
	v_exp_f32_e32 v63, v63
	v_add_f32_e32 v154, v154, v60
	v_cvt_pk_bf16_f32 v139, v60, v61
	s_waitcnt lgkmcnt(5)
	v_mfma_f32_32x32x16_bf16 v[66:81], v[202:205], v[118:121], v[66:81]
	ds_read_b64_tr_b16 v[158:159], v189 offset:51200
	ds_read_b64_tr_b16 v[160:161], v189 offset:51712
	v_add_f32_e32 v154, v154, v61
	v_exp_f32_e32 v64, v64
	v_exp_f32_e32 v65, v65
	v_add_f32_e32 v198, v62, v154
	s_waitcnt lgkmcnt(6)
	v_mfma_f32_32x32x16_bf16 v[82:97], v[194:197], v[118:121], v[82:97]
	ds_read_b64_tr_b16 v[154:155], v189 offset:52224
	ds_read_b64_tr_b16 v[156:157], v189 offset:52736
	v_add_f32_e32 v141, v198, v63
	v_add_f32_e32 v198, v64, v141
	v_cvt_pk_bf16_f32 v140, v62, v63
	v_cvt_pk_bf16_f32 v141, v64, v65
	v_add_f32_e32 v194, v65, v198
	s_waitcnt vmcnt(6) lgkmcnt(0)
	s_barrier
	v_mfma_f32_32x32x16_bf16 v[2:17], v[150:153], v[166:169], v[2:17]
	ds_read_b64_tr_b16 v[34:35], v189 offset:53248
	ds_read_b64_tr_b16 v[36:37], v189 offset:53760
	v_exp_f32_e32 v66, v66
	v_exp_f32_e32 v67, v67
	v_exp_f32_e32 v68, v68
	v_mfma_f32_32x32x16_bf16 v[2:17], v[146:149], v[162:165], v[2:17]
	ds_read_b64_tr_b16 v[38:39], v189 offset:54272
	ds_read_b64_tr_b16 v[40:41], v189 offset:54784
	v_add_f32_e32 v42, v194, v66
	v_exp_f32_e32 v69, v69
	v_cvt_pk_bf16_f32 v134, v66, v67
	v_add_f32_e32 v46, v67, v42
	v_mfma_f32_32x32x16_bf16 v[2:17], v[142:145], v[158:161], v[2:17]
	ds_read_b64_tr_b16 v[42:43], v189 offset:55296
	ds_read_b64_tr_b16 v[44:45], v189 offset:55808
	v_exp_f32_e32 v70, v70
	v_exp_f32_e32 v71, v71
	v_add_f32_e32 v50, v46, v68
	v_cvt_pk_bf16_f32 v135, v68, v69
	v_mfma_f32_32x32x16_bf16 v[2:17], v[138:141], v[154:157], v[2:17]
	ds_read_b64_tr_b16 v[46:47], v189 offset:56320
	ds_read_b64_tr_b16 v[48:49], v189 offset:56832
	v_add_f32_e32 v50, v50, v69
	v_exp_f32_e32 v72, v72
	v_exp_f32_e32 v73, v73
	v_add_f32_e32 v54, v70, v50
	s_waitcnt lgkmcnt(6)
	v_mfma_f32_32x32x16_bf16 v[18:33], v[150:153], v[34:37], v[18:33]
	ds_read_b128 v[50:53], v182
	v_cvt_pk_bf16_f32 v136, v70, v71
	v_add_f32_e32 v58, v54, v71
	v_exp_f32_e32 v74, v74
	v_exp_f32_e32 v75, v75
	s_waitcnt lgkmcnt(5)
	v_mfma_f32_32x32x16_bf16 v[18:33], v[146:149], v[38:41], v[18:33]
	ds_read_b128 v[54:57], v182 offset:4096
	v_add_f32_e32 v34, v58, v72
	v_exp_f32_e32 v76, v76
	v_cvt_pk_bf16_f32 v137, v72, v73
	v_add_f32_e32 v34, v73, v34
	s_waitcnt lgkmcnt(4)
	v_mfma_f32_32x32x16_bf16 v[18:33], v[142:145], v[42:45], v[18:33]
	ds_read_b128 v[154:157], v183
	v_add_f32_e32 v34, v34, v74
	v_exp_f32_e32 v77, v77
	v_cvt_pk_bf16_f32 v130, v74, v75
	v_add_f32_e32 v34, v75, v34
	s_waitcnt lgkmcnt(3)
	v_mfma_f32_32x32x16_bf16 v[18:33], v[138:141], v[46:49], v[18:33]
	ds_read_b128 v[162:165], v183 offset:4096
	v_exp_f32_e32 v78, v78
	v_exp_f32_e32 v79, v79
	v_add_f32_e32 v34, v34, v76
	v_cvt_pk_bf16_f32 v131, v76, v77
	s_nop 0
	v_add_f32_e32 v34, v34, v77
	v_add_f32_e32 v59, v78, v34
	s_waitcnt lgkmcnt(3)
	v_mfma_f32_32x32x16_bf16 v[34:49], v[50:53], v[98:101], 0
	ds_read_b128 v[166:169], v184
	v_exp_f32_e32 v80, v80
	v_exp_f32_e32 v81, v81
	ds_read_b128 v[158:161], v184 offset:4096
	v_add_f32_e32 v193, v59, v79
	s_waitcnt lgkmcnt(4)
	v_mfma_f32_32x32x16_bf16 v[50:65], v[54:57], v[98:101], 0
	v_exp_f32_e32 v82, v82
	v_exp_f32_e32 v83, v83
	v_cvt_pk_bf16_f32 v132, v78, v79
	s_add_i32 s26, 0x9000, s8
	s_add_i32 s28, 0x6000, s12
	s_add_i32 s24, s26, 0x2000
	s_mov_b32 m0, s26
	s_nop 0
	global_load_lds_dwordx4 v174, s[20:21]
	s_mov_b32 m0, s24
	s_nop 0
	global_load_lds_dwordx4 v192, s[22:23]
	s_mov_b32 m0, s28
	s_nop 0
	global_load_lds_dwordx4 v191, s[20:21]
	s_mov_b32 m0, s25
	s_waitcnt lgkmcnt(3)
	v_mfma_f32_32x32x16_bf16 v[34:49], v[154:157], v[102:105], v[34:49]
	ds_read_b128 v[194:197], v185
	v_add_f32_e32 v154, v193, v80
	v_exp_f32_e32 v84, v84
	v_cvt_pk_bf16_f32 v133, v80, v81
	v_add_f32_e32 v193, v81, v154
	s_waitcnt lgkmcnt(3)
	v_mfma_f32_32x32x16_bf16 v[50:65], v[162:165], v[102:105], v[50:65]
	ds_read_b128 v[154:157], v185 offset:4096
	v_add_f32_e32 v193, v193, v82
	v_exp_f32_e32 v85, v85
	v_cvt_pk_bf16_f32 v126, v82, v83
	v_add_f32_e32 v193, v83, v193
	s_waitcnt lgkmcnt(3)
	v_mfma_f32_32x32x16_bf16 v[34:49], v[166:169], v[106:109], v[34:49]
	ds_read_b128 v[162:165], v187 offset:8192
	v_exp_f32_e32 v86, v86
	v_exp_f32_e32 v87, v87
	v_add_f32_e32 v193, v193, v84
	v_cvt_pk_bf16_f32 v127, v84, v85
	s_waitcnt lgkmcnt(3)
	v_mfma_f32_32x32x16_bf16 v[50:65], v[158:161], v[106:109], v[50:65]
	ds_read_b128 v[198:201], v187 offset:10240
	v_add_f32_e32 v166, v193, v85
	v_exp_f32_e32 v88, v88
	v_exp_f32_e32 v89, v89
	v_add_f32_e32 v166, v86, v166
	s_waitcnt lgkmcnt(3)
	v_mfma_f32_32x32x16_bf16 v[34:49], v[194:197], v[110:113], v[34:49]
	ds_read_b128 v[202:205], v188 offset:8192
	v_cvt_pk_bf16_f32 v128, v86, v87
	v_add_f32_e32 v159, v166, v87
	v_exp_f32_e32 v90, v90
	v_exp_f32_e32 v91, v91
	s_waitcnt lgkmcnt(3)
	v_mfma_f32_32x32x16_bf16 v[50:65], v[154:157], v[110:113], v[50:65]
	ds_read_b128 v[194:197], v188 offset:10240
	v_add_f32_e32 v158, v159, v88
	v_exp_f32_e32 v92, v92
	v_cvt_pk_bf16_f32 v129, v88, v89
	v_add_f32_e32 v158, v89, v158
	s_waitcnt lgkmcnt(3)
	v_mfma_f32_32x32x16_bf16 v[34:49], v[162:165], v[114:117], v[34:49]
	ds_read_b64_tr_b16 v[166:167], v189 offset:57344
	ds_read_b64_tr_b16 v[168:169], v189 offset:57856
	v_add_f32_e32 v154, v158, v90
	v_exp_f32_e32 v93, v93
	v_cvt_pk_bf16_f32 v122, v90, v91
	v_add_f32_e32 v154, v91, v154
	s_waitcnt lgkmcnt(4)
	v_mfma_f32_32x32x16_bf16 v[50:65], v[198:201], v[114:117], v[50:65]
	ds_read_b64_tr_b16 v[162:163], v189 offset:58368
	ds_read_b64_tr_b16 v[164:165], v189 offset:58880
	v_exp_f32_e32 v94, v94
	v_exp_f32_e32 v95, v95
	v_add_f32_e32 v154, v154, v92
	v_cvt_pk_bf16_f32 v123, v92, v93
	s_waitcnt lgkmcnt(5)
	v_mfma_f32_32x32x16_bf16 v[34:49], v[202:205], v[118:121], v[34:49]
	ds_read_b64_tr_b16 v[158:159], v189 offset:59392
	ds_read_b64_tr_b16 v[160:161], v189 offset:59904
	v_add_f32_e32 v154, v154, v93
	v_exp_f32_e32 v96, v96
	v_exp_f32_e32 v97, v97
	v_add_f32_e32 v193, v94, v154
	s_waitcnt lgkmcnt(6)
	v_mfma_f32_32x32x16_bf16 v[50:65], v[194:197], v[118:121], v[50:65]
	ds_read_b64_tr_b16 v[154:155], v189 offset:60416
	ds_read_b64_tr_b16 v[156:157], v189 offset:60928
	v_add_f32_e32 v125, v193, v95
	v_add_f32_e32 v193, v96, v125
	v_cvt_pk_bf16_f32 v124, v94, v95
	v_cvt_pk_bf16_f32 v125, v96, v97
	v_add_f32_e32 v193, v97, v193
	s_add_u32 s22, s22, 0x2000
	s_addc_u32 s23, s23, 0
	s_add_u32 s20, s20, 0x40000
	s_addc_u32 s21, s21, 0
	s_waitcnt vmcnt(6) lgkmcnt(0)
	s_barrier
	v_mfma_f32_32x32x16_bf16 v[2:17], v[134:137], v[166:169], v[2:17]
	ds_read_b64_tr_b16 v[66:67], v189 offset:61440
	ds_read_b64_tr_b16 v[68:69], v189 offset:61952
	v_exp_f32_e32 v34, v34
	v_exp_f32_e32 v35, v35
	v_exp_f32_e32 v36, v36
	v_mfma_f32_32x32x16_bf16 v[2:17], v[130:133], v[162:165], v[2:17]
	ds_read_b64_tr_b16 v[70:71], v189 offset:62464
	ds_read_b64_tr_b16 v[72:73], v189 offset:62976
	v_add_f32_e32 v74, v193, v34
	v_exp_f32_e32 v37, v37
	v_cvt_pk_bf16_f32 v150, v34, v35
	v_add_f32_e32 v78, v35, v74
	v_mfma_f32_32x32x16_bf16 v[2:17], v[126:129], v[158:161], v[2:17]
	ds_read_b64_tr_b16 v[74:75], v189 offset:63488
	ds_read_b64_tr_b16 v[76:77], v189 offset:64000
	v_exp_f32_e32 v38, v38
	v_exp_f32_e32 v39, v39
	v_add_f32_e32 v82, v78, v36
	v_cvt_pk_bf16_f32 v151, v36, v37
	v_mfma_f32_32x32x16_bf16 v[2:17], v[122:125], v[154:157], v[2:17]
	ds_read_b64_tr_b16 v[78:79], v189 offset:64512
	ds_read_b64_tr_b16 v[80:81], v189 offset:65024
	v_add_f32_e32 v82, v82, v37
	v_exp_f32_e32 v40, v40
	v_exp_f32_e32 v41, v41
	v_add_f32_e32 v86, v38, v82
	s_waitcnt lgkmcnt(6)
	v_mfma_f32_32x32x16_bf16 v[18:33], v[134:137], v[66:69], v[18:33]
	ds_read_b128 v[82:85], v182 offset:12288
	v_cvt_pk_bf16_f32 v152, v38, v39
	v_add_f32_e32 v90, v86, v39
	v_exp_f32_e32 v42, v42
	v_exp_f32_e32 v43, v43
	s_waitcnt lgkmcnt(5)
	v_mfma_f32_32x32x16_bf16 v[18:33], v[130:133], v[70:73], v[18:33]
	ds_read_b128 v[86:89], v182 offset:16384
	v_add_f32_e32 v66, v90, v40
	v_exp_f32_e32 v44, v44
	v_cvt_pk_bf16_f32 v153, v40, v41
	v_add_f32_e32 v66, v41, v66
	s_waitcnt lgkmcnt(4)
	v_mfma_f32_32x32x16_bf16 v[18:33], v[126:129], v[74:77], v[18:33]
	ds_read_b128 v[154:157], v183 offset:12288
	v_add_f32_e32 v66, v66, v42
	v_exp_f32_e32 v45, v45
	v_cvt_pk_bf16_f32 v146, v42, v43
	v_add_f32_e32 v66, v43, v66
	s_waitcnt lgkmcnt(3)
	v_mfma_f32_32x32x16_bf16 v[18:33], v[122:125], v[78:81], v[18:33]
	ds_read_b128 v[162:165], v183 offset:16384
	v_exp_f32_e32 v46, v46
	v_exp_f32_e32 v47, v47
	v_add_f32_e32 v66, v66, v44
	v_cvt_pk_bf16_f32 v147, v44, v45
	s_nop 0
	v_add_f32_e32 v66, v66, v45
	v_add_f32_e32 v91, v46, v66
	s_waitcnt lgkmcnt(3)
	v_mfma_f32_32x32x16_bf16 v[66:81], v[82:85], v[98:101], 0
	ds_read_b128 v[166:169], v184 offset:12288
	v_exp_f32_e32 v48, v48
	v_exp_f32_e32 v49, v49
	ds_read_b128 v[158:161], v184 offset:16384
	v_add_f32_e32 v193, v91, v47
	s_waitcnt lgkmcnt(4)
	v_mfma_f32_32x32x16_bf16 v[82:97], v[86:89], v[98:101], 0
	v_exp_f32_e32 v50, v50
	v_exp_f32_e32 v51, v51
	v_cvt_pk_bf16_f32 v148, v46, v47
	s_add_u32 s26, s20, 0xfffe0000
	s_addc_u32 s27, s21, -1
	s_add_i32 s31, 0, s8
	s_add_i32 s33, 0x8000, s12
	s_add_u32 s28, s22, 0xfffff000
	s_addc_u32 s29, s23, -1
	s_add_i32 s40, s31, 0x2000
	s_mov_b32 m0, s31
	s_nop 0
	global_load_lds_dwordx4 v174, s[26:27]
	s_mov_b32 m0, s40
	s_nop 0
	global_load_lds_dwordx4 v192, s[28:29]
	s_mov_b32 m0, s33
	s_nop 0
	global_load_lds_dwordx4 v191, s[26:27]
	s_mov_b32 m0, s41
	s_waitcnt lgkmcnt(3)
	v_mfma_f32_32x32x16_bf16 v[66:81], v[154:157], v[102:105], v[66:81]
	ds_read_b128 v[194:197], v185 offset:12288
	v_add_f32_e32 v193, v193, v48
	v_cvt_pk_bf16_f32 v149, v48, v49
	v_add_f32_e32 v193, v49, v193
	v_exp_f32_e32 v52, v52
	s_waitcnt lgkmcnt(3)
	v_mfma_f32_32x32x16_bf16 v[82:97], v[162:165], v[102:105], v[82:97]
	ds_read_b128 v[154:157], v185 offset:16384
	v_add_f32_e32 v193, v193, v50
	v_exp_f32_e32 v53, v53
	v_cvt_pk_bf16_f32 v142, v50, v51
	v_add_f32_e32 v193, v51, v193
	s_waitcnt lgkmcnt(3)
	v_mfma_f32_32x32x16_bf16 v[66:81], v[166:169], v[106:109], v[66:81]
	ds_read_b128 v[162:165], v187 offset:20480
	v_exp_f32_e32 v54, v54
	v_exp_f32_e32 v55, v55
	v_add_f32_e32 v193, v193, v52
	v_cvt_pk_bf16_f32 v143, v52, v53
	s_waitcnt lgkmcnt(3)
	v_mfma_f32_32x32x16_bf16 v[82:97], v[158:161], v[106:109], v[82:97]
	ds_read_b128 v[198:201], v187 offset:22528
	v_add_f32_e32 v166, v193, v53
	v_exp_f32_e32 v56, v56
	v_exp_f32_e32 v57, v57
	v_add_f32_e32 v166, v54, v166
	s_waitcnt lgkmcnt(3)
	v_mfma_f32_32x32x16_bf16 v[66:81], v[194:197], v[110:113], v[66:81]
	ds_read_b128 v[202:205], v188 offset:20480
	v_cvt_pk_bf16_f32 v144, v54, v55
	v_add_f32_e32 v159, v166, v55
	v_exp_f32_e32 v58, v58
	v_exp_f32_e32 v59, v59
	s_waitcnt lgkmcnt(3)
	v_mfma_f32_32x32x16_bf16 v[82:97], v[154:157], v[110:113], v[82:97]
	ds_read_b128 v[194:197], v188 offset:22528
	v_add_f32_e32 v158, v159, v56
	v_exp_f32_e32 v60, v60
	v_cvt_pk_bf16_f32 v145, v56, v57
	v_add_f32_e32 v158, v57, v158
	s_waitcnt lgkmcnt(3)
	v_mfma_f32_32x32x16_bf16 v[66:81], v[162:165], v[114:117], v[66:81]
	ds_read_b64_tr_b16 v[166:167], v189 offset:16384
	ds_read_b64_tr_b16 v[168:169], v189 offset:16896
	v_add_f32_e32 v154, v158, v58
	v_exp_f32_e32 v61, v61
	v_cvt_pk_bf16_f32 v138, v58, v59
	v_add_f32_e32 v154, v59, v154
	s_waitcnt lgkmcnt(4)
	v_mfma_f32_32x32x16_bf16 v[82:97], v[198:201], v[114:117], v[82:97]
	ds_read_b64_tr_b16 v[162:163], v189 offset:17408
	ds_read_b64_tr_b16 v[164:165], v189 offset:17920
	v_exp_f32_e32 v62, v62
	v_exp_f32_e32 v63, v63
	v_add_f32_e32 v154, v154, v60
	v_cvt_pk_bf16_f32 v139, v60, v61
	s_waitcnt lgkmcnt(5)
	v_mfma_f32_32x32x16_bf16 v[66:81], v[202:205], v[118:121], v[66:81]
	ds_read_b64_tr_b16 v[158:159], v189 offset:18432
	ds_read_b64_tr_b16 v[160:161], v189 offset:18944
	v_add_f32_e32 v154, v154, v61
	v_exp_f32_e32 v64, v64
	v_exp_f32_e32 v65, v65
	v_add_f32_e32 v198, v62, v154
	s_waitcnt lgkmcnt(6)
	v_mfma_f32_32x32x16_bf16 v[82:97], v[194:197], v[118:121], v[82:97]
	ds_read_b64_tr_b16 v[154:155], v189 offset:19456
	ds_read_b64_tr_b16 v[156:157], v189 offset:19968
	v_add_f32_e32 v141, v198, v63
	v_add_f32_e32 v198, v64, v141
	v_cvt_pk_bf16_f32 v140, v62, v63
	v_cvt_pk_bf16_f32 v141, v64, v65
	v_add_f32_e32 v194, v65, v198
	s_waitcnt vmcnt(6) lgkmcnt(0)
	s_barrier
	v_mfma_f32_32x32x16_bf16 v[2:17], v[150:153], v[166:169], v[2:17]
	ds_read_b64_tr_b16 v[34:35], v189 offset:20480
	ds_read_b64_tr_b16 v[36:37], v189 offset:20992
	v_exp_f32_e32 v66, v66
	v_exp_f32_e32 v67, v67
	v_exp_f32_e32 v68, v68
	v_mfma_f32_32x32x16_bf16 v[2:17], v[146:149], v[162:165], v[2:17]
	ds_read_b64_tr_b16 v[38:39], v189 offset:21504
	ds_read_b64_tr_b16 v[40:41], v189 offset:22016
	v_add_f32_e32 v42, v194, v66
	v_exp_f32_e32 v69, v69
	v_cvt_pk_bf16_f32 v134, v66, v67
	v_add_f32_e32 v46, v67, v42
	v_mfma_f32_32x32x16_bf16 v[2:17], v[142:145], v[158:161], v[2:17]
	ds_read_b64_tr_b16 v[42:43], v189 offset:22528
	ds_read_b64_tr_b16 v[44:45], v189 offset:23040
	v_exp_f32_e32 v70, v70
	v_exp_f32_e32 v71, v71
	v_add_f32_e32 v50, v46, v68
	v_cvt_pk_bf16_f32 v135, v68, v69
	v_mfma_f32_32x32x16_bf16 v[2:17], v[138:141], v[154:157], v[2:17]
	ds_read_b64_tr_b16 v[46:47], v189 offset:23552
	ds_read_b64_tr_b16 v[48:49], v189 offset:24064
	v_add_f32_e32 v50, v50, v69
	v_exp_f32_e32 v72, v72
	v_exp_f32_e32 v73, v73
	v_add_f32_e32 v54, v70, v50
	s_waitcnt lgkmcnt(6)
	v_mfma_f32_32x32x16_bf16 v[18:33], v[150:153], v[34:37], v[18:33]
	ds_read_b128 v[50:53], v182 offset:24576
	v_cvt_pk_bf16_f32 v136, v70, v71
	v_add_f32_e32 v58, v54, v71
	v_exp_f32_e32 v74, v74
	v_exp_f32_e32 v75, v75
	s_waitcnt lgkmcnt(5)
	v_mfma_f32_32x32x16_bf16 v[18:33], v[146:149], v[38:41], v[18:33]
	ds_read_b128 v[54:57], v182 offset:28672
	v_add_f32_e32 v34, v58, v72
	v_exp_f32_e32 v76, v76
	v_cvt_pk_bf16_f32 v137, v72, v73
	v_add_f32_e32 v34, v73, v34
	s_waitcnt lgkmcnt(4)
	v_mfma_f32_32x32x16_bf16 v[18:33], v[142:145], v[42:45], v[18:33]
	ds_read_b128 v[154:157], v183 offset:24576
	v_add_f32_e32 v34, v34, v74
	v_exp_f32_e32 v77, v77
	v_cvt_pk_bf16_f32 v130, v74, v75
	v_add_f32_e32 v34, v75, v34
	s_waitcnt lgkmcnt(3)
	v_mfma_f32_32x32x16_bf16 v[18:33], v[138:141], v[46:49], v[18:33]
	ds_read_b128 v[162:165], v183 offset:28672
	v_exp_f32_e32 v78, v78
	v_exp_f32_e32 v79, v79
	v_add_f32_e32 v34, v34, v76
	v_cvt_pk_bf16_f32 v131, v76, v77
	s_nop 0
	v_add_f32_e32 v34, v34, v77
	v_add_f32_e32 v59, v78, v34
	s_waitcnt lgkmcnt(3)
	v_mfma_f32_32x32x16_bf16 v[34:49], v[50:53], v[98:101], 0
	ds_read_b128 v[166:169], v184 offset:24576
	v_exp_f32_e32 v80, v80
	v_exp_f32_e32 v81, v81
	ds_read_b128 v[158:161], v184 offset:28672
	v_add_f32_e32 v193, v59, v79
	s_waitcnt lgkmcnt(4)
	v_mfma_f32_32x32x16_bf16 v[50:65], v[54:57], v[98:101], 0
	v_exp_f32_e32 v82, v82
	v_exp_f32_e32 v83, v83
	v_cvt_pk_bf16_f32 v132, v78, v79
	s_add_i32 s26, 0x3000, s8
	s_add_i32 s28, 0xa000, s12
	s_add_i32 s24, s26, 0x2000
	s_mov_b32 m0, s26
	s_nop 0
	global_load_lds_dwordx4 v174, s[20:21]
	s_mov_b32 m0, s24
	s_nop 0
	global_load_lds_dwordx4 v192, s[22:23]
	s_mov_b32 m0, s28
	s_nop 0
	global_load_lds_dwordx4 v191, s[20:21]
	s_mov_b32 m0, s25
	s_waitcnt lgkmcnt(3)
	v_mfma_f32_32x32x16_bf16 v[34:49], v[154:157], v[102:105], v[34:49]
	ds_read_b128 v[194:197], v185 offset:24576
	v_add_f32_e32 v154, v193, v80
	v_exp_f32_e32 v84, v84
	v_cvt_pk_bf16_f32 v133, v80, v81
	v_add_f32_e32 v193, v81, v154
	s_waitcnt lgkmcnt(3)
	v_mfma_f32_32x32x16_bf16 v[50:65], v[162:165], v[102:105], v[50:65]
	ds_read_b128 v[154:157], v185 offset:28672
	v_add_f32_e32 v193, v193, v82
	v_exp_f32_e32 v85, v85
	v_cvt_pk_bf16_f32 v126, v82, v83
	v_add_f32_e32 v193, v83, v193
	s_waitcnt lgkmcnt(3)
	v_mfma_f32_32x32x16_bf16 v[34:49], v[166:169], v[106:109], v[34:49]
	ds_read_b128 v[162:165], v187 offset:32768
	v_exp_f32_e32 v86, v86
	v_exp_f32_e32 v87, v87
	v_add_f32_e32 v193, v193, v84
	v_cvt_pk_bf16_f32 v127, v84, v85
	s_waitcnt lgkmcnt(3)
	v_mfma_f32_32x32x16_bf16 v[50:65], v[158:161], v[106:109], v[50:65]
	ds_read_b128 v[198:201], v187 offset:34816
	v_add_f32_e32 v166, v193, v85
	v_exp_f32_e32 v88, v88
	v_exp_f32_e32 v89, v89
	v_add_f32_e32 v166, v86, v166
	s_waitcnt lgkmcnt(3)
	v_mfma_f32_32x32x16_bf16 v[34:49], v[194:197], v[110:113], v[34:49]
	ds_read_b128 v[202:205], v188 offset:32768
	v_cvt_pk_bf16_f32 v128, v86, v87
	v_add_f32_e32 v159, v166, v87
	v_exp_f32_e32 v90, v90
	v_exp_f32_e32 v91, v91
	s_waitcnt lgkmcnt(3)
	v_mfma_f32_32x32x16_bf16 v[50:65], v[154:157], v[110:113], v[50:65]
	ds_read_b128 v[194:197], v188 offset:34816
	v_add_f32_e32 v158, v159, v88
	v_exp_f32_e32 v92, v92
	v_cvt_pk_bf16_f32 v129, v88, v89
	v_add_f32_e32 v158, v89, v158
	s_waitcnt lgkmcnt(3)
	v_mfma_f32_32x32x16_bf16 v[34:49], v[162:165], v[114:117], v[34:49]
	ds_read_b64_tr_b16 v[166:167], v189 offset:24576
	ds_read_b64_tr_b16 v[168:169], v189 offset:25088
	v_add_f32_e32 v154, v158, v90
	v_exp_f32_e32 v93, v93
	v_cvt_pk_bf16_f32 v122, v90, v91
	v_add_f32_e32 v154, v91, v154
	s_waitcnt lgkmcnt(4)
	v_mfma_f32_32x32x16_bf16 v[50:65], v[198:201], v[114:117], v[50:65]
	ds_read_b64_tr_b16 v[162:163], v189 offset:25600
	ds_read_b64_tr_b16 v[164:165], v189 offset:26112
	v_exp_f32_e32 v94, v94
	v_exp_f32_e32 v95, v95
	v_add_f32_e32 v154, v154, v92
	v_cvt_pk_bf16_f32 v123, v92, v93
	s_waitcnt lgkmcnt(5)
	v_mfma_f32_32x32x16_bf16 v[34:49], v[202:205], v[118:121], v[34:49]
	ds_read_b64_tr_b16 v[158:159], v189 offset:26624
	ds_read_b64_tr_b16 v[160:161], v189 offset:27136
	v_add_f32_e32 v154, v154, v93
	v_exp_f32_e32 v96, v96
	v_exp_f32_e32 v97, v97
	v_add_f32_e32 v193, v94, v154
	s_waitcnt lgkmcnt(6)
	v_mfma_f32_32x32x16_bf16 v[50:65], v[194:197], v[118:121], v[50:65]
	ds_read_b64_tr_b16 v[154:155], v189 offset:27648
	ds_read_b64_tr_b16 v[156:157], v189 offset:28160
	v_add_f32_e32 v125, v193, v95
	v_add_f32_e32 v193, v96, v125
	v_cvt_pk_bf16_f32 v124, v94, v95
	v_cvt_pk_bf16_f32 v125, v96, v97
	v_add_f32_e32 v193, v97, v193
	s_add_u32 s22, s22, 0x2000
	s_addc_u32 s23, s23, 0
	s_add_u32 s20, s20, 0x40000
	s_addc_u32 s21, s21, 0
	s_add_i32 s13, s13, 12
	s_cmp_le_i32 s13, 108
	s_cbranch_scc1 .Lmla_fast_w03
	v_subrev_u32_e32 v189, 0x8000, v189
	s_mov_b32 s2, 0x4000
	s_mov_b32 s17, 0x6000
	s_mov_b32 s26, 0x2000
	s_mov_b32 s14, 0x0
	s_mov_b32 s15, 0x9000
	s_branch .LBB0_1278
.Lmla_fast_w47:
	s_waitcnt vmcnt(4) lgkmcnt(0)
	s_barrier
	v_mfma_f32_32x32x16_bf16 v[2:17], v[134:137], v[166:169], v[2:17]
	ds_read_b64_tr_b16 v[66:67], v189 offset:28672
	ds_read_b64_tr_b16 v[68:69], v189 offset:29184
	v_exp_f32_e32 v34, v34
	v_exp_f32_e32 v35, v35
	v_exp_f32_e32 v36, v36
	v_mfma_f32_32x32x16_bf16 v[2:17], v[130:133], v[162:165], v[2:17]
	ds_read_b64_tr_b16 v[70:71], v189 offset:29696
	ds_read_b64_tr_b16 v[72:73], v189 offset:30208
	v_add_f32_e32 v74, v193, v34
	v_exp_f32_e32 v37, v37
	v_cvt_pk_bf16_f32 v150, v34, v35
	v_add_f32_e32 v78, v35, v74
	v_mfma_f32_32x32x16_bf16 v[2:17], v[126:129], v[158:161], v[2:17]
	ds_read_b64_tr_b16 v[74:75], v189 offset:30720
	ds_read_b64_tr_b16 v[76:77], v189 offset:31232
	v_exp_f32_e32 v38, v38
	v_exp_f32_e32 v39, v39
	v_add_f32_e32 v82, v78, v36
	v_cvt_pk_bf16_f32 v151, v36, v37
	v_mfma_f32_32x32x16_bf16 v[2:17], v[122:125], v[154:157], v[2:17]
	ds_read_b64_tr_b16 v[78:79], v189 offset:31744
	ds_read_b64_tr_b16 v[80:81], v189 offset:32256
	v_add_f32_e32 v82, v82, v37
	v_exp_f32_e32 v40, v40
	v_exp_f32_e32 v41, v41
	v_add_f32_e32 v86, v38, v82
	s_waitcnt lgkmcnt(6)
	v_mfma_f32_32x32x16_bf16 v[18:33], v[134:137], v[66:69], v[18:33]
	ds_read_b128 v[82:85], v182 offset:36864
	v_cvt_pk_bf16_f32 v152, v38, v39
	v_add_f32_e32 v90, v86, v39
	v_exp_f32_e32 v42, v42
	v_exp_f32_e32 v43, v43
	s_waitcnt lgkmcnt(5)
	v_mfma_f32_32x32x16_bf16 v[18:33], v[130:133], v[70:73], v[18:33]
	ds_read_b128 v[86:89], v182 offset:40960
	v_add_f32_e32 v66, v90, v40
	v_exp_f32_e32 v44, v44
	v_cvt_pk_bf16_f32 v153, v40, v41
	v_add_f32_e32 v66, v41, v66
	s_waitcnt lgkmcnt(4)
	v_mfma_f32_32x32x16_bf16 v[18:33], v[126:129], v[74:77], v[18:33]
	ds_read_b128 v[154:157], v183 offset:36864
	v_add_f32_e32 v66, v66, v42
	v_exp_f32_e32 v45, v45
	v_cvt_pk_bf16_f32 v146, v42, v43
	v_add_f32_e32 v66, v43, v66
	s_waitcnt lgkmcnt(3)
	v_mfma_f32_32x32x16_bf16 v[18:33], v[122:125], v[78:81], v[18:33]
	ds_read_b128 v[162:165], v183 offset:40960
	v_exp_f32_e32 v46, v46
	v_exp_f32_e32 v47, v47
	v_add_f32_e32 v66, v66, v44
	v_cvt_pk_bf16_f32 v147, v44, v45
	s_nop 0
	v_add_f32_e32 v66, v66, v45
	v_add_f32_e32 v91, v46, v66
	s_waitcnt lgkmcnt(3)
	v_mfma_f32_32x32x16_bf16 v[66:81], v[82:85], v[98:101], 0
	ds_read_b128 v[166:169], v184 offset:36864
	v_exp_f32_e32 v48, v48
	v_exp_f32_e32 v49, v49
	ds_read_b128 v[158:161], v184 offset:40960
	v_add_f32_e32 v193, v91, v47
	s_waitcnt lgkmcnt(4)
	v_mfma_f32_32x32x16_bf16 v[82:97], v[86:89], v[98:101], 0
	v_exp_f32_e32 v50, v50
	v_exp_f32_e32 v51, v51
	v_cvt_pk_bf16_f32 v148, v46, v47
	s_add_u32 s26, s20, 0xfffe0000
	s_addc_u32 s27, s21, -1
	s_add_i32 s31, 0x6000, s8
	s_add_i32 s33, 0, s12
	s_mov_b32 m0, s31
	s_nop 0
	global_load_lds_dwordx4 v174, s[26:27]
	s_mov_b32 m0, s33
	s_nop 0
	global_load_lds_dwordx4 v191, s[26:27]
	s_mov_b32 m0, s28
	s_waitcnt lgkmcnt(3)
	v_mfma_f32_32x32x16_bf16 v[66:81], v[154:157], v[102:105], v[66:81]
	ds_read_b128 v[194:197], v185 offset:36864
	v_add_f32_e32 v193, v193, v48
	v_cvt_pk_bf16_f32 v149, v48, v49
	v_add_f32_e32 v193, v49, v193
	v_exp_f32_e32 v52, v52
	s_waitcnt lgkmcnt(3)
	v_mfma_f32_32x32x16_bf16 v[82:97], v[162:165], v[102:105], v[82:97]
	ds_read_b128 v[154:157], v185 offset:40960
	v_add_f32_e32 v193, v193, v50
	v_exp_f32_e32 v53, v53
	v_cvt_pk_bf16_f32 v142, v50, v51
	v_add_f32_e32 v193, v51, v193
	s_waitcnt lgkmcnt(3)
	v_mfma_f32_32x32x16_bf16 v[66:81], v[166:169], v[106:109], v[66:81]
	ds_read_b128 v[162:165], v187 offset:45056
	v_exp_f32_e32 v54, v54
	v_exp_f32_e32 v55, v55
	v_add_f32_e32 v193, v193, v52
	v_cvt_pk_bf16_f32 v143, v52, v53
	s_waitcnt lgkmcnt(3)
	v_mfma_f32_32x32x16_bf16 v[82:97], v[158:161], v[106:109], v[82:97]
	ds_read_b128 v[198:201], v187 offset:47104
	v_add_f32_e32 v166, v193, v53
	v_exp_f32_e32 v56, v56
	v_exp_f32_e32 v57, v57
	v_add_f32_e32 v166, v54, v166
	s_waitcnt lgkmcnt(3)
	v_mfma_f32_32x32x16_bf16 v[66:81], v[194:197], v[110:113], v[66:81]
	ds_read_b128 v[202:205], v188 offset:45056
	v_cvt_pk_bf16_f32 v144, v54, v55
	v_add_f32_e32 v159, v166, v55
	v_exp_f32_e32 v58, v58
	v_exp_f32_e32 v59, v59
	s_waitcnt lgkmcnt(3)
	v_mfma_f32_32x32x16_bf16 v[82:97], v[154:157], v[110:113], v[82:97]
	ds_read_b128 v[194:197], v188 offset:47104
	v_add_f32_e32 v158, v159, v56
	v_exp_f32_e32 v60, v60
	v_cvt_pk_bf16_f32 v145, v56, v57
	v_add_f32_e32 v158, v57, v158
	s_waitcnt lgkmcnt(3)
	v_mfma_f32_32x32x16_bf16 v[66:81], v[162:165], v[114:117], v[66:81]
	ds_read_b64_tr_b16 v[166:167], v189 offset:32768
	ds_read_b64_tr_b16 v[168:169], v189 offset:33280
	v_add_f32_e32 v154, v158, v58
	v_exp_f32_e32 v61, v61
	v_cvt_pk_bf16_f32 v138, v58, v59
	v_add_f32_e32 v154, v59, v154
	s_waitcnt lgkmcnt(4)
	v_mfma_f32_32x32x16_bf16 v[82:97], v[198:201], v[114:117], v[82:97]
	ds_read_b64_tr_b16 v[162:163], v189 offset:33792
	ds_read_b64_tr_b16 v[164:165], v189 offset:34304
	v_exp_f32_e32 v62, v62
	v_exp_f32_e32 v63, v63
	v_add_f32_e32 v154, v154, v60
	v_cvt_pk_bf16_f32 v139, v60, v61
	s_waitcnt lgkmcnt(5)
	v_mfma_f32_32x32x16_bf16 v[66:81], v[202:205], v[118:121], v[66:81]
	ds_read_b64_tr_b16 v[158:159], v189 offset:34816
	ds_read_b64_tr_b16 v[160:161], v189 offset:35328
	v_add_f32_e32 v154, v154, v61
	v_exp_f32_e32 v64, v64
	v_exp_f32_e32 v65, v65
	v_add_f32_e32 v198, v62, v154
	s_waitcnt lgkmcnt(6)
	v_mfma_f32_32x32x16_bf16 v[82:97], v[194:197], v[118:121], v[82:97]
	ds_read_b64_tr_b16 v[154:155], v189 offset:35840
	ds_read_b64_tr_b16 v[156:157], v189 offset:36352
	v_add_f32_e32 v141, v198, v63
	v_add_f32_e32 v198, v64, v141
	v_cvt_pk_bf16_f32 v140, v62, v63
	v_cvt_pk_bf16_f32 v141, v64, v65
	v_add_f32_e32 v194, v65, v198
	s_waitcnt vmcnt(4) lgkmcnt(0)
	s_barrier
	v_mfma_f32_32x32x16_bf16 v[2:17], v[150:153], v[166:169], v[2:17]
	ds_read_b64_tr_b16 v[34:35], v189 offset:36864
	ds_read_b64_tr_b16 v[36:37], v189 offset:37376
	v_exp_f32_e32 v66, v66
	v_exp_f32_e32 v67, v67
	v_exp_f32_e32 v68, v68
	v_mfma_f32_32x32x16_bf16 v[2:17], v[146:149], v[162:165], v[2:17]
	ds_read_b64_tr_b16 v[38:39], v189 offset:37888
	ds_read_b64_tr_b16 v[40:41], v189 offset:38400
	v_add_f32_e32 v42, v194, v66
	v_exp_f32_e32 v69, v69
	v_cvt_pk_bf16_f32 v134, v66, v67
	v_add_f32_e32 v46, v67, v42
	v_mfma_f32_32x32x16_bf16 v[2:17], v[142:145], v[158:161], v[2:17]
	ds_read_b64_tr_b16 v[42:43], v189 offset:38912
	ds_read_b64_tr_b16 v[44:45], v189 offset:39424
	v_exp_f32_e32 v70, v70
	v_exp_f32_e32 v71, v71
	v_add_f32_e32 v50, v46, v68
	v_cvt_pk_bf16_f32 v135, v68, v69
	v_mfma_f32_32x32x16_bf16 v[2:17], v[138:141], v[154:157], v[2:17]
	ds_read_b64_tr_b16 v[46:47], v189 offset:39936
	ds_read_b64_tr_b16 v[48:49], v189 offset:40448
	v_add_f32_e32 v50, v50, v69
	v_exp_f32_e32 v72, v72
	v_exp_f32_e32 v73, v73
	v_add_f32_e32 v54, v70, v50
	s_waitcnt lgkmcnt(6)
	v_mfma_f32_32x32x16_bf16 v[18:33], v[150:153], v[34:37], v[18:33]
	ds_read_b128 v[50:53], v182
	v_cvt_pk_bf16_f32 v136, v70, v71
	v_add_f32_e32 v58, v54, v71
	v_exp_f32_e32 v74, v74
	v_exp_f32_e32 v75, v75
	s_waitcnt lgkmcnt(5)
	v_mfma_f32_32x32x16_bf16 v[18:33], v[146:149], v[38:41], v[18:33]
	ds_read_b128 v[54:57], v182 offset:4096
	v_add_f32_e32 v34, v58, v72
	v_exp_f32_e32 v76, v76
	v_cvt_pk_bf16_f32 v137, v72, v73
	v_add_f32_e32 v34, v73, v34
	s_waitcnt lgkmcnt(4)
	v_mfma_f32_32x32x16_bf16 v[18:33], v[142:145], v[42:45], v[18:33]
	ds_read_b128 v[154:157], v183
	v_add_f32_e32 v34, v34, v74
	v_exp_f32_e32 v77, v77
	v_cvt_pk_bf16_f32 v130, v74, v75
	v_add_f32_e32 v34, v75, v34
	s_waitcnt lgkmcnt(3)
	v_mfma_f32_32x32x16_bf16 v[18:33], v[138:141], v[46:49], v[18:33]
	ds_read_b128 v[162:165], v183 offset:4096
	v_exp_f32_e32 v78, v78
	v_exp_f32_e32 v79, v79
	v_add_f32_e32 v34, v34, v76
	v_cvt_pk_bf16_f32 v131, v76, v77
	s_nop 0
	v_add_f32_e32 v34, v34, v77
	v_add_f32_e32 v59, v78, v34
	s_waitcnt lgkmcnt(3)
	v_mfma_f32_32x32x16_bf16 v[34:49], v[50:53], v[98:101], 0
	ds_read_b128 v[166:169], v184
	v_exp_f32_e32 v80, v80
	v_exp_f32_e32 v81, v81
	ds_read_b128 v[158:161], v184 offset:4096
	v_add_f32_e32 v193, v59, v79
	s_waitcnt lgkmcnt(4)
	v_mfma_f32_32x32x16_bf16 v[50:65], v[54:57], v[98:101], 0
	v_exp_f32_e32 v82, v82
	v_exp_f32_e32 v83, v83
	v_cvt_pk_bf16_f32 v132, v78, v79
	s_add_i32 s26, 0x9000, s8
	s_add_i32 s28, 0x2000, s12
	s_mov_b32 m0, s26
	s_nop 0
	global_load_lds_dwordx4 v174, s[20:21]
	s_mov_b32 m0, s28
	s_nop 0
	global_load_lds_dwordx4 v191, s[20:21]
	s_mov_b32 m0, s24
	s_waitcnt lgkmcnt(3)
	v_mfma_f32_32x32x16_bf16 v[34:49], v[154:157], v[102:105], v[34:49]
	ds_read_b128 v[194:197], v185
	v_add_f32_e32 v154, v193, v80
	v_exp_f32_e32 v84, v84
	v_cvt_pk_bf16_f32 v133, v80, v81
	v_add_f32_e32 v193, v81, v154
	s_waitcnt lgkmcnt(3)
	v_mfma_f32_32x32x16_bf16 v[50:65], v[162:165], v[102:105], v[50:65]
	ds_read_b128 v[154:157], v185 offset:4096
	v_add_f32_e32 v193, v193, v82
	v_exp_f32_e32 v85, v85
	v_cvt_pk_bf16_f32 v126, v82, v83
	v_add_f32_e32 v193, v83, v193
	s_waitcnt lgkmcnt(3)
	v_mfma_f32_32x32x16_bf16 v[34:49], v[166:169], v[106:109], v[34:49]
	ds_read_b128 v[162:165], v187 offset:8192
	v_exp_f32_e32 v86, v86
	v_exp_f32_e32 v87, v87
	v_add_f32_e32 v193, v193, v84
	v_cvt_pk_bf16_f32 v127, v84, v85
	s_waitcnt lgkmcnt(3)
	v_mfma_f32_32x32x16_bf16 v[50:65], v[158:161], v[106:109], v[50:65]
	ds_read_b128 v[198:201], v187 offset:10240
	v_add_f32_e32 v166, v193, v85
	v_exp_f32_e32 v88, v88
	v_exp_f32_e32 v89, v89
	v_add_f32_e32 v166, v86, v166
	s_waitcnt lgkmcnt(3)
	v_mfma_f32_32x32x16_bf16 v[34:49], v[194:197], v[110:113], v[34:49]
	ds_read_b128 v[202:205], v188 offset:8192
	v_cvt_pk_bf16_f32 v128, v86, v87
	v_add_f32_e32 v159, v166, v87
	v_exp_f32_e32 v90, v90
	v_exp_f32_e32 v91, v91
	s_waitcnt lgkmcnt(3)
	v_mfma_f32_32x32x16_bf16 v[50:65], v[154:157], v[110:113], v[50:65]
	ds_read_b128 v[194:197], v188 offset:10240
	v_add_f32_e32 v158, v159, v88
	v_exp_f32_e32 v92, v92
	v_cvt_pk_bf16_f32 v129, v88, v89
	v_add_f32_e32 v158, v89, v158
	s_waitcnt lgkmcnt(3)
	v_mfma_f32_32x32x16_bf16 v[34:49], v[162:165], v[114:117], v[34:49]
	ds_read_b64_tr_b16 v[166:167], v189 offset:40960
	ds_read_b64_tr_b16 v[168:169], v189 offset:41472
	v_add_f32_e32 v154, v158, v90
	v_exp_f32_e32 v93, v93
	v_cvt_pk_bf16_f32 v122, v90, v91
	v_add_f32_e32 v154, v91, v154
	s_waitcnt lgkmcnt(4)
	v_mfma_f32_32x32x16_bf16 v[50:65], v[198:201], v[114:117], v[50:65]
	ds_read_b64_tr_b16 v[162:163], v189 offset:41984
	ds_read_b64_tr_b16 v[164:165], v189 offset:42496
	v_exp_f32_e32 v94, v94
	v_exp_f32_e32 v95, v95
	v_add_f32_e32 v154, v154, v92
	v_cvt_pk_bf16_f32 v123, v92, v93
	s_waitcnt lgkmcnt(5)
	v_mfma_f32_32x32x16_bf16 v[34:49], v[202:205], v[118:121], v[34:49]
	ds_read_b64_tr_b16 v[158:159], v189 offset:43008
	ds_read_b64_tr_b16 v[160:161], v189 offset:43520
	v_add_f32_e32 v154, v154, v93
	v_exp_f32_e32 v96, v96
	v_exp_f32_e32 v97, v97
	v_add_f32_e32 v193, v94, v154
	s_waitcnt lgkmcnt(6)
	v_mfma_f32_32x32x16_bf16 v[50:65], v[194:197], v[118:121], v[50:65]
	ds_read_b64_tr_b16 v[154:155], v189 offset:44032
	ds_read_b64_tr_b16 v[156:157], v189 offset:44544
	v_add_f32_e32 v125, v193, v95
	v_add_f32_e32 v193, v96, v125
	v_cvt_pk_bf16_f32 v124, v94, v95
	v_cvt_pk_bf16_f32 v125, v96, v97
	v_add_f32_e32 v193, v97, v193
	s_add_u32 s22, s22, 0x2000
	s_addc_u32 s23, s23, 0
	s_add_u32 s20, s20, 0x40000
	s_addc_u32 s21, s21, 0
	s_waitcnt vmcnt(4) lgkmcnt(0)
	s_barrier
	v_mfma_f32_32x32x16_bf16 v[2:17], v[134:137], v[166:169], v[2:17]
	ds_read_b64_tr_b16 v[66:67], v189 offset:45056
	ds_read_b64_tr_b16 v[68:69], v189 offset:45568
	v_exp_f32_e32 v34, v34
	v_exp_f32_e32 v35, v35
	v_exp_f32_e32 v36, v36
	v_mfma_f32_32x32x16_bf16 v[2:17], v[130:133], v[162:165], v[2:17]
	ds_read_b64_tr_b16 v[70:71], v189 offset:46080
	ds_read_b64_tr_b16 v[72:73], v189 offset:46592
	v_add_f32_e32 v74, v193, v34
	v_exp_f32_e32 v37, v37
	v_cvt_pk_bf16_f32 v150, v34, v35
	v_add_f32_e32 v78, v35, v74
	v_mfma_f32_32x32x16_bf16 v[2:17], v[126:129], v[158:161], v[2:17]
	ds_read_b64_tr_b16 v[74:75], v189 offset:47104
	ds_read_b64_tr_b16 v[76:77], v189 offset:47616
	v_exp_f32_e32 v38, v38
	v_exp_f32_e32 v39, v39
	v_add_f32_e32 v82, v78, v36
	v_cvt_pk_bf16_f32 v151, v36, v37
	v_mfma_f32_32x32x16_bf16 v[2:17], v[122:125], v[154:157], v[2:17]
	ds_read_b64_tr_b16 v[78:79], v189 offset:48128
	ds_read_b64_tr_b16 v[80:81], v189 offset:48640
	v_add_f32_e32 v82, v82, v37
	v_exp_f32_e32 v40, v40
	v_exp_f32_e32 v41, v41
	v_add_f32_e32 v86, v38, v82
	s_waitcnt lgkmcnt(6)
	v_mfma_f32_32x32x16_bf16 v[18:33], v[134:137], v[66:69], v[18:33]
	ds_read_b128 v[82:85], v182 offset:12288
	v_cvt_pk_bf16_f32 v152, v38, v39
	v_add_f32_e32 v90, v86, v39
	v_exp_f32_e32 v42, v42
	v_exp_f32_e32 v43, v43
	s_waitcnt lgkmcnt(5)
	v_mfma_f32_32x32x16_bf16 v[18:33], v[130:133], v[70:73], v[18:33]
	ds_read_b128 v[86:89], v182 offset:16384
	v_add_f32_e32 v66, v90, v40
	v_exp_f32_e32 v44, v44
	v_cvt_pk_bf16_f32 v153, v40, v41
	v_add_f32_e32 v66, v41, v66
	s_waitcnt lgkmcnt(4)
	v_mfma_f32_32x32x16_bf16 v[18:33], v[126:129], v[74:77], v[18:33]
	ds_read_b128 v[154:157], v183 offset:12288
	v_add_f32_e32 v66, v66, v42
	v_exp_f32_e32 v45, v45
	v_cvt_pk_bf16_f32 v146, v42, v43
	v_add_f32_e32 v66, v43, v66
	s_waitcnt lgkmcnt(3)
	v_mfma_f32_32x32x16_bf16 v[18:33], v[122:125], v[78:81], v[18:33]
	ds_read_b128 v[162:165], v183 offset:16384
	v_exp_f32_e32 v46, v46
	v_exp_f32_e32 v47, v47
	v_add_f32_e32 v66, v66, v44
	v_cvt_pk_bf16_f32 v147, v44, v45
	s_nop 0
	v_add_f32_e32 v66, v66, v45
	v_add_f32_e32 v91, v46, v66
	s_waitcnt lgkmcnt(3)
	v_mfma_f32_32x32x16_bf16 v[66:81], v[82:85], v[98:101], 0
	ds_read_b128 v[166:169], v184 offset:12288
	v_exp_f32_e32 v48, v48
	v_exp_f32_e32 v49, v49
	ds_read_b128 v[158:161], v184 offset:16384
	v_add_f32_e32 v193, v91, v47
	s_waitcnt lgkmcnt(4)
	v_mfma_f32_32x32x16_bf16 v[82:97], v[86:89], v[98:101], 0
	v_exp_f32_e32 v50, v50
	v_exp_f32_e32 v51, v51
	v_cvt_pk_bf16_f32 v148, v46, v47
	s_add_u32 s26, s20, 0xfffe0000
	s_addc_u32 s27, s21, -1
	s_add_i32 s31, 0, s8
	s_add_i32 s33, 0x4000, s12
	s_mov_b32 m0, s31
	s_nop 0
	global_load_lds_dwordx4 v174, s[26:27]
	s_mov_b32 m0, s33
	s_nop 0
	global_load_lds_dwordx4 v191, s[26:27]
	s_mov_b32 m0, s28
	s_waitcnt lgkmcnt(3)
	v_mfma_f32_32x32x16_bf16 v[66:81], v[154:157], v[102:105], v[66:81]
	ds_read_b128 v[194:197], v185 offset:12288
	v_add_f32_e32 v193, v193, v48
	v_cvt_pk_bf16_f32 v149, v48, v49
	v_add_f32_e32 v193, v49, v193
	v_exp_f32_e32 v52, v52
	s_waitcnt lgkmcnt(3)
	v_mfma_f32_32x32x16_bf16 v[82:97], v[162:165], v[102:105], v[82:97]
	ds_read_b128 v[154:157], v185 offset:16384
	v_add_f32_e32 v193, v193, v50
	v_exp_f32_e32 v53, v53
	v_cvt_pk_bf16_f32 v142, v50, v51
	v_add_f32_e32 v193, v51, v193
	s_waitcnt lgkmcnt(3)
	v_mfma_f32_32x32x16_bf16 v[66:81], v[166:169], v[106:109], v[66:81]
	ds_read_b128 v[162:165], v187 offset:20480
	v_exp_f32_e32 v54, v54
	v_exp_f32_e32 v55, v55
	v_add_f32_e32 v193, v193, v52
	v_cvt_pk_bf16_f32 v143, v52, v53
	s_waitcnt lgkmcnt(3)
	v_mfma_f32_32x32x16_bf16 v[82:97], v[158:161], v[106:109], v[82:97]
	ds_read_b128 v[198:201], v187 offset:22528
	v_add_f32_e32 v166, v193, v53
	v_exp_f32_e32 v56, v56
	v_exp_f32_e32 v57, v57
	v_add_f32_e32 v166, v54, v166
	s_waitcnt lgkmcnt(3)
	v_mfma_f32_32x32x16_bf16 v[66:81], v[194:197], v[110:113], v[66:81]
	ds_read_b128 v[202:205], v188 offset:20480
	v_cvt_pk_bf16_f32 v144, v54, v55
	v_add_f32_e32 v159, v166, v55
	v_exp_f32_e32 v58, v58
	v_exp_f32_e32 v59, v59
	s_waitcnt lgkmcnt(3)
	v_mfma_f32_32x32x16_bf16 v[82:97], v[154:157], v[110:113], v[82:97]
	ds_read_b128 v[194:197], v188 offset:22528
	v_add_f32_e32 v158, v159, v56
	v_exp_f32_e32 v60, v60
	v_cvt_pk_bf16_f32 v145, v56, v57
	v_add_f32_e32 v158, v57, v158
	s_waitcnt lgkmcnt(3)
	v_mfma_f32_32x32x16_bf16 v[66:81], v[162:165], v[114:117], v[66:81]
	ds_read_b64_tr_b16 v[166:167], v189 offset:49152
	ds_read_b64_tr_b16 v[168:169], v189 offset:49664
	v_add_f32_e32 v154, v158, v58
	v_exp_f32_e32 v61, v61
	v_cvt_pk_bf16_f32 v138, v58, v59
	v_add_f32_e32 v154, v59, v154
	s_waitcnt lgkmcnt(4)
	v_mfma_f32_32x32x16_bf16 v[82:97], v[198:201], v[114:117], v[82:97]
	ds_read_b64_tr_b16 v[162:163], v189 offset:50176
	ds_read_b64_tr_b16 v[164:165], v189 offset:50688
	v_exp_f32_e32 v62, v62
	v_exp_f32_e32 v63, v63
	v_add_f32_e32 v154, v154, v60
	v_cvt_pk_bf16_f32 v139, v60, v61
	s_waitcnt lgkmcnt(5)
	v_mfma_f32_32x32x16_bf16 v[66:81], v[202:205], v[118:121], v[66:81]
	ds_read_b64_tr_b16 v[158:159], v189 offset:51200
	ds_read_b64_tr_b16 v[160:161], v189 offset:51712
	v_add_f32_e32 v154, v154, v61
	v_exp_f32_e32 v64, v64
	v_exp_f32_e32 v65, v65
	v_add_f32_e32 v198, v62, v154
	s_waitcnt lgkmcnt(6)
	v_mfma_f32_32x32x16_bf16 v[82:97], v[194:197], v[118:121], v[82:97]
	ds_read_b64_tr_b16 v[154:155], v189 offset:52224
	ds_read_b64_tr_b16 v[156:157], v189 offset:52736
	v_add_f32_e32 v141, v198, v63
	v_add_f32_e32 v198, v64, v141
	v_cvt_pk_bf16_f32 v140, v62, v63
	v_cvt_pk_bf16_f32 v141, v64, v65
	v_add_f32_e32 v194, v65, v198
	s_waitcnt vmcnt(4) lgkmcnt(0)
	s_barrier
	v_mfma_f32_32x32x16_bf16 v[2:17], v[150:153], v[166:169], v[2:17]
	ds_read_b64_tr_b16 v[34:35], v189 offset:53248
	ds_read_b64_tr_b16 v[36:37], v189 offset:53760
	v_exp_f32_e32 v66, v66
	v_exp_f32_e32 v67, v67
	v_exp_f32_e32 v68, v68
	v_mfma_f32_32x32x16_bf16 v[2:17], v[146:149], v[162:165], v[2:17]
	ds_read_b64_tr_b16 v[38:39], v189 offset:54272
	ds_read_b64_tr_b16 v[40:41], v189 offset:54784
	v_add_f32_e32 v42, v194, v66
	v_exp_f32_e32 v69, v69
	v_cvt_pk_bf16_f32 v134, v66, v67
	v_add_f32_e32 v46, v67, v42
	v_mfma_f32_32x32x16_bf16 v[2:17], v[142:145], v[158:161], v[2:17]
	ds_read_b64_tr_b16 v[42:43], v189 offset:55296
	ds_read_b64_tr_b16 v[44:45], v189 offset:55808
	v_exp_f32_e32 v70, v70
	v_exp_f32_e32 v71, v71
	v_add_f32_e32 v50, v46, v68
	v_cvt_pk_bf16_f32 v135, v68, v69
	v_mfma_f32_32x32x16_bf16 v[2:17], v[138:141], v[154:157], v[2:17]
	ds_read_b64_tr_b16 v[46:47], v189 offset:56320
	ds_read_b64_tr_b16 v[48:49], v189 offset:56832
	v_add_f32_e32 v50, v50, v69
	v_exp_f32_e32 v72, v72
	v_exp_f32_e32 v73, v73
	v_add_f32_e32 v54, v70, v50
	s_waitcnt lgkmcnt(6)
	v_mfma_f32_32x32x16_bf16 v[18:33], v[150:153], v[34:37], v[18:33]
	ds_read_b128 v[50:53], v182 offset:24576
	v_cvt_pk_bf16_f32 v136, v70, v71
	v_add_f32_e32 v58, v54, v71
	v_exp_f32_e32 v74, v74
	v_exp_f32_e32 v75, v75
	s_waitcnt lgkmcnt(5)
	v_mfma_f32_32x32x16_bf16 v[18:33], v[146:149], v[38:41], v[18:33]
	ds_read_b128 v[54:57], v182 offset:28672
	v_add_f32_e32 v34, v58, v72
	v_exp_f32_e32 v76, v76
	v_cvt_pk_bf16_f32 v137, v72, v73
	v_add_f32_e32 v34, v73, v34
	s_waitcnt lgkmcnt(4)
	v_mfma_f32_32x32x16_bf16 v[18:33], v[142:145], v[42:45], v[18:33]
	ds_read_b128 v[154:157], v183 offset:24576
	v_add_f32_e32 v34, v34, v74
	v_exp_f32_e32 v77, v77
	v_cvt_pk_bf16_f32 v130, v74, v75
	v_add_f32_e32 v34, v75, v34
	s_waitcnt lgkmcnt(3)
	v_mfma_f32_32x32x16_bf16 v[18:33], v[138:141], v[46:49], v[18:33]
	ds_read_b128 v[162:165], v183 offset:28672
	v_exp_f32_e32 v78, v78
	v_exp_f32_e32 v79, v79
	v_add_f32_e32 v34, v34, v76
	v_cvt_pk_bf16_f32 v131, v76, v77
	s_nop 0
	v_add_f32_e32 v34, v34, v77
	v_add_f32_e32 v59, v78, v34
	s_waitcnt lgkmcnt(3)
	v_mfma_f32_32x32x16_bf16 v[34:49], v[50:53], v[98:101], 0
	ds_read_b128 v[166:169], v184 offset:24576
	v_exp_f32_e32 v80, v80
	v_exp_f32_e32 v81, v81
	ds_read_b128 v[158:161], v184 offset:28672
	v_add_f32_e32 v193, v59, v79
	s_waitcnt lgkmcnt(4)
	v_mfma_f32_32x32x16_bf16 v[50:65], v[54:57], v[98:101], 0
	v_exp_f32_e32 v82, v82
	v_exp_f32_e32 v83, v83
	v_cvt_pk_bf16_f32 v132, v78, v79
	s_add_i32 s26, 0x3000, s8
	s_add_i32 s28, 0x6000, s12
	s_mov_b32 m0, s26
	s_nop 0
	global_load_lds_dwordx4 v174, s[20:21]
	s_mov_b32 m0, s28
	s_nop 0
	global_load_lds_dwordx4 v191, s[20:21]
	s_mov_b32 m0, s24
	s_waitcnt lgkmcnt(3)
	v_mfma_f32_32x32x16_bf16 v[34:49], v[154:157], v[102:105], v[34:49]
	ds_read_b128 v[194:197], v185 offset:24576
	v_add_f32_e32 v154, v193, v80
	v_exp_f32_e32 v84, v84
	v_cvt_pk_bf16_f32 v133, v80, v81
	v_add_f32_e32 v193, v81, v154
	s_waitcnt lgkmcnt(3)
	v_mfma_f32_32x32x16_bf16 v[50:65], v[162:165], v[102:105], v[50:65]
	ds_read_b128 v[154:157], v185 offset:28672
	v_add_f32_e32 v193, v193, v82
	v_exp_f32_e32 v85, v85
	v_cvt_pk_bf16_f32 v126, v82, v83
	v_add_f32_e32 v193, v83, v193
	s_waitcnt lgkmcnt(3)
	v_mfma_f32_32x32x16_bf16 v[34:49], v[166:169], v[106:109], v[34:49]
	ds_read_b128 v[162:165], v187 offset:32768
	v_exp_f32_e32 v86, v86
	v_exp_f32_e32 v87, v87
	v_add_f32_e32 v193, v193, v84
	v_cvt_pk_bf16_f32 v127, v84, v85
	s_waitcnt lgkmcnt(3)
	v_mfma_f32_32x32x16_bf16 v[50:65], v[158:161], v[106:109], v[50:65]
	ds_read_b128 v[198:201], v187 offset:34816
	v_add_f32_e32 v166, v193, v85
	v_exp_f32_e32 v88, v88
	v_exp_f32_e32 v89, v89
	v_add_f32_e32 v166, v86, v166
	s_waitcnt lgkmcnt(3)
	v_mfma_f32_32x32x16_bf16 v[34:49], v[194:197], v[110:113], v[34:49]
	ds_read_b128 v[202:205], v188 offset:32768
	v_cvt_pk_bf16_f32 v128, v86, v87
	v_add_f32_e32 v159, v166, v87
	v_exp_f32_e32 v90, v90
	v_exp_f32_e32 v91, v91
	s_waitcnt lgkmcnt(3)
	v_mfma_f32_32x32x16_bf16 v[50:65], v[154:157], v[110:113], v[50:65]
	ds_read_b128 v[194:197], v188 offset:34816
	v_add_f32_e32 v158, v159, v88
	v_exp_f32_e32 v92, v92
	v_cvt_pk_bf16_f32 v129, v88, v89
	v_add_f32_e32 v158, v89, v158
	s_waitcnt lgkmcnt(3)
	v_mfma_f32_32x32x16_bf16 v[34:49], v[162:165], v[114:117], v[34:49]
	ds_read_b64_tr_b16 v[166:167], v189 offset:57344
	ds_read_b64_tr_b16 v[168:169], v189 offset:57856
	v_add_f32_e32 v154, v158, v90
	v_exp_f32_e32 v93, v93
	v_cvt_pk_bf16_f32 v122, v90, v91
	v_add_f32_e32 v154, v91, v154
	s_waitcnt lgkmcnt(4)
	v_mfma_f32_32x32x16_bf16 v[50:65], v[198:201], v[114:117], v[50:65]
	ds_read_b64_tr_b16 v[162:163], v189 offset:58368
	ds_read_b64_tr_b16 v[164:165], v189 offset:58880
	v_exp_f32_e32 v94, v94
	v_exp_f32_e32 v95, v95
	v_add_f32_e32 v154, v154, v92
	v_cvt_pk_bf16_f32 v123, v92, v93
	s_waitcnt lgkmcnt(5)
	v_mfma_f32_32x32x16_bf16 v[34:49], v[202:205], v[118:121], v[34:49]
	ds_read_b64_tr_b16 v[158:159], v189 offset:59392
	ds_read_b64_tr_b16 v[160:161], v189 offset:59904
	v_add_f32_e32 v154, v154, v93
	v_exp_f32_e32 v96, v96
	v_exp_f32_e32 v97, v97
	v_add_f32_e32 v193, v94, v154
	s_waitcnt lgkmcnt(6)
	v_mfma_f32_32x32x16_bf16 v[50:65], v[194:197], v[118:121], v[50:65]
	ds_read_b64_tr_b16 v[154:155], v189 offset:60416
	ds_read_b64_tr_b16 v[156:157], v189 offset:60928
	v_add_f32_e32 v125, v193, v95
	v_add_f32_e32 v193, v96, v125
	v_cvt_pk_bf16_f32 v124, v94, v95
	v_cvt_pk_bf16_f32 v125, v96, v97
	v_add_f32_e32 v193, v97, v193
	s_add_u32 s22, s22, 0x2000
	s_addc_u32 s23, s23, 0
	s_add_u32 s20, s20, 0x40000
	s_addc_u32 s21, s21, 0
	s_waitcnt vmcnt(4) lgkmcnt(0)
	s_barrier
	v_mfma_f32_32x32x16_bf16 v[2:17], v[134:137], v[166:169], v[2:17]
	ds_read_b64_tr_b16 v[66:67], v189 offset:61440
	ds_read_b64_tr_b16 v[68:69], v189 offset:61952
	v_exp_f32_e32 v34, v34
	v_exp_f32_e32 v35, v35
	v_exp_f32_e32 v36, v36
	v_mfma_f32_32x32x16_bf16 v[2:17], v[130:133], v[162:165], v[2:17]
	ds_read_b64_tr_b16 v[70:71], v189 offset:62464
	ds_read_b64_tr_b16 v[72:73], v189 offset:62976
	v_add_f32_e32 v74, v193, v34
	v_exp_f32_e32 v37, v37
	v_cvt_pk_bf16_f32 v150, v34, v35
	v_add_f32_e32 v78, v35, v74
	v_mfma_f32_32x32x16_bf16 v[2:17], v[126:129], v[158:161], v[2:17]
	ds_read_b64_tr_b16 v[74:75], v189 offset:63488
	ds_read_b64_tr_b16 v[76:77], v189 offset:64000
	v_exp_f32_e32 v38, v38
	v_exp_f32_e32 v39, v39
	v_add_f32_e32 v82, v78, v36
	v_cvt_pk_bf16_f32 v151, v36, v37
	v_mfma_f32_32x32x16_bf16 v[2:17], v[122:125], v[154:157], v[2:17]
	ds_read_b64_tr_b16 v[78:79], v189 offset:64512
	ds_read_b64_tr_b16 v[80:81], v189 offset:65024
	v_add_f32_e32 v82, v82, v37
	v_exp_f32_e32 v40, v40
	v_exp_f32_e32 v41, v41
	v_add_f32_e32 v86, v38, v82
	s_waitcnt lgkmcnt(6)
	v_mfma_f32_32x32x16_bf16 v[18:33], v[134:137], v[66:69], v[18:33]
	ds_read_b128 v[82:85], v182 offset:36864
	v_cvt_pk_bf16_f32 v152, v38, v39
	v_add_f32_e32 v90, v86, v39
	v_exp_f32_e32 v42, v42
	v_exp_f32_e32 v43, v43
	s_waitcnt lgkmcnt(5)
	v_mfma_f32_32x32x16_bf16 v[18:33], v[130:133], v[70:73], v[18:33]
	ds_read_b128 v[86:89], v182 offset:40960
	v_add_f32_e32 v66, v90, v40
	v_exp_f32_e32 v44, v44
	v_cvt_pk_bf16_f32 v153, v40, v41
	v_add_f32_e32 v66, v41, v66
	s_waitcnt lgkmcnt(4)
	v_mfma_f32_32x32x16_bf16 v[18:33], v[126:129], v[74:77], v[18:33]
	ds_read_b128 v[154:157], v183 offset:36864
	v_add_f32_e32 v66, v66, v42
	v_exp_f32_e32 v45, v45
	v_cvt_pk_bf16_f32 v146, v42, v43
	v_add_f32_e32 v66, v43, v66
	s_waitcnt lgkmcnt(3)
	v_mfma_f32_32x32x16_bf16 v[18:33], v[122:125], v[78:81], v[18:33]
	ds_read_b128 v[162:165], v183 offset:40960
	v_exp_f32_e32 v46, v46
	v_exp_f32_e32 v47, v47
	v_add_f32_e32 v66, v66, v44
	v_cvt_pk_bf16_f32 v147, v44, v45
	s_nop 0
	v_add_f32_e32 v66, v66, v45
	v_add_f32_e32 v91, v46, v66
	s_waitcnt lgkmcnt(3)
	v_mfma_f32_32x32x16_bf16 v[66:81], v[82:85], v[98:101], 0
	ds_read_b128 v[166:169], v184 offset:36864
	v_exp_f32_e32 v48, v48
	v_exp_f32_e32 v49, v49
	ds_read_b128 v[158:161], v184 offset:40960
	v_add_f32_e32 v193, v91, v47
	s_waitcnt lgkmcnt(4)
	v_mfma_f32_32x32x16_bf16 v[82:97], v[86:89], v[98:101], 0
	v_exp_f32_e32 v50, v50
	v_exp_f32_e32 v51, v51
	v_cvt_pk_bf16_f32 v148, v46, v47
	s_add_u32 s26, s20, 0xfffe0000
	s_addc_u32 s27, s21, -1
	s_add_i32 s31, 0x6000, s8
	s_add_i32 s33, 0x8000, s12
	s_mov_b32 m0, s31
	s_nop 0
	global_load_lds_dwordx4 v174, s[26:27]
	s_mov_b32 m0, s33
	s_nop 0
	global_load_lds_dwordx4 v191, s[26:27]
	s_mov_b32 m0, s28
	s_waitcnt lgkmcnt(3)
	v_mfma_f32_32x32x16_bf16 v[66:81], v[154:157], v[102:105], v[66:81]
	ds_read_b128 v[194:197], v185 offset:36864
	v_add_f32_e32 v193, v193, v48
	v_cvt_pk_bf16_f32 v149, v48, v49
	v_add_f32_e32 v193, v49, v193
	v_exp_f32_e32 v52, v52
	s_waitcnt lgkmcnt(3)
	v_mfma_f32_32x32x16_bf16 v[82:97], v[162:165], v[102:105], v[82:97]
	ds_read_b128 v[154:157], v185 offset:40960
	v_add_f32_e32 v193, v193, v50
	v_exp_f32_e32 v53, v53
	v_cvt_pk_bf16_f32 v142, v50, v51
	v_add_f32_e32 v193, v51, v193
	s_waitcnt lgkmcnt(3)
	v_mfma_f32_32x32x16_bf16 v[66:81], v[166:169], v[106:109], v[66:81]
	ds_read_b128 v[162:165], v187 offset:45056
	v_exp_f32_e32 v54, v54
	v_exp_f32_e32 v55, v55
	v_add_f32_e32 v193, v193, v52
	v_cvt_pk_bf16_f32 v143, v52, v53
	s_waitcnt lgkmcnt(3)
	v_mfma_f32_32x32x16_bf16 v[82:97], v[158:161], v[106:109], v[82:97]
	ds_read_b128 v[198:201], v187 offset:47104
	v_add_f32_e32 v166, v193, v53
	v_exp_f32_e32 v56, v56
	v_exp_f32_e32 v57, v57
	v_add_f32_e32 v166, v54, v166
	s_waitcnt lgkmcnt(3)
	v_mfma_f32_32x32x16_bf16 v[66:81], v[194:197], v[110:113], v[66:81]
	ds_read_b128 v[202:205], v188 offset:45056
	v_cvt_pk_bf16_f32 v144, v54, v55
	v_add_f32_e32 v159, v166, v55
	v_exp_f32_e32 v58, v58
	v_exp_f32_e32 v59, v59
	s_waitcnt lgkmcnt(3)
	v_mfma_f32_32x32x16_bf16 v[82:97], v[154:157], v[110:113], v[82:97]
	ds_read_b128 v[194:197], v188 offset:47104
	v_add_f32_e32 v158, v159, v56
	v_exp_f32_e32 v60, v60
	v_cvt_pk_bf16_f32 v145, v56, v57
	v_add_f32_e32 v158, v57, v158
	s_waitcnt lgkmcnt(3)
	v_mfma_f32_32x32x16_bf16 v[66:81], v[162:165], v[114:117], v[66:81]
	ds_read_b64_tr_b16 v[166:167], v189 offset:16384
	ds_read_b64_tr_b16 v[168:169], v189 offset:16896
	v_add_f32_e32 v154, v158, v58
	v_exp_f32_e32 v61, v61
	v_cvt_pk_bf16_f32 v138, v58, v59
	v_add_f32_e32 v154, v59, v154
	s_waitcnt lgkmcnt(4)
	v_mfma_f32_32x32x16_bf16 v[82:97], v[198:201], v[114:117], v[82:97]
	ds_read_b64_tr_b16 v[162:163], v189 offset:17408
	ds_read_b64_tr_b16 v[164:165], v189 offset:17920
	v_exp_f32_e32 v62, v62
	v_exp_f32_e32 v63, v63
	v_add_f32_e32 v154, v154, v60
	v_cvt_pk_bf16_f32 v139, v60, v61
	s_waitcnt lgkmcnt(5)
	v_mfma_f32_32x32x16_bf16 v[66:81], v[202:205], v[118:121], v[66:81]
	ds_read_b64_tr_b16 v[158:159], v189 offset:18432
	ds_read_b64_tr_b16 v[160:161], v189 offset:18944
	v_add_f32_e32 v154, v154, v61
	v_exp_f32_e32 v64, v64
	v_exp_f32_e32 v65, v65
	v_add_f32_e32 v198, v62, v154
	s_waitcnt lgkmcnt(6)
	v_mfma_f32_32x32x16_bf16 v[82:97], v[194:197], v[118:121], v[82:97]
	ds_read_b64_tr_b16 v[154:155], v189 offset:19456
	ds_read_b64_tr_b16 v[156:157], v189 offset:19968
	v_add_f32_e32 v141, v198, v63
	v_add_f32_e32 v198, v64, v141
	v_cvt_pk_bf16_f32 v140, v62, v63
	v_cvt_pk_bf16_f32 v141, v64, v65
	v_add_f32_e32 v194, v65, v198
	s_waitcnt vmcnt(4) lgkmcnt(0)
	s_barrier
	v_mfma_f32_32x32x16_bf16 v[2:17], v[150:153], v[166:169], v[2:17]
	ds_read_b64_tr_b16 v[34:35], v189 offset:20480
	ds_read_b64_tr_b16 v[36:37], v189 offset:20992
	v_exp_f32_e32 v66, v66
	v_exp_f32_e32 v67, v67
	v_exp_f32_e32 v68, v68
	v_mfma_f32_32x32x16_bf16 v[2:17], v[146:149], v[162:165], v[2:17]
	ds_read_b64_tr_b16 v[38:39], v189 offset:21504
	ds_read_b64_tr_b16 v[40:41], v189 offset:22016
	v_add_f32_e32 v42, v194, v66
	v_exp_f32_e32 v69, v69
	v_cvt_pk_bf16_f32 v134, v66, v67
	v_add_f32_e32 v46, v67, v42
	v_mfma_f32_32x32x16_bf16 v[2:17], v[142:145], v[158:161], v[2:17]
	ds_read_b64_tr_b16 v[42:43], v189 offset:22528
	ds_read_b64_tr_b16 v[44:45], v189 offset:23040
	v_exp_f32_e32 v70, v70
	v_exp_f32_e32 v71, v71
	v_add_f32_e32 v50, v46, v68
	v_cvt_pk_bf16_f32 v135, v68, v69
	v_mfma_f32_32x32x16_bf16 v[2:17], v[138:141], v[154:157], v[2:17]
	ds_read_b64_tr_b16 v[46:47], v189 offset:23552
	ds_read_b64_tr_b16 v[48:49], v189 offset:24064
	v_add_f32_e32 v50, v50, v69
	v_exp_f32_e32 v72, v72
	v_exp_f32_e32 v73, v73
	v_add_f32_e32 v54, v70, v50
	s_waitcnt lgkmcnt(6)
	v_mfma_f32_32x32x16_bf16 v[18:33], v[150:153], v[34:37], v[18:33]
	ds_read_b128 v[50:53], v182
	v_cvt_pk_bf16_f32 v136, v70, v71
	v_add_f32_e32 v58, v54, v71
	v_exp_f32_e32 v74, v74
	v_exp_f32_e32 v75, v75
	s_waitcnt lgkmcnt(5)
	v_mfma_f32_32x32x16_bf16 v[18:33], v[146:149], v[38:41], v[18:33]
	ds_read_b128 v[54:57], v182 offset:4096
	v_add_f32_e32 v34, v58, v72
	v_exp_f32_e32 v76, v76
	v_cvt_pk_bf16_f32 v137, v72, v73
	v_add_f32_e32 v34, v73, v34
	s_waitcnt lgkmcnt(4)
	v_mfma_f32_32x32x16_bf16 v[18:33], v[142:145], v[42:45], v[18:33]
	ds_read_b128 v[154:157], v183
	v_add_f32_e32 v34, v34, v74
	v_exp_f32_e32 v77, v77
	v_cvt_pk_bf16_f32 v130, v74, v75
	v_add_f32_e32 v34, v75, v34
	s_waitcnt lgkmcnt(3)
	v_mfma_f32_32x32x16_bf16 v[18:33], v[138:141], v[46:49], v[18:33]
	ds_read_b128 v[162:165], v183 offset:4096
	v_exp_f32_e32 v78, v78
	v_exp_f32_e32 v79, v79
	v_add_f32_e32 v34, v34, v76
	v_cvt_pk_bf16_f32 v131, v76, v77
	s_nop 0
	v_add_f32_e32 v34, v34, v77
	v_add_f32_e32 v59, v78, v34
	s_waitcnt lgkmcnt(3)
	v_mfma_f32_32x32x16_bf16 v[34:49], v[50:53], v[98:101], 0
	ds_read_b128 v[166:169], v184
	v_exp_f32_e32 v80, v80
	v_exp_f32_e32 v81, v81
	ds_read_b128 v[158:161], v184 offset:4096
	v_add_f32_e32 v193, v59, v79
	s_waitcnt lgkmcnt(4)
	v_mfma_f32_32x32x16_bf16 v[50:65], v[54:57], v[98:101], 0
	v_exp_f32_e32 v82, v82
	v_exp_f32_e32 v83, v83
	v_cvt_pk_bf16_f32 v132, v78, v79
	s_add_i32 s26, 0x9000, s8
	s_add_i32 s28, 0xa000, s12
	s_mov_b32 m0, s26
	s_nop 0
	global_load_lds_dwordx4 v174, s[20:21]
	s_mov_b32 m0, s28
	s_nop 0
	global_load_lds_dwordx4 v191, s[20:21]
	s_mov_b32 m0, s24
	s_waitcnt lgkmcnt(3)
	v_mfma_f32_32x32x16_bf16 v[34:49], v[154:157], v[102:105], v[34:49]
	ds_read_b128 v[194:197], v185
	v_add_f32_e32 v154, v193, v80
	v_exp_f32_e32 v84, v84
	v_cvt_pk_bf16_f32 v133, v80, v81
	v_add_f32_e32 v193, v81, v154
	s_waitcnt lgkmcnt(3)
	v_mfma_f32_32x32x16_bf16 v[50:65], v[162:165], v[102:105], v[50:65]
	ds_read_b128 v[154:157], v185 offset:4096
	v_add_f32_e32 v193, v193, v82
	v_exp_f32_e32 v85, v85
	v_cvt_pk_bf16_f32 v126, v82, v83
	v_add_f32_e32 v193, v83, v193
	s_waitcnt lgkmcnt(3)
	v_mfma_f32_32x32x16_bf16 v[34:49], v[166:169], v[106:109], v[34:49]
	ds_read_b128 v[162:165], v187 offset:8192
	v_exp_f32_e32 v86, v86
	v_exp_f32_e32 v87, v87
	v_add_f32_e32 v193, v193, v84
	v_cvt_pk_bf16_f32 v127, v84, v85
	s_waitcnt lgkmcnt(3)
	v_mfma_f32_32x32x16_bf16 v[50:65], v[158:161], v[106:109], v[50:65]
	ds_read_b128 v[198:201], v187 offset:10240
	v_add_f32_e32 v166, v193, v85
	v_exp_f32_e32 v88, v88
	v_exp_f32_e32 v89, v89
	v_add_f32_e32 v166, v86, v166
	s_waitcnt lgkmcnt(3)
	v_mfma_f32_32x32x16_bf16 v[34:49], v[194:197], v[110:113], v[34:49]
	ds_read_b128 v[202:205], v188 offset:8192
	v_cvt_pk_bf16_f32 v128, v86, v87
	v_add_f32_e32 v159, v166, v87
	v_exp_f32_e32 v90, v90
	v_exp_f32_e32 v91, v91
	s_waitcnt lgkmcnt(3)
	v_mfma_f32_32x32x16_bf16 v[50:65], v[154:157], v[110:113], v[50:65]
	ds_read_b128 v[194:197], v188 offset:10240
	v_add_f32_e32 v158, v159, v88
	v_exp_f32_e32 v92, v92
	v_cvt_pk_bf16_f32 v129, v88, v89
	v_add_f32_e32 v158, v89, v158
	s_waitcnt lgkmcnt(3)
	v_mfma_f32_32x32x16_bf16 v[34:49], v[162:165], v[114:117], v[34:49]
	ds_read_b64_tr_b16 v[166:167], v189 offset:24576
	ds_read_b64_tr_b16 v[168:169], v189 offset:25088
	v_add_f32_e32 v154, v158, v90
	v_exp_f32_e32 v93, v93
	v_cvt_pk_bf16_f32 v122, v90, v91
	v_add_f32_e32 v154, v91, v154
	s_waitcnt lgkmcnt(4)
	v_mfma_f32_32x32x16_bf16 v[50:65], v[198:201], v[114:117], v[50:65]
	ds_read_b64_tr_b16 v[162:163], v189 offset:25600
	ds_read_b64_tr_b16 v[164:165], v189 offset:26112
	v_exp_f32_e32 v94, v94
	v_exp_f32_e32 v95, v95
	v_add_f32_e32 v154, v154, v92
	v_cvt_pk_bf16_f32 v123, v92, v93
	s_waitcnt lgkmcnt(5)
	v_mfma_f32_32x32x16_bf16 v[34:49], v[202:205], v[118:121], v[34:49]
	ds_read_b64_tr_b16 v[158:159], v189 offset:26624
	ds_read_b64_tr_b16 v[160:161], v189 offset:27136
	v_add_f32_e32 v154, v154, v93
	v_exp_f32_e32 v96, v96
	v_exp_f32_e32 v97, v97
	v_add_f32_e32 v193, v94, v154
	s_waitcnt lgkmcnt(6)
	v_mfma_f32_32x32x16_bf16 v[50:65], v[194:197], v[118:121], v[50:65]
	ds_read_b64_tr_b16 v[154:155], v189 offset:27648
	ds_read_b64_tr_b16 v[156:157], v189 offset:28160
	v_add_f32_e32 v125, v193, v95
	v_add_f32_e32 v193, v96, v125
	v_cvt_pk_bf16_f32 v124, v94, v95
	v_cvt_pk_bf16_f32 v125, v96, v97
	v_add_f32_e32 v193, v97, v193
	s_add_u32 s22, s22, 0x2000
	s_addc_u32 s23, s23, 0
	s_add_u32 s20, s20, 0x40000
	s_addc_u32 s21, s21, 0
	s_waitcnt vmcnt(4) lgkmcnt(0)
	s_barrier
	v_mfma_f32_32x32x16_bf16 v[2:17], v[134:137], v[166:169], v[2:17]
	ds_read_b64_tr_b16 v[66:67], v189 offset:28672
	ds_read_b64_tr_b16 v[68:69], v189 offset:29184
	v_exp_f32_e32 v34, v34
	v_exp_f32_e32 v35, v35
	v_exp_f32_e32 v36, v36
	v_mfma_f32_32x32x16_bf16 v[2:17], v[130:133], v[162:165], v[2:17]
	ds_read_b64_tr_b16 v[70:71], v189 offset:29696
	ds_read_b64_tr_b16 v[72:73], v189 offset:30208
	v_add_f32_e32 v74, v193, v34
	v_exp_f32_e32 v37, v37
	v_cvt_pk_bf16_f32 v150, v34, v35
	v_add_f32_e32 v78, v35, v74
	v_mfma_f32_32x32x16_bf16 v[2:17], v[126:129], v[158:161], v[2:17]
	ds_read_b64_tr_b16 v[74:75], v189 offset:30720
	ds_read_b64_tr_b16 v[76:77], v189 offset:31232
	v_exp_f32_e32 v38, v38
	v_exp_f32_e32 v39, v39
	v_add_f32_e32 v82, v78, v36
	v_cvt_pk_bf16_f32 v151, v36, v37
	v_mfma_f32_32x32x16_bf16 v[2:17], v[122:125], v[154:157], v[2:17]
	ds_read_b64_tr_b16 v[78:79], v189 offset:31744
	ds_read_b64_tr_b16 v[80:81], v189 offset:32256
	v_add_f32_e32 v82, v82, v37
	v_exp_f32_e32 v40, v40
	v_exp_f32_e32 v41, v41
	v_add_f32_e32 v86, v38, v82
	s_waitcnt lgkmcnt(6)
	v_mfma_f32_32x32x16_bf16 v[18:33], v[134:137], v[66:69], v[18:33]
	ds_read_b128 v[82:85], v182 offset:12288
	v_cvt_pk_bf16_f32 v152, v38, v39
	v_add_f32_e32 v90, v86, v39
	v_exp_f32_e32 v42, v42
	v_exp_f32_e32 v43, v43
	s_waitcnt lgkmcnt(5)
	v_mfma_f32_32x32x16_bf16 v[18:33], v[130:133], v[70:73], v[18:33]
	ds_read_b128 v[86:89], v182 offset:16384
	v_add_f32_e32 v66, v90, v40
	v_exp_f32_e32 v44, v44
	v_cvt_pk_bf16_f32 v153, v40, v41
	v_add_f32_e32 v66, v41, v66
	s_waitcnt lgkmcnt(4)
	v_mfma_f32_32x32x16_bf16 v[18:33], v[126:129], v[74:77], v[18:33]
	ds_read_b128 v[154:157], v183 offset:12288
	v_add_f32_e32 v66, v66, v42
	v_exp_f32_e32 v45, v45
	v_cvt_pk_bf16_f32 v146, v42, v43
	v_add_f32_e32 v66, v43, v66
	s_waitcnt lgkmcnt(3)
	v_mfma_f32_32x32x16_bf16 v[18:33], v[122:125], v[78:81], v[18:33]
	ds_read_b128 v[162:165], v183 offset:16384
	v_exp_f32_e32 v46, v46
	v_exp_f32_e32 v47, v47
	v_add_f32_e32 v66, v66, v44
	v_cvt_pk_bf16_f32 v147, v44, v45
	s_nop 0
	v_add_f32_e32 v66, v66, v45
	v_add_f32_e32 v91, v46, v66
	s_waitcnt lgkmcnt(3)
	v_mfma_f32_32x32x16_bf16 v[66:81], v[82:85], v[98:101], 0
	ds_read_b128 v[166:169], v184 offset:12288
	v_exp_f32_e32 v48, v48
	v_exp_f32_e32 v49, v49
	ds_read_b128 v[158:161], v184 offset:16384
	v_add_f32_e32 v193, v91, v47
	s_waitcnt lgkmcnt(4)
	v_mfma_f32_32x32x16_bf16 v[82:97], v[86:89], v[98:101], 0
	v_exp_f32_e32 v50, v50
	v_exp_f32_e32 v51, v51
	v_cvt_pk_bf16_f32 v148, v46, v47
	s_add_u32 s26, s20, 0xfffe0000
	s_addc_u32 s27, s21, -1
	s_add_i32 s31, 0, s8
	s_add_i32 s33, 0, s12
	s_mov_b32 m0, s31
	s_nop 0
	global_load_lds_dwordx4 v174, s[26:27]
	s_mov_b32 m0, s33
	s_nop 0
	global_load_lds_dwordx4 v191, s[26:27]
	s_mov_b32 m0, s28
	s_waitcnt lgkmcnt(3)
	v_mfma_f32_32x32x16_bf16 v[66:81], v[154:157], v[102:105], v[66:81]
	ds_read_b128 v[194:197], v185 offset:12288
	v_add_f32_e32 v193, v193, v48
	v_cvt_pk_bf16_f32 v149, v48, v49
	v_add_f32_e32 v193, v49, v193
	v_exp_f32_e32 v52, v52
	s_waitcnt lgkmcnt(3)
	v_mfma_f32_32x32x16_bf16 v[82:97], v[162:165], v[102:105], v[82:97]
	ds_read_b128 v[154:157], v185 offset:16384
	v_add_f32_e32 v193, v193, v50
	v_exp_f32_e32 v53, v53
	v_cvt_pk_bf16_f32 v142, v50, v51
	v_add_f32_e32 v193, v51, v193
	s_waitcnt lgkmcnt(3)
	v_mfma_f32_32x32x16_bf16 v[66:81], v[166:169], v[106:109], v[66:81]
	ds_read_b128 v[162:165], v187 offset:20480
	v_exp_f32_e32 v54, v54
	v_exp_f32_e32 v55, v55
	v_add_f32_e32 v193, v193, v52
	v_cvt_pk_bf16_f32 v143, v52, v53
	s_waitcnt lgkmcnt(3)
	v_mfma_f32_32x32x16_bf16 v[82:97], v[158:161], v[106:109], v[82:97]
	ds_read_b128 v[198:201], v187 offset:22528
	v_add_f32_e32 v166, v193, v53
	v_exp_f32_e32 v56, v56
	v_exp_f32_e32 v57, v57
	v_add_f32_e32 v166, v54, v166
	s_waitcnt lgkmcnt(3)
	v_mfma_f32_32x32x16_bf16 v[66:81], v[194:197], v[110:113], v[66:81]
	ds_read_b128 v[202:205], v188 offset:20480
	v_cvt_pk_bf16_f32 v144, v54, v55
	v_add_f32_e32 v159, v166, v55
	v_exp_f32_e32 v58, v58
	v_exp_f32_e32 v59, v59
	s_waitcnt lgkmcnt(3)
	v_mfma_f32_32x32x16_bf16 v[82:97], v[154:157], v[110:113], v[82:97]
	ds_read_b128 v[194:197], v188 offset:22528
	v_add_f32_e32 v158, v159, v56
	v_exp_f32_e32 v60, v60
	v_cvt_pk_bf16_f32 v145, v56, v57
	v_add_f32_e32 v158, v57, v158
	s_waitcnt lgkmcnt(3)
	v_mfma_f32_32x32x16_bf16 v[66:81], v[162:165], v[114:117], v[66:81]
	ds_read_b64_tr_b16 v[166:167], v189 offset:32768
	ds_read_b64_tr_b16 v[168:169], v189 offset:33280
	v_add_f32_e32 v154, v158, v58
	v_exp_f32_e32 v61, v61
	v_cvt_pk_bf16_f32 v138, v58, v59
	v_add_f32_e32 v154, v59, v154
	s_waitcnt lgkmcnt(4)
	v_mfma_f32_32x32x16_bf16 v[82:97], v[198:201], v[114:117], v[82:97]
	ds_read_b64_tr_b16 v[162:163], v189 offset:33792
	ds_read_b64_tr_b16 v[164:165], v189 offset:34304
	v_exp_f32_e32 v62, v62
	v_exp_f32_e32 v63, v63
	v_add_f32_e32 v154, v154, v60
	v_cvt_pk_bf16_f32 v139, v60, v61
	s_waitcnt lgkmcnt(5)
	v_mfma_f32_32x32x16_bf16 v[66:81], v[202:205], v[118:121], v[66:81]
	ds_read_b64_tr_b16 v[158:159], v189 offset:34816
	ds_read_b64_tr_b16 v[160:161], v189 offset:35328
	v_add_f32_e32 v154, v154, v61
	v_exp_f32_e32 v64, v64
	v_exp_f32_e32 v65, v65
	v_add_f32_e32 v198, v62, v154
	s_waitcnt lgkmcnt(6)
	v_mfma_f32_32x32x16_bf16 v[82:97], v[194:197], v[118:121], v[82:97]
	ds_read_b64_tr_b16 v[154:155], v189 offset:35840
	ds_read_b64_tr_b16 v[156:157], v189 offset:36352
	v_add_f32_e32 v141, v198, v63
	v_add_f32_e32 v198, v64, v141
	v_cvt_pk_bf16_f32 v140, v62, v63
	v_cvt_pk_bf16_f32 v141, v64, v65
	v_add_f32_e32 v194, v65, v198
	s_waitcnt vmcnt(4) lgkmcnt(0)
	s_barrier
	v_mfma_f32_32x32x16_bf16 v[2:17], v[150:153], v[166:169], v[2:17]
	ds_read_b64_tr_b16 v[34:35], v189 offset:36864
	ds_read_b64_tr_b16 v[36:37], v189 offset:37376
	v_exp_f32_e32 v66, v66
	v_exp_f32_e32 v67, v67
	v_exp_f32_e32 v68, v68
	v_mfma_f32_32x32x16_bf16 v[2:17], v[146:149], v[162:165], v[2:17]
	ds_read_b64_tr_b16 v[38:39], v189 offset:37888
	ds_read_b64_tr_b16 v[40:41], v189 offset:38400
	v_add_f32_e32 v42, v194, v66
	v_exp_f32_e32 v69, v69
	v_cvt_pk_bf16_f32 v134, v66, v67
	v_add_f32_e32 v46, v67, v42
	v_mfma_f32_32x32x16_bf16 v[2:17], v[142:145], v[158:161], v[2:17]
	ds_read_b64_tr_b16 v[42:43], v189 offset:38912
	ds_read_b64_tr_b16 v[44:45], v189 offset:39424
	v_exp_f32_e32 v70, v70
	v_exp_f32_e32 v71, v71
	v_add_f32_e32 v50, v46, v68
	v_cvt_pk_bf16_f32 v135, v68, v69
	v_mfma_f32_32x32x16_bf16 v[2:17], v[138:141], v[154:157], v[2:17]
	ds_read_b64_tr_b16 v[46:47], v189 offset:39936
	ds_read_b64_tr_b16 v[48:49], v189 offset:40448
	v_add_f32_e32 v50, v50, v69
	v_exp_f32_e32 v72, v72
	v_exp_f32_e32 v73, v73
	v_add_f32_e32 v54, v70, v50
	s_waitcnt lgkmcnt(6)
	v_mfma_f32_32x32x16_bf16 v[18:33], v[150:153], v[34:37], v[18:33]
	ds_read_b128 v[50:53], v182 offset:24576
	v_cvt_pk_bf16_f32 v136, v70, v71
	v_add_f32_e32 v58, v54, v71
	v_exp_f32_e32 v74, v74
	v_exp_f32_e32 v75, v75
	s_waitcnt lgkmcnt(5)
	v_mfma_f32_32x32x16_bf16 v[18:33], v[146:149], v[38:41], v[18:33]
	ds_read_b128 v[54:57], v182 offset:28672
	v_add_f32_e32 v34, v58, v72
	v_exp_f32_e32 v76, v76
	v_cvt_pk_bf16_f32 v137, v72, v73
	v_add_f32_e32 v34, v73, v34
	s_waitcnt lgkmcnt(4)
	v_mfma_f32_32x32x16_bf16 v[18:33], v[142:145], v[42:45], v[18:33]
	ds_read_b128 v[154:157], v183 offset:24576
	v_add_f32_e32 v34, v34, v74
	v_exp_f32_e32 v77, v77
	v_cvt_pk_bf16_f32 v130, v74, v75
	v_add_f32_e32 v34, v75, v34
	s_waitcnt lgkmcnt(3)
	v_mfma_f32_32x32x16_bf16 v[18:33], v[138:141], v[46:49], v[18:33]
	ds_read_b128 v[162:165], v183 offset:28672
	v_exp_f32_e32 v78, v78
	v_exp_f32_e32 v79, v79
	v_add_f32_e32 v34, v34, v76
	v_cvt_pk_bf16_f32 v131, v76, v77
	s_nop 0
	v_add_f32_e32 v34, v34, v77
	v_add_f32_e32 v59, v78, v34
	s_waitcnt lgkmcnt(3)
	v_mfma_f32_32x32x16_bf16 v[34:49], v[50:53], v[98:101], 0
	ds_read_b128 v[166:169], v184 offset:24576
	v_exp_f32_e32 v80, v80
	v_exp_f32_e32 v81, v81
	ds_read_b128 v[158:161], v184 offset:28672
	v_add_f32_e32 v193, v59, v79
	s_waitcnt lgkmcnt(4)
	v_mfma_f32_32x32x16_bf16 v[50:65], v[54:57], v[98:101], 0
	v_exp_f32_e32 v82, v82
	v_exp_f32_e32 v83, v83
	v_cvt_pk_bf16_f32 v132, v78, v79
	s_add_i32 s26, 0x3000, s8
	s_add_i32 s28, 0x2000, s12
	s_mov_b32 m0, s26
	s_nop 0
	global_load_lds_dwordx4 v174, s[20:21]
	s_mov_b32 m0, s28
	s_nop 0
	global_load_lds_dwordx4 v191, s[20:21]
	s_mov_b32 m0, s24
	s_waitcnt lgkmcnt(3)
	v_mfma_f32_32x32x16_bf16 v[34:49], v[154:157], v[102:105], v[34:49]
	ds_read_b128 v[194:197], v185 offset:24576
	v_add_f32_e32 v154, v193, v80
	v_exp_f32_e32 v84, v84
	v_cvt_pk_bf16_f32 v133, v80, v81
	v_add_f32_e32 v193, v81, v154
	s_waitcnt lgkmcnt(3)
	v_mfma_f32_32x32x16_bf16 v[50:65], v[162:165], v[102:105], v[50:65]
	ds_read_b128 v[154:157], v185 offset:28672
	v_add_f32_e32 v193, v193, v82
	v_exp_f32_e32 v85, v85
	v_cvt_pk_bf16_f32 v126, v82, v83
	v_add_f32_e32 v193, v83, v193
	s_waitcnt lgkmcnt(3)
	v_mfma_f32_32x32x16_bf16 v[34:49], v[166:169], v[106:109], v[34:49]
	ds_read_b128 v[162:165], v187 offset:32768
	v_exp_f32_e32 v86, v86
	v_exp_f32_e32 v87, v87
	v_add_f32_e32 v193, v193, v84
	v_cvt_pk_bf16_f32 v127, v84, v85
	s_waitcnt lgkmcnt(3)
	v_mfma_f32_32x32x16_bf16 v[50:65], v[158:161], v[106:109], v[50:65]
	ds_read_b128 v[198:201], v187 offset:34816
	v_add_f32_e32 v166, v193, v85
	v_exp_f32_e32 v88, v88
	v_exp_f32_e32 v89, v89
	v_add_f32_e32 v166, v86, v166
	s_waitcnt lgkmcnt(3)
	v_mfma_f32_32x32x16_bf16 v[34:49], v[194:197], v[110:113], v[34:49]
	ds_read_b128 v[202:205], v188 offset:32768
	v_cvt_pk_bf16_f32 v128, v86, v87
	v_add_f32_e32 v159, v166, v87
	v_exp_f32_e32 v90, v90
	v_exp_f32_e32 v91, v91
	s_waitcnt lgkmcnt(3)
	v_mfma_f32_32x32x16_bf16 v[50:65], v[154:157], v[110:113], v[50:65]
	ds_read_b128 v[194:197], v188 offset:34816
	v_add_f32_e32 v158, v159, v88
	v_exp_f32_e32 v92, v92
	v_cvt_pk_bf16_f32 v129, v88, v89
	v_add_f32_e32 v158, v89, v158
	s_waitcnt lgkmcnt(3)
	v_mfma_f32_32x32x16_bf16 v[34:49], v[162:165], v[114:117], v[34:49]
	ds_read_b64_tr_b16 v[166:167], v189 offset:40960
	ds_read_b64_tr_b16 v[168:169], v189 offset:41472
	v_add_f32_e32 v154, v158, v90
	v_exp_f32_e32 v93, v93
	v_cvt_pk_bf16_f32 v122, v90, v91
	v_add_f32_e32 v154, v91, v154
	s_waitcnt lgkmcnt(4)
	v_mfma_f32_32x32x16_bf16 v[50:65], v[198:201], v[114:117], v[50:65]
	ds_read_b64_tr_b16 v[162:163], v189 offset:41984
	ds_read_b64_tr_b16 v[164:165], v189 offset:42496
	v_exp_f32_e32 v94, v94
	v_exp_f32_e32 v95, v95
	v_add_f32_e32 v154, v154, v92
	v_cvt_pk_bf16_f32 v123, v92, v93
	s_waitcnt lgkmcnt(5)
	v_mfma_f32_32x32x16_bf16 v[34:49], v[202:205], v[118:121], v[34:49]
	ds_read_b64_tr_b16 v[158:159], v189 offset:43008
	ds_read_b64_tr_b16 v[160:161], v189 offset:43520
	v_add_f32_e32 v154, v154, v93
	v_exp_f32_e32 v96, v96
	v_exp_f32_e32 v97, v97
	v_add_f32_e32 v193, v94, v154
	s_waitcnt lgkmcnt(6)
	v_mfma_f32_32x32x16_bf16 v[50:65], v[194:197], v[118:121], v[50:65]
	ds_read_b64_tr_b16 v[154:155], v189 offset:44032
	ds_read_b64_tr_b16 v[156:157], v189 offset:44544
	v_add_f32_e32 v125, v193, v95
	v_add_f32_e32 v193, v96, v125
	v_cvt_pk_bf16_f32 v124, v94, v95
	v_cvt_pk_bf16_f32 v125, v96, v97
	v_add_f32_e32 v193, v97, v193
	s_add_u32 s22, s22, 0x2000
	s_addc_u32 s23, s23, 0
	s_add_u32 s20, s20, 0x40000
	s_addc_u32 s21, s21, 0
	s_waitcnt vmcnt(4) lgkmcnt(0)
	s_barrier
	v_mfma_f32_32x32x16_bf16 v[2:17], v[134:137], v[166:169], v[2:17]
	ds_read_b64_tr_b16 v[66:67], v189 offset:45056
	ds_read_b64_tr_b16 v[68:69], v189 offset:45568
	v_exp_f32_e32 v34, v34
	v_exp_f32_e32 v35, v35
	v_exp_f32_e32 v36, v36
	v_mfma_f32_32x32x16_bf16 v[2:17], v[130:133], v[162:165], v[2:17]
	ds_read_b64_tr_b16 v[70:71], v189 offset:46080
	ds_read_b64_tr_b16 v[72:73], v189 offset:46592
	v_add_f32_e32 v74, v193, v34
	v_exp_f32_e32 v37, v37
	v_cvt_pk_bf16_f32 v150, v34, v35
	v_add_f32_e32 v78, v35, v74
	v_mfma_f32_32x32x16_bf16 v[2:17], v[126:129], v[158:161], v[2:17]
	ds_read_b64_tr_b16 v[74:75], v189 offset:47104
	ds_read_b64_tr_b16 v[76:77], v189 offset:47616
	v_exp_f32_e32 v38, v38
	v_exp_f32_e32 v39, v39
	v_add_f32_e32 v82, v78, v36
	v_cvt_pk_bf16_f32 v151, v36, v37
	v_mfma_f32_32x32x16_bf16 v[2:17], v[122:125], v[154:157], v[2:17]
	ds_read_b64_tr_b16 v[78:79], v189 offset:48128
	ds_read_b64_tr_b16 v[80:81], v189 offset:48640
	v_add_f32_e32 v82, v82, v37
	v_exp_f32_e32 v40, v40
	v_exp_f32_e32 v41, v41
	v_add_f32_e32 v86, v38, v82
	s_waitcnt lgkmcnt(6)
	v_mfma_f32_32x32x16_bf16 v[18:33], v[134:137], v[66:69], v[18:33]
	ds_read_b128 v[82:85], v182 offset:36864
	v_cvt_pk_bf16_f32 v152, v38, v39
	v_add_f32_e32 v90, v86, v39
	v_exp_f32_e32 v42, v42
	v_exp_f32_e32 v43, v43
	s_waitcnt lgkmcnt(5)
	v_mfma_f32_32x32x16_bf16 v[18:33], v[130:133], v[70:73], v[18:33]
	ds_read_b128 v[86:89], v182 offset:40960
	v_add_f32_e32 v66, v90, v40
	v_exp_f32_e32 v44, v44
	v_cvt_pk_bf16_f32 v153, v40, v41
	v_add_f32_e32 v66, v41, v66
	s_waitcnt lgkmcnt(4)
	v_mfma_f32_32x32x16_bf16 v[18:33], v[126:129], v[74:77], v[18:33]
	ds_read_b128 v[154:157], v183 offset:36864
	v_add_f32_e32 v66, v66, v42
	v_exp_f32_e32 v45, v45
	v_cvt_pk_bf16_f32 v146, v42, v43
	v_add_f32_e32 v66, v43, v66
	s_waitcnt lgkmcnt(3)
	v_mfma_f32_32x32x16_bf16 v[18:33], v[122:125], v[78:81], v[18:33]
	ds_read_b128 v[162:165], v183 offset:40960
	v_exp_f32_e32 v46, v46
	v_exp_f32_e32 v47, v47
	v_add_f32_e32 v66, v66, v44
	v_cvt_pk_bf16_f32 v147, v44, v45
	s_nop 0
	v_add_f32_e32 v66, v66, v45
	v_add_f32_e32 v91, v46, v66
	s_waitcnt lgkmcnt(3)
	v_mfma_f32_32x32x16_bf16 v[66:81], v[82:85], v[98:101], 0
	ds_read_b128 v[166:169], v184 offset:36864
	v_exp_f32_e32 v48, v48
	v_exp_f32_e32 v49, v49
	ds_read_b128 v[158:161], v184 offset:40960
	v_add_f32_e32 v193, v91, v47
	s_waitcnt lgkmcnt(4)
	v_mfma_f32_32x32x16_bf16 v[82:97], v[86:89], v[98:101], 0
	v_exp_f32_e32 v50, v50
	v_exp_f32_e32 v51, v51
	v_cvt_pk_bf16_f32 v148, v46, v47
	s_add_u32 s26, s20, 0xfffe0000
	s_addc_u32 s27, s21, -1
	s_add_i32 s31, 0x6000, s8
	s_add_i32 s33, 0x4000, s12
	s_mov_b32 m0, s31
	s_nop 0
	global_load_lds_dwordx4 v174, s[26:27]
	s_mov_b32 m0, s33
	s_nop 0
	global_load_lds_dwordx4 v191, s[26:27]
	s_mov_b32 m0, s28
	s_waitcnt lgkmcnt(3)
	v_mfma_f32_32x32x16_bf16 v[66:81], v[154:157], v[102:105], v[66:81]
	ds_read_b128 v[194:197], v185 offset:36864
	v_add_f32_e32 v193, v193, v48
	v_cvt_pk_bf16_f32 v149, v48, v49
	v_add_f32_e32 v193, v49, v193
	v_exp_f32_e32 v52, v52
	s_waitcnt lgkmcnt(3)
	v_mfma_f32_32x32x16_bf16 v[82:97], v[162:165], v[102:105], v[82:97]
	ds_read_b128 v[154:157], v185 offset:40960
	v_add_f32_e32 v193, v193, v50
	v_exp_f32_e32 v53, v53
	v_cvt_pk_bf16_f32 v142, v50, v51
	v_add_f32_e32 v193, v51, v193
	s_waitcnt lgkmcnt(3)
	v_mfma_f32_32x32x16_bf16 v[66:81], v[166:169], v[106:109], v[66:81]
	ds_read_b128 v[162:165], v187 offset:45056
	v_exp_f32_e32 v54, v54
	v_exp_f32_e32 v55, v55
	v_add_f32_e32 v193, v193, v52
	v_cvt_pk_bf16_f32 v143, v52, v53
	s_waitcnt lgkmcnt(3)
	v_mfma_f32_32x32x16_bf16 v[82:97], v[158:161], v[106:109], v[82:97]
	ds_read_b128 v[198:201], v187 offset:47104
	v_add_f32_e32 v166, v193, v53
	v_exp_f32_e32 v56, v56
	v_exp_f32_e32 v57, v57
	v_add_f32_e32 v166, v54, v166
	s_waitcnt lgkmcnt(3)
	v_mfma_f32_32x32x16_bf16 v[66:81], v[194:197], v[110:113], v[66:81]
	ds_read_b128 v[202:205], v188 offset:45056
	v_cvt_pk_bf16_f32 v144, v54, v55
	v_add_f32_e32 v159, v166, v55
	v_exp_f32_e32 v58, v58
	v_exp_f32_e32 v59, v59
	s_waitcnt lgkmcnt(3)
	v_mfma_f32_32x32x16_bf16 v[82:97], v[154:157], v[110:113], v[82:97]
	ds_read_b128 v[194:197], v188 offset:47104
	v_add_f32_e32 v158, v159, v56
	v_exp_f32_e32 v60, v60
	v_cvt_pk_bf16_f32 v145, v56, v57
	v_add_f32_e32 v158, v57, v158
	s_waitcnt lgkmcnt(3)
	v_mfma_f32_32x32x16_bf16 v[66:81], v[162:165], v[114:117], v[66:81]
	ds_read_b64_tr_b16 v[166:167], v189 offset:49152
	ds_read_b64_tr_b16 v[168:169], v189 offset:49664
	v_add_f32_e32 v154, v158, v58
	v_exp_f32_e32 v61, v61
	v_cvt_pk_bf16_f32 v138, v58, v59
	v_add_f32_e32 v154, v59, v154
	s_waitcnt lgkmcnt(4)
	v_mfma_f32_32x32x16_bf16 v[82:97], v[198:201], v[114:117], v[82:97]
	ds_read_b64_tr_b16 v[162:163], v189 offset:50176
	ds_read_b64_tr_b16 v[164:165], v189 offset:50688
	v_exp_f32_e32 v62, v62
	v_exp_f32_e32 v63, v63
	v_add_f32_e32 v154, v154, v60
	v_cvt_pk_bf16_f32 v139, v60, v61
	s_waitcnt lgkmcnt(5)
	v_mfma_f32_32x32x16_bf16 v[66:81], v[202:205], v[118:121], v[66:81]
	ds_read_b64_tr_b16 v[158:159], v189 offset:51200
	ds_read_b64_tr_b16 v[160:161], v189 offset:51712
	v_add_f32_e32 v154, v154, v61
	v_exp_f32_e32 v64, v64
	v_exp_f32_e32 v65, v65
	v_add_f32_e32 v198, v62, v154
	s_waitcnt lgkmcnt(6)
	v_mfma_f32_32x32x16_bf16 v[82:97], v[194:197], v[118:121], v[82:97]
	ds_read_b64_tr_b16 v[154:155], v189 offset:52224
	ds_read_b64_tr_b16 v[156:157], v189 offset:52736
	v_add_f32_e32 v141, v198, v63
	v_add_f32_e32 v198, v64, v141
	v_cvt_pk_bf16_f32 v140, v62, v63
	v_cvt_pk_bf16_f32 v141, v64, v65
	v_add_f32_e32 v194, v65, v198
	s_waitcnt vmcnt(4) lgkmcnt(0)
	s_barrier
	v_mfma_f32_32x32x16_bf16 v[2:17], v[150:153], v[166:169], v[2:17]
	ds_read_b64_tr_b16 v[34:35], v189 offset:53248
	ds_read_b64_tr_b16 v[36:37], v189 offset:53760
	v_exp_f32_e32 v66, v66
	v_exp_f32_e32 v67, v67
	v_exp_f32_e32 v68, v68
	v_mfma_f32_32x32x16_bf16 v[2:17], v[146:149], v[162:165], v[2:17]
	ds_read_b64_tr_b16 v[38:39], v189 offset:54272
	ds_read_b64_tr_b16 v[40:41], v189 offset:54784
	v_add_f32_e32 v42, v194, v66
	v_exp_f32_e32 v69, v69
	v_cvt_pk_bf16_f32 v134, v66, v67
	v_add_f32_e32 v46, v67, v42
	v_mfma_f32_32x32x16_bf16 v[2:17], v[142:145], v[158:161], v[2:17]
	ds_read_b64_tr_b16 v[42:43], v189 offset:55296
	ds_read_b64_tr_b16 v[44:45], v189 offset:55808
	v_exp_f32_e32 v70, v70
	v_exp_f32_e32 v71, v71
	v_add_f32_e32 v50, v46, v68
	v_cvt_pk_bf16_f32 v135, v68, v69
	v_mfma_f32_32x32x16_bf16 v[2:17], v[138:141], v[154:157], v[2:17]
	ds_read_b64_tr_b16 v[46:47], v189 offset:56320
	ds_read_b64_tr_b16 v[48:49], v189 offset:56832
	v_add_f32_e32 v50, v50, v69
	v_exp_f32_e32 v72, v72
	v_exp_f32_e32 v73, v73
	v_add_f32_e32 v54, v70, v50
	s_waitcnt lgkmcnt(6)
	v_mfma_f32_32x32x16_bf16 v[18:33], v[150:153], v[34:37], v[18:33]
	ds_read_b128 v[50:53], v182
	v_cvt_pk_bf16_f32 v136, v70, v71
	v_add_f32_e32 v58, v54, v71
	v_exp_f32_e32 v74, v74
	v_exp_f32_e32 v75, v75
	s_waitcnt lgkmcnt(5)
	v_mfma_f32_32x32x16_bf16 v[18:33], v[146:149], v[38:41], v[18:33]
	ds_read_b128 v[54:57], v182 offset:4096
	v_add_f32_e32 v34, v58, v72
	v_exp_f32_e32 v76, v76
	v_cvt_pk_bf16_f32 v137, v72, v73
	v_add_f32_e32 v34, v73, v34
	s_waitcnt lgkmcnt(4)
	v_mfma_f32_32x32x16_bf16 v[18:33], v[142:145], v[42:45], v[18:33]
	ds_read_b128 v[154:157], v183
	v_add_f32_e32 v34, v34, v74
	v_exp_f32_e32 v77, v77
	v_cvt_pk_bf16_f32 v130, v74, v75
	v_add_f32_e32 v34, v75, v34
	s_waitcnt lgkmcnt(3)
	v_mfma_f32_32x32x16_bf16 v[18:33], v[138:141], v[46:49], v[18:33]
	ds_read_b128 v[162:165], v183 offset:4096
	v_exp_f32_e32 v78, v78
	v_exp_f32_e32 v79, v79
	v_add_f32_e32 v34, v34, v76
	v_cvt_pk_bf16_f32 v131, v76, v77
	s_nop 0
	v_add_f32_e32 v34, v34, v77
	v_add_f32_e32 v59, v78, v34
	s_waitcnt lgkmcnt(3)
	v_mfma_f32_32x32x16_bf16 v[34:49], v[50:53], v[98:101], 0
	ds_read_b128 v[166:169], v184
	v_exp_f32_e32 v80, v80
	v_exp_f32_e32 v81, v81
	ds_read_b128 v[158:161], v184 offset:4096
	v_add_f32_e32 v193, v59, v79
	s_waitcnt lgkmcnt(4)
	v_mfma_f32_32x32x16_bf16 v[50:65], v[54:57], v[98:101], 0
	v_exp_f32_e32 v82, v82
	v_exp_f32_e32 v83, v83
	v_cvt_pk_bf16_f32 v132, v78, v79
	s_add_i32 s26, 0x9000, s8
	s_add_i32 s28, 0x6000, s12
	s_mov_b32 m0, s26
	s_nop 0
	global_load_lds_dwordx4 v174, s[20:21]
	s_mov_b32 m0, s28
	s_nop 0
	global_load_lds_dwordx4 v191, s[20:21]
	s_mov_b32 m0, s24
	s_waitcnt lgkmcnt(3)
	v_mfma_f32_32x32x16_bf16 v[34:49], v[154:157], v[102:105], v[34:49]
	ds_read_b128 v[194:197], v185
	v_add_f32_e32 v154, v193, v80
	v_exp_f32_e32 v84, v84
	v_cvt_pk_bf16_f32 v133, v80, v81
	v_add_f32_e32 v193, v81, v154
	s_waitcnt lgkmcnt(3)
	v_mfma_f32_32x32x16_bf16 v[50:65], v[162:165], v[102:105], v[50:65]
	ds_read_b128 v[154:157], v185 offset:4096
	v_add_f32_e32 v193, v193, v82
	v_exp_f32_e32 v85, v85
	v_cvt_pk_bf16_f32 v126, v82, v83
	v_add_f32_e32 v193, v83, v193
	s_waitcnt lgkmcnt(3)
	v_mfma_f32_32x32x16_bf16 v[34:49], v[166:169], v[106:109], v[34:49]
	ds_read_b128 v[162:165], v187 offset:8192
	v_exp_f32_e32 v86, v86
	v_exp_f32_e32 v87, v87
	v_add_f32_e32 v193, v193, v84
	v_cvt_pk_bf16_f32 v127, v84, v85
	s_waitcnt lgkmcnt(3)
	v_mfma_f32_32x32x16_bf16 v[50:65], v[158:161], v[106:109], v[50:65]
	ds_read_b128 v[198:201], v187 offset:10240
	v_add_f32_e32 v166, v193, v85
	v_exp_f32_e32 v88, v88
	v_exp_f32_e32 v89, v89
	v_add_f32_e32 v166, v86, v166
	s_waitcnt lgkmcnt(3)
	v_mfma_f32_32x32x16_bf16 v[34:49], v[194:197], v[110:113], v[34:49]
	ds_read_b128 v[202:205], v188 offset:8192
	v_cvt_pk_bf16_f32 v128, v86, v87
	v_add_f32_e32 v159, v166, v87
	v_exp_f32_e32 v90, v90
	v_exp_f32_e32 v91, v91
	s_waitcnt lgkmcnt(3)
	v_mfma_f32_32x32x16_bf16 v[50:65], v[154:157], v[110:113], v[50:65]
	ds_read_b128 v[194:197], v188 offset:10240
	v_add_f32_e32 v158, v159, v88
	v_exp_f32_e32 v92, v92
	v_cvt_pk_bf16_f32 v129, v88, v89
	v_add_f32_e32 v158, v89, v158
	s_waitcnt lgkmcnt(3)
	v_mfma_f32_32x32x16_bf16 v[34:49], v[162:165], v[114:117], v[34:49]
	ds_read_b64_tr_b16 v[166:167], v189 offset:57344
	ds_read_b64_tr_b16 v[168:169], v189 offset:57856
	v_add_f32_e32 v154, v158, v90
	v_exp_f32_e32 v93, v93
	v_cvt_pk_bf16_f32 v122, v90, v91
	v_add_f32_e32 v154, v91, v154
	s_waitcnt lgkmcnt(4)
	v_mfma_f32_32x32x16_bf16 v[50:65], v[198:201], v[114:117], v[50:65]
	ds_read_b64_tr_b16 v[162:163], v189 offset:58368
	ds_read_b64_tr_b16 v[164:165], v189 offset:58880
	v_exp_f32_e32 v94, v94
	v_exp_f32_e32 v95, v95
	v_add_f32_e32 v154, v154, v92
	v_cvt_pk_bf16_f32 v123, v92, v93
	s_waitcnt lgkmcnt(5)
	v_mfma_f32_32x32x16_bf16 v[34:49], v[202:205], v[118:121], v[34:49]
	ds_read_b64_tr_b16 v[158:159], v189 offset:59392
	ds_read_b64_tr_b16 v[160:161], v189 offset:59904
	v_add_f32_e32 v154, v154, v93
	v_exp_f32_e32 v96, v96
	v_exp_f32_e32 v97, v97
	v_add_f32_e32 v193, v94, v154
	s_waitcnt lgkmcnt(6)
	v_mfma_f32_32x32x16_bf16 v[50:65], v[194:197], v[118:121], v[50:65]
	ds_read_b64_tr_b16 v[154:155], v189 offset:60416
	ds_read_b64_tr_b16 v[156:157], v189 offset:60928
	v_add_f32_e32 v125, v193, v95
	v_add_f32_e32 v193, v96, v125
	v_cvt_pk_bf16_f32 v124, v94, v95
	v_cvt_pk_bf16_f32 v125, v96, v97
	v_add_f32_e32 v193, v97, v193
	s_add_u32 s22, s22, 0x2000
	s_addc_u32 s23, s23, 0
	s_add_u32 s20, s20, 0x40000
	s_addc_u32 s21, s21, 0
	s_waitcnt vmcnt(4) lgkmcnt(0)
	s_barrier
	v_mfma_f32_32x32x16_bf16 v[2:17], v[134:137], v[166:169], v[2:17]
	ds_read_b64_tr_b16 v[66:67], v189 offset:61440
	ds_read_b64_tr_b16 v[68:69], v189 offset:61952
	v_exp_f32_e32 v34, v34
	v_exp_f32_e32 v35, v35
	v_exp_f32_e32 v36, v36
	v_mfma_f32_32x32x16_bf16 v[2:17], v[130:133], v[162:165], v[2:17]
	ds_read_b64_tr_b16 v[70:71], v189 offset:62464
	ds_read_b64_tr_b16 v[72:73], v189 offset:62976
	v_add_f32_e32 v74, v193, v34
	v_exp_f32_e32 v37, v37
	v_cvt_pk_bf16_f32 v150, v34, v35
	v_add_f32_e32 v78, v35, v74
	v_mfma_f32_32x32x16_bf16 v[2:17], v[126:129], v[158:161], v[2:17]
	ds_read_b64_tr_b16 v[74:75], v189 offset:63488
	ds_read_b64_tr_b16 v[76:77], v189 offset:64000
	v_exp_f32_e32 v38, v38
	v_exp_f32_e32 v39, v39
	v_add_f32_e32 v82, v78, v36
	v_cvt_pk_bf16_f32 v151, v36, v37
	v_mfma_f32_32x32x16_bf16 v[2:17], v[122:125], v[154:157], v[2:17]
	ds_read_b64_tr_b16 v[78:79], v189 offset:64512
	ds_read_b64_tr_b16 v[80:81], v189 offset:65024
	v_add_f32_e32 v82, v82, v37
	v_exp_f32_e32 v40, v40
	v_exp_f32_e32 v41, v41
	v_add_f32_e32 v86, v38, v82
	s_waitcnt lgkmcnt(6)
	v_mfma_f32_32x32x16_bf16 v[18:33], v[134:137], v[66:69], v[18:33]
	ds_read_b128 v[82:85], v182 offset:12288
	v_cvt_pk_bf16_f32 v152, v38, v39
	v_add_f32_e32 v90, v86, v39
	v_exp_f32_e32 v42, v42
	v_exp_f32_e32 v43, v43
	s_waitcnt lgkmcnt(5)
	v_mfma_f32_32x32x16_bf16 v[18:33], v[130:133], v[70:73], v[18:33]
	ds_read_b128 v[86:89], v182 offset:16384
	v_add_f32_e32 v66, v90, v40
	v_exp_f32_e32 v44, v44
	v_cvt_pk_bf16_f32 v153, v40, v41
	v_add_f32_e32 v66, v41, v66
	s_waitcnt lgkmcnt(4)
	v_mfma_f32_32x32x16_bf16 v[18:33], v[126:129], v[74:77], v[18:33]
	ds_read_b128 v[154:157], v183 offset:12288
	v_add_f32_e32 v66, v66, v42
	v_exp_f32_e32 v45, v45
	v_cvt_pk_bf16_f32 v146, v42, v43
	v_add_f32_e32 v66, v43, v66
	s_waitcnt lgkmcnt(3)
	v_mfma_f32_32x32x16_bf16 v[18:33], v[122:125], v[78:81], v[18:33]
	ds_read_b128 v[162:165], v183 offset:16384
	v_exp_f32_e32 v46, v46
	v_exp_f32_e32 v47, v47
	v_add_f32_e32 v66, v66, v44
	v_cvt_pk_bf16_f32 v147, v44, v45
	s_nop 0
	v_add_f32_e32 v66, v66, v45
	v_add_f32_e32 v91, v46, v66
	s_waitcnt lgkmcnt(3)
	v_mfma_f32_32x32x16_bf16 v[66:81], v[82:85], v[98:101], 0
	ds_read_b128 v[166:169], v184 offset:12288
	v_exp_f32_e32 v48, v48
	v_exp_f32_e32 v49, v49
	ds_read_b128 v[158:161], v184 offset:16384
	v_add_f32_e32 v193, v91, v47
	s_waitcnt lgkmcnt(4)
	v_mfma_f32_32x32x16_bf16 v[82:97], v[86:89], v[98:101], 0
	v_exp_f32_e32 v50, v50
	v_exp_f32_e32 v51, v51
	v_cvt_pk_bf16_f32 v148, v46, v47
	s_add_u32 s26, s20, 0xfffe0000
	s_addc_u32 s27, s21, -1
	s_add_i32 s31, 0, s8
	s_add_i32 s33, 0x8000, s12
	s_mov_b32 m0, s31
	s_nop 0
	global_load_lds_dwordx4 v174, s[26:27]
	s_mov_b32 m0, s33
	s_nop 0
	global_load_lds_dwordx4 v191, s[26:27]
	s_mov_b32 m0, s28
	s_waitcnt lgkmcnt(3)
	v_mfma_f32_32x32x16_bf16 v[66:81], v[154:157], v[102:105], v[66:81]
	ds_read_b128 v[194:197], v185 offset:12288
	v_add_f32_e32 v193, v193, v48
	v_cvt_pk_bf16_f32 v149, v48, v49
	v_add_f32_e32 v193, v49, v193
	v_exp_f32_e32 v52, v52
	s_waitcnt lgkmcnt(3)
	v_mfma_f32_32x32x16_bf16 v[82:97], v[162:165], v[102:105], v[82:97]
	ds_read_b128 v[154:157], v185 offset:16384
	v_add_f32_e32 v193, v193, v50
	v_exp_f32_e32 v53, v53
	v_cvt_pk_bf16_f32 v142, v50, v51
	v_add_f32_e32 v193, v51, v193
	s_waitcnt lgkmcnt(3)
	v_mfma_f32_32x32x16_bf16 v[66:81], v[166:169], v[106:109], v[66:81]
	ds_read_b128 v[162:165], v187 offset:20480
	v_exp_f32_e32 v54, v54
	v_exp_f32_e32 v55, v55
	v_add_f32_e32 v193, v193, v52
	v_cvt_pk_bf16_f32 v143, v52, v53
	s_waitcnt lgkmcnt(3)
	v_mfma_f32_32x32x16_bf16 v[82:97], v[158:161], v[106:109], v[82:97]
	ds_read_b128 v[198:201], v187 offset:22528
	v_add_f32_e32 v166, v193, v53
	v_exp_f32_e32 v56, v56
	v_exp_f32_e32 v57, v57
	v_add_f32_e32 v166, v54, v166
	s_waitcnt lgkmcnt(3)
	v_mfma_f32_32x32x16_bf16 v[66:81], v[194:197], v[110:113], v[66:81]
	ds_read_b128 v[202:205], v188 offset:20480
	v_cvt_pk_bf16_f32 v144, v54, v55
	v_add_f32_e32 v159, v166, v55
	v_exp_f32_e32 v58, v58
	v_exp_f32_e32 v59, v59
	s_waitcnt lgkmcnt(3)
	v_mfma_f32_32x32x16_bf16 v[82:97], v[154:157], v[110:113], v[82:97]
	ds_read_b128 v[194:197], v188 offset:22528
	v_add_f32_e32 v158, v159, v56
	v_exp_f32_e32 v60, v60
	v_cvt_pk_bf16_f32 v145, v56, v57
	v_add_f32_e32 v158, v57, v158
	s_waitcnt lgkmcnt(3)
	v_mfma_f32_32x32x16_bf16 v[66:81], v[162:165], v[114:117], v[66:81]
	ds_read_b64_tr_b16 v[166:167], v189 offset:16384
	ds_read_b64_tr_b16 v[168:169], v189 offset:16896
	v_add_f32_e32 v154, v158, v58
	v_exp_f32_e32 v61, v61
	v_cvt_pk_bf16_f32 v138, v58, v59
	v_add_f32_e32 v154, v59, v154
	s_waitcnt lgkmcnt(4)
	v_mfma_f32_32x32x16_bf16 v[82:97], v[198:201], v[114:117], v[82:97]
	ds_read_b64_tr_b16 v[162:163], v189 offset:17408
	ds_read_b64_tr_b16 v[164:165], v189 offset:17920
	v_exp_f32_e32 v62, v62
	v_exp_f32_e32 v63, v63
	v_add_f32_e32 v154, v154, v60
	v_cvt_pk_bf16_f32 v139, v60, v61
	s_waitcnt lgkmcnt(5)
	v_mfma_f32_32x32x16_bf16 v[66:81], v[202:205], v[118:121], v[66:81]
	ds_read_b64_tr_b16 v[158:159], v189 offset:18432
	ds_read_b64_tr_b16 v[160:161], v189 offset:18944
	v_add_f32_e32 v154, v154, v61
	v_exp_f32_e32 v64, v64
	v_exp_f32_e32 v65, v65
	v_add_f32_e32 v198, v62, v154
	s_waitcnt lgkmcnt(6)
	v_mfma_f32_32x32x16_bf16 v[82:97], v[194:197], v[118:121], v[82:97]
	ds_read_b64_tr_b16 v[154:155], v189 offset:19456
	ds_read_b64_tr_b16 v[156:157], v189 offset:19968
	v_add_f32_e32 v141, v198, v63
	v_add_f32_e32 v198, v64, v141
	v_cvt_pk_bf16_f32 v140, v62, v63
	v_cvt_pk_bf16_f32 v141, v64, v65
	v_add_f32_e32 v194, v65, v198
	s_waitcnt vmcnt(4) lgkmcnt(0)
	s_barrier
	v_mfma_f32_32x32x16_bf16 v[2:17], v[150:153], v[166:169], v[2:17]
	ds_read_b64_tr_b16 v[34:35], v189 offset:20480
	ds_read_b64_tr_b16 v[36:37], v189 offset:20992
	v_exp_f32_e32 v66, v66
	v_exp_f32_e32 v67, v67
	v_exp_f32_e32 v68, v68
	v_mfma_f32_32x32x16_bf16 v[2:17], v[146:149], v[162:165], v[2:17]
	ds_read_b64_tr_b16 v[38:39], v189 offset:21504
	ds_read_b64_tr_b16 v[40:41], v189 offset:22016
	v_add_f32_e32 v42, v194, v66
	v_exp_f32_e32 v69, v69
	v_cvt_pk_bf16_f32 v134, v66, v67
	v_add_f32_e32 v46, v67, v42
	v_mfma_f32_32x32x16_bf16 v[2:17], v[142:145], v[158:161], v[2:17]
	ds_read_b64_tr_b16 v[42:43], v189 offset:22528
	ds_read_b64_tr_b16 v[44:45], v189 offset:23040
	v_exp_f32_e32 v70, v70
	v_exp_f32_e32 v71, v71
	v_add_f32_e32 v50, v46, v68
	v_cvt_pk_bf16_f32 v135, v68, v69
	v_mfma_f32_32x32x16_bf16 v[2:17], v[138:141], v[154:157], v[2:17]
	ds_read_b64_tr_b16 v[46:47], v189 offset:23552
	ds_read_b64_tr_b16 v[48:49], v189 offset:24064
	v_add_f32_e32 v50, v50, v69
	v_exp_f32_e32 v72, v72
	v_exp_f32_e32 v73, v73
	v_add_f32_e32 v54, v70, v50
	s_waitcnt lgkmcnt(6)
	v_mfma_f32_32x32x16_bf16 v[18:33], v[150:153], v[34:37], v[18:33]
	ds_read_b128 v[50:53], v182 offset:24576
	v_cvt_pk_bf16_f32 v136, v70, v71
	v_add_f32_e32 v58, v54, v71
	v_exp_f32_e32 v74, v74
	v_exp_f32_e32 v75, v75
	s_waitcnt lgkmcnt(5)
	v_mfma_f32_32x32x16_bf16 v[18:33], v[146:149], v[38:41], v[18:33]
	ds_read_b128 v[54:57], v182 offset:28672
	v_add_f32_e32 v34, v58, v72
	v_exp_f32_e32 v76, v76
	v_cvt_pk_bf16_f32 v137, v72, v73
	v_add_f32_e32 v34, v73, v34
	s_waitcnt lgkmcnt(4)
	v_mfma_f32_32x32x16_bf16 v[18:33], v[142:145], v[42:45], v[18:33]
	ds_read_b128 v[154:157], v183 offset:24576
	v_add_f32_e32 v34, v34, v74
	v_exp_f32_e32 v77, v77
	v_cvt_pk_bf16_f32 v130, v74, v75
	v_add_f32_e32 v34, v75, v34
	s_waitcnt lgkmcnt(3)
	v_mfma_f32_32x32x16_bf16 v[18:33], v[138:141], v[46:49], v[18:33]
	ds_read_b128 v[162:165], v183 offset:28672
	v_exp_f32_e32 v78, v78
	v_exp_f32_e32 v79, v79
	v_add_f32_e32 v34, v34, v76
	v_cvt_pk_bf16_f32 v131, v76, v77
	s_nop 0
	v_add_f32_e32 v34, v34, v77
	v_add_f32_e32 v59, v78, v34
	s_waitcnt lgkmcnt(3)
	v_mfma_f32_32x32x16_bf16 v[34:49], v[50:53], v[98:101], 0
	ds_read_b128 v[166:169], v184 offset:24576
	v_exp_f32_e32 v80, v80
	v_exp_f32_e32 v81, v81
	ds_read_b128 v[158:161], v184 offset:28672
	v_add_f32_e32 v193, v59, v79
	s_waitcnt lgkmcnt(4)
	v_mfma_f32_32x32x16_bf16 v[50:65], v[54:57], v[98:101], 0
	v_exp_f32_e32 v82, v82
	v_exp_f32_e32 v83, v83
	v_cvt_pk_bf16_f32 v132, v78, v79
	s_add_i32 s26, 0x3000, s8
	s_add_i32 s28, 0xa000, s12
	s_mov_b32 m0, s26
	s_nop 0
	global_load_lds_dwordx4 v174, s[20:21]
	s_mov_b32 m0, s28
	s_nop 0
	global_load_lds_dwordx4 v191, s[20:21]
	s_mov_b32 m0, s24
	s_waitcnt lgkmcnt(3)
	v_mfma_f32_32x32x16_bf16 v[34:49], v[154:157], v[102:105], v[34:49]
	ds_read_b128 v[194:197], v185 offset:24576
	v_add_f32_e32 v154, v193, v80
	v_exp_f32_e32 v84, v84
	v_cvt_pk_bf16_f32 v133, v80, v81
	v_add_f32_e32 v193, v81, v154
	s_waitcnt lgkmcnt(3)
	v_mfma_f32_32x32x16_bf16 v[50:65], v[162:165], v[102:105], v[50:65]
	ds_read_b128 v[154:157], v185 offset:28672
	v_add_f32_e32 v193, v193, v82
	v_exp_f32_e32 v85, v85
	v_cvt_pk_bf16_f32 v126, v82, v83
	v_add_f32_e32 v193, v83, v193
	s_waitcnt lgkmcnt(3)
	v_mfma_f32_32x32x16_bf16 v[34:49], v[166:169], v[106:109], v[34:49]
	ds_read_b128 v[162:165], v187 offset:32768
	v_exp_f32_e32 v86, v86
	v_exp_f32_e32 v87, v87
	v_add_f32_e32 v193, v193, v84
	v_cvt_pk_bf16_f32 v127, v84, v85
	s_waitcnt lgkmcnt(3)
	v_mfma_f32_32x32x16_bf16 v[50:65], v[158:161], v[106:109], v[50:65]
	ds_read_b128 v[198:201], v187 offset:34816
	v_add_f32_e32 v166, v193, v85
	v_exp_f32_e32 v88, v88
	v_exp_f32_e32 v89, v89
	v_add_f32_e32 v166, v86, v166
	s_waitcnt lgkmcnt(3)
	v_mfma_f32_32x32x16_bf16 v[34:49], v[194:197], v[110:113], v[34:49]
	ds_read_b128 v[202:205], v188 offset:32768
	v_cvt_pk_bf16_f32 v128, v86, v87
	v_add_f32_e32 v159, v166, v87
	v_exp_f32_e32 v90, v90
	v_exp_f32_e32 v91, v91
	s_waitcnt lgkmcnt(3)
	v_mfma_f32_32x32x16_bf16 v[50:65], v[154:157], v[110:113], v[50:65]
	ds_read_b128 v[194:197], v188 offset:34816
	v_add_f32_e32 v158, v159, v88
	v_exp_f32_e32 v92, v92
	v_cvt_pk_bf16_f32 v129, v88, v89
	v_add_f32_e32 v158, v89, v158
	s_waitcnt lgkmcnt(3)
	v_mfma_f32_32x32x16_bf16 v[34:49], v[162:165], v[114:117], v[34:49]
	ds_read_b64_tr_b16 v[166:167], v189 offset:24576
	ds_read_b64_tr_b16 v[168:169], v189 offset:25088
	v_add_f32_e32 v154, v158, v90
	v_exp_f32_e32 v93, v93
	v_cvt_pk_bf16_f32 v122, v90, v91
	v_add_f32_e32 v154, v91, v154
	s_waitcnt lgkmcnt(4)
	v_mfma_f32_32x32x16_bf16 v[50:65], v[198:201], v[114:117], v[50:65]
	ds_read_b64_tr_b16 v[162:163], v189 offset:25600
	ds_read_b64_tr_b16 v[164:165], v189 offset:26112
	v_exp_f32_e32 v94, v94
	v_exp_f32_e32 v95, v95
	v_add_f32_e32 v154, v154, v92
	v_cvt_pk_bf16_f32 v123, v92, v93
	s_waitcnt lgkmcnt(5)
	v_mfma_f32_32x32x16_bf16 v[34:49], v[202:205], v[118:121], v[34:49]
	ds_read_b64_tr_b16 v[158:159], v189 offset:26624
	ds_read_b64_tr_b16 v[160:161], v189 offset:27136
	v_add_f32_e32 v154, v154, v93
	v_exp_f32_e32 v96, v96
	v_exp_f32_e32 v97, v97
	v_add_f32_e32 v193, v94, v154
	s_waitcnt lgkmcnt(6)
	v_mfma_f32_32x32x16_bf16 v[50:65], v[194:197], v[118:121], v[50:65]
	ds_read_b64_tr_b16 v[154:155], v189 offset:27648
	ds_read_b64_tr_b16 v[156:157], v189 offset:28160
	v_add_f32_e32 v125, v193, v95
	v_add_f32_e32 v193, v96, v125
	v_cvt_pk_bf16_f32 v124, v94, v95
	v_cvt_pk_bf16_f32 v125, v96, v97
	v_add_f32_e32 v193, v97, v193
	s_add_u32 s22, s22, 0x2000
	s_addc_u32 s23, s23, 0
	s_add_u32 s20, s20, 0x40000
	s_addc_u32 s21, s21, 0
	s_add_i32 s13, s13, 12
	s_cmp_le_i32 s13, 108
	s_cbranch_scc1 .Lmla_fast_w47
	v_subrev_u32_e32 v189, 0x8000, v189
	s_mov_b32 s2, 0x4000
	s_mov_b32 s17, 0x6000
	s_mov_b32 s26, 0x2000
	s_mov_b32 s14, 0x0
	s_mov_b32 s15, 0x9000
	s_branch .LBB0_1278
